# PLE prompt tiles on the merged-phase 256x256 core: gate GEMM -> sigmoid -> bf16 parked in the idle ACT buffer -> proj GEMM -> acc*gate -> 16-byte bf16 stores; sample rows as split-K units combined in
# baseline (speedup 1.0000x reference)
; DI unsigned pk2(float lo, float hi) { const f32x2 v = {lo, hi}; return __builtin_bit_cast(unsigned, __builtin_convertvector(v, bf2_t)); }
; DI void rowpass(const Params& p, bool init, float scale, const float* __restrict__ gpost, const float* __restrict__ gnext, int nparts, int bid, int nb, const int tid) {
;     ...
;             } else {
; #pragma unroll
;                 for (int i = 0; i < 4; ++i) y[i] = make_float4(0.f, 0.f, 0.f, 0.f);
;                 for (int pt = 0; pt < nparts; ++pt) {
; #pragma unroll
;                     for (int i = 0; i < 4; ++i) { const float4 u = *(const float4*)(YS + (size_t)pt * NS * DM + (size_t)(row - NP) * DM + i * 256 + lane * 4); y[i].x += u.x; y[i].y += u.y; y[i].z += u.z; y[i].w += u.w; }
;                 }
;             }
; DI void gemm_ple(const Params& p, int bid, int nb, char* smem, const int tid) {
;     ...
;                     float g[4];
; #pragma unroll
;                     for (int e = 0; e < 4; ++e) g[e] = __builtin_amdgcn_rcpf(1.0f + __builtin_amdgcn_exp2f(-LOG2E * gate[i][j][e]));
;                     gpk[i][j].x = pk2(g[0], g[1]); gpk[i][j].y = pk2(g[2], g[3]);
;                 }
;         }
;         f32x4 acc[4][4]; zero_acc(acc);
;         gemm_stream2(PB, 256, WP, 256, 256, m0, n0, have, XN, 1024, WG, 1024, tm2 * 256, tn2 * 128, smem, acc, tid, rg);
; #pragma unroll
;         for (int i = 0; i < 4; ++i)
; #pragma unroll
;             for (int j = 0; j < 4; ++j) {
;                 acc[i][j][0] *= __uint_as_float(gpk[i][j].x << 16); acc[i][j][1] *= __uint_as_float(gpk[i][j].x & 0xffff0000u);
;                 acc[i][j][2] *= __uint_as_float(gpk[i][j].y << 16); acc[i][j][3] *= __uint_as_float(gpk[i][j].y & 0xffff0000u);
.LBB0_31:
	flat_load_dwordx4 v[36:39], v[44:45]
	flat_load_dwordx4 v[32:35], v[44:45] offset:1024
	flat_load_dwordx4 v[28:31], v[44:45] offset:2048
	flat_load_dwordx4 v[24:27], v[44:45] offset:3072
	s_cmpk_lt_i32 s2, 0x4000
	s_mov_b64 s[36:37], -1
	s_cbranch_scc1 .LBB0_33
	s_add_i32 s86, s2, 0xffffc000
	s_lshl_b64 s[10:11], s[86:87], 12
	v_lshl_add_u64 v[58:59], v[18:19], 0, s[10:11]
	v_add_co_u32_e32 v200, vcc, 0x100000, v58
	s_nop 1
	v_addc_co_u32_e32 v201, vcc, 0, v59, vcc
	global_load_dwordx4 v[84:87], v[200:201], off
	global_load_dwordx4 v[88:91], v[200:201], off offset:1024
	global_load_dwordx4 v[92:95], v[200:201], off offset:2048
	global_load_dwordx4 v[96:99], v[200:201], off offset:3072
	v_add_co_u32_e32 v200, vcc, 0x200000, v58
	s_nop 1
	v_addc_co_u32_e32 v201, vcc, 0, v59, vcc
	global_load_dwordx4 v[100:103], v[200:201], off
	global_load_dwordx4 v[104:107], v[200:201], off offset:1024
	global_load_dwordx4 v[108:111], v[200:201], off offset:2048
	global_load_dwordx4 v[112:115], v[200:201], off offset:3072
	v_add_co_u32_e32 v200, vcc, 0x300000, v58
	s_nop 1
	v_addc_co_u32_e32 v201, vcc, 0, v59, vcc
	global_load_dwordx4 v[116:119], v[200:201], off
	global_load_dwordx4 v[120:123], v[200:201], off offset:1024
	global_load_dwordx4 v[124:127], v[200:201], off offset:2048
	global_load_dwordx4 v[128:131], v[200:201], off offset:3072
	v_add_co_u32_e32 v200, vcc, 0x400000, v58
	s_nop 1
	v_addc_co_u32_e32 v201, vcc, 0, v59, vcc
	global_load_dwordx4 v[132:135], v[200:201], off
	global_load_dwordx4 v[136:139], v[200:201], off offset:1024
	global_load_dwordx4 v[140:143], v[200:201], off offset:2048
	global_load_dwordx4 v[144:147], v[200:201], off offset:3072
	v_add_co_u32_e32 v200, vcc, 0x500000, v58
	s_nop 1
	v_addc_co_u32_e32 v201, vcc, 0, v59, vcc
	global_load_dwordx4 v[148:151], v[200:201], off
	global_load_dwordx4 v[152:155], v[200:201], off offset:1024
	global_load_dwordx4 v[156:159], v[200:201], off offset:2048
	global_load_dwordx4 v[160:163], v[200:201], off offset:3072
	s_waitcnt vmcnt(0) lgkmcnt(0)
	v_pk_add_f32 v[84:85], v[84:85], v[100:101]
	v_pk_add_f32 v[86:87], v[86:87], v[102:103]
	v_pk_add_f32 v[88:89], v[88:89], v[104:105]
	v_pk_add_f32 v[90:91], v[90:91], v[106:107]
	v_pk_add_f32 v[92:93], v[92:93], v[108:109]
	v_pk_add_f32 v[94:95], v[94:95], v[110:111]
	v_pk_add_f32 v[96:97], v[96:97], v[112:113]
	v_pk_add_f32 v[98:99], v[98:99], v[114:115]
	v_pk_add_f32 v[84:85], v[84:85], v[116:117]
	v_pk_add_f32 v[86:87], v[86:87], v[118:119]
	v_pk_add_f32 v[88:89], v[88:89], v[120:121]
	v_pk_add_f32 v[90:91], v[90:91], v[122:123]
	v_pk_add_f32 v[92:93], v[92:93], v[124:125]
	v_pk_add_f32 v[94:95], v[94:95], v[126:127]
	v_pk_add_f32 v[96:97], v[96:97], v[128:129]
	v_pk_add_f32 v[98:99], v[98:99], v[130:131]
	v_pk_add_f32 v[84:85], v[84:85], v[132:133]
	v_pk_add_f32 v[86:87], v[86:87], v[134:135]
	v_pk_add_f32 v[88:89], v[88:89], v[136:137]
	v_pk_add_f32 v[90:91], v[90:91], v[138:139]
	v_pk_add_f32 v[92:93], v[92:93], v[140:141]
	v_pk_add_f32 v[94:95], v[94:95], v[142:143]
	v_pk_add_f32 v[96:97], v[96:97], v[144:145]
	v_pk_add_f32 v[98:99], v[98:99], v[146:147]
	v_mul_f32_e32 v84, 0xbfb8aa3b, v84
	v_mul_f32_e32 v85, 0xbfb8aa3b, v85
	v_mul_f32_e32 v86, 0xbfb8aa3b, v86
	v_mul_f32_e32 v87, 0xbfb8aa3b, v87
	v_mul_f32_e32 v88, 0xbfb8aa3b, v88
	v_mul_f32_e32 v89, 0xbfb8aa3b, v89
	v_mul_f32_e32 v90, 0xbfb8aa3b, v90
	v_mul_f32_e32 v91, 0xbfb8aa3b, v91
	v_mul_f32_e32 v92, 0xbfb8aa3b, v92
	v_mul_f32_e32 v93, 0xbfb8aa3b, v93
	v_mul_f32_e32 v94, 0xbfb8aa3b, v94
	v_mul_f32_e32 v95, 0xbfb8aa3b, v95
	v_mul_f32_e32 v96, 0xbfb8aa3b, v96
	v_mul_f32_e32 v97, 0xbfb8aa3b, v97
	v_mul_f32_e32 v98, 0xbfb8aa3b, v98
	v_mul_f32_e32 v99, 0xbfb8aa3b, v99
	v_exp_f32_e32 v84, v84
	v_exp_f32_e32 v85, v85
	v_exp_f32_e32 v86, v86
	v_exp_f32_e32 v87, v87
	v_exp_f32_e32 v88, v88
	v_exp_f32_e32 v89, v89
	v_exp_f32_e32 v90, v90
	v_exp_f32_e32 v91, v91
	v_exp_f32_e32 v92, v92
	v_exp_f32_e32 v93, v93
	v_exp_f32_e32 v94, v94
	v_exp_f32_e32 v95, v95
	v_exp_f32_e32 v96, v96
	v_exp_f32_e32 v97, v97
	v_exp_f32_e32 v98, v98
	v_exp_f32_e32 v99, v99
	s_nop 0
	v_add_f32_e32 v84, 1.0, v84
	v_add_f32_e32 v85, 1.0, v85
	v_add_f32_e32 v86, 1.0, v86
	v_add_f32_e32 v87, 1.0, v87
	v_add_f32_e32 v88, 1.0, v88
	v_add_f32_e32 v89, 1.0, v89
	v_add_f32_e32 v90, 1.0, v90
	v_add_f32_e32 v91, 1.0, v91
	v_add_f32_e32 v92, 1.0, v92
	v_add_f32_e32 v93, 1.0, v93
	v_add_f32_e32 v94, 1.0, v94
	v_add_f32_e32 v95, 1.0, v95
	v_add_f32_e32 v96, 1.0, v96
	v_add_f32_e32 v97, 1.0, v97
	v_add_f32_e32 v98, 1.0, v98
	v_add_f32_e32 v99, 1.0, v99
	v_rcp_f32_e32 v84, v84
	v_rcp_f32_e32 v85, v85
	v_rcp_f32_e32 v86, v86
	v_rcp_f32_e32 v87, v87
	v_rcp_f32_e32 v88, v88
	v_rcp_f32_e32 v89, v89
	v_rcp_f32_e32 v90, v90
	v_rcp_f32_e32 v91, v91
	v_rcp_f32_e32 v92, v92
	v_rcp_f32_e32 v93, v93
	v_rcp_f32_e32 v94, v94
	v_rcp_f32_e32 v95, v95
	v_rcp_f32_e32 v96, v96
	v_rcp_f32_e32 v97, v97
	v_rcp_f32_e32 v98, v98
	v_rcp_f32_e32 v99, v99
	s_nop 0
	v_cvt_pk_bf16_f32 v100, v84, v85
	v_cvt_pk_bf16_f32 v101, v86, v87
	v_cvt_pk_bf16_f32 v102, v88, v89
	v_cvt_pk_bf16_f32 v103, v90, v91
	v_cvt_pk_bf16_f32 v104, v92, v93
	v_cvt_pk_bf16_f32 v105, v94, v95
	v_cvt_pk_bf16_f32 v106, v96, v97
	v_cvt_pk_bf16_f32 v107, v98, v99
	v_lshlrev_b32_e32 v84, 16, v100
	v_and_b32_e32 v85, 0xffff0000, v100
	v_lshlrev_b32_e32 v86, 16, v101
	v_and_b32_e32 v87, 0xffff0000, v101
	v_lshlrev_b32_e32 v88, 16, v102
	v_and_b32_e32 v89, 0xffff0000, v102
	v_lshlrev_b32_e32 v90, 16, v103
	v_and_b32_e32 v91, 0xffff0000, v103
	v_lshlrev_b32_e32 v92, 16, v104
	v_and_b32_e32 v93, 0xffff0000, v104
	v_lshlrev_b32_e32 v94, 16, v105
	v_and_b32_e32 v95, 0xffff0000, v105
	v_lshlrev_b32_e32 v96, 16, v106
	v_and_b32_e32 v97, 0xffff0000, v106
	v_lshlrev_b32_e32 v98, 16, v107
	v_and_b32_e32 v99, 0xffff0000, v107
	v_pk_mul_f32 v[46:47], v[148:149], v[84:85]
	v_pk_mul_f32 v[48:49], v[150:151], v[86:87]
	v_pk_mul_f32 v[50:51], v[152:153], v[88:89]
	v_pk_mul_f32 v[52:53], v[154:155], v[90:91]
	v_pk_mul_f32 v[54:55], v[156:157], v[92:93]
	v_pk_mul_f32 v[56:57], v[158:159], v[94:95]
	v_pk_mul_f32 v[58:59], v[160:161], v[96:97]
	v_pk_mul_f32 v[60:61], v[162:163], v[98:99]
	s_mov_b32 s86, 0x800000
	s_mov_b64 s[36:37], 0
	s_nop 1

;     DI void init(int ntm_, int ntn_, int bid, int nb) {
;         ntm = ntm_; ntn = ntn_;
;         const int nt = ntm * ntn;
;         if ((nb & 7) == 0) { const int x = bid & 7, per = (nt + 7) >> 3; L = x * per + (bid >> 3); end = min((x + 1) * per, nt); step = nb >> 3; }
;         else { L = bid; end = nt; step = nb; }
;     }
; DI void gemm_ple(const Params& p, int bid, int nb, char* smem, const int tid) {
;     const bf16_t* XN = (const bf16_t*)(p.ws + B_XN);
;     const bf16_t* PB = (const bf16_t*)(p.ws + W_PBF);
;     const bf16_t* WG = (const bf16_t*)(p.ws + W_PG);
;     const bf16_t* WP = (const bf16_t*)(p.ws + W_PP);
;     const int ntn = 8, ntiles = 130 * ntn;
;     TileIter ti; ti.init(65, ntn, bid, nb);
;     int tm, tn, tm2 = 0, tn2 = 0;
;     bool have = ti.next(tm, tn);
;     Ring rg; rg.st = 0; rg.primed = 0;
;     for (; have; tm = tm2, tn = tn2) {
.LBB0_109:
	s_mov_b64 s[70:71], s[46:47]
	s_andn2_b64 vcc, exec, s[0:1]
	s_cbranch_vccnz .LBB0_147
.Lplm_entry:
	v_readlane_b32 s96, v240, 0
	v_readlane_b32 s97, v238, 54
	v_readfirstlane_b32 s10, v193
	s_nop 3
	s_lshr_b32 s10, s10, 6
	s_lshr_b32 s33, s10, 2
	s_and_b32 s36, s10, 3
	s_lshl_b32 s39, s10, 11
	s_add_i32 s39, s39, 16
	s_and_b32 s1, s97, 7
	s_cmp_eq_u32 s1, 0
	s_cbranch_scc0 .Lplm_simple
	s_and_b32 s1, s96, 7
	s_lshr_b32 s2, s96, 3
	s_lshl_b32 s3, s1, 5
	s_add_i32 s51, s3, s2
	s_add_i32 s52, s3, 32
	s_lshr_b32 s53, s97, 3
	s_branch .Lplm_ranged

; #define BAR() { __builtin_amdgcn_sched_barrier(0); __builtin_amdgcn_s_barrier(); asm volatile("" ::: "memory"); __builtin_amdgcn_sched_barrier(0); }
; DI void gemm_stream2(const bf16_t* __restrict__ A, int lda, const bf16_t* __restrict__ Bt, int ldb, int K, int m0, int n0, ...
;     ...
;     int st = rg.st;
;     if (!rg.primed) {
;         const int s1p = st == 2 ? 0 : st + 1;
;         BAR();
;         STAGE(st, 0);
;         STAGE(s1p, 1);
;         asm volatile("s_waitcnt vmcnt(6)" ::: "memory");
;         BAR();
;     }
;     if (grp == 1) BAR();
; DI void gemm_ple(const Params& p, int bid, int nb, char* smem, const int tid) {
;     ...
;     for (; have; tm = tm2, tn = tn2) {
;         have = ti.next(tm2, tn2);
;         const int m0 = tm * 256, n0 = tn * 128;
;         u32x2 gpk[4][4];
;         {
;             f32x4 gate[4][4]; zero_acc(gate);
;             gemm_stream2(XN, 1024, WG, 1024, 1024, m0, n0, true, PB, 256, WP, 256, m0, n0, smem, gate, tid, rg);
.Lplm_ranged:
	s_cmp_lt_u32 s51, s52
	s_cbranch_scc0 .Lpls_entry
	v_and_b32_e32 v190, 63, v193
	v_and_b32_e32 v191, 15, v190
	v_lshrrev_b32_e32 v17, 4, v190
	v_lshrrev_b32_e32 v18, 3, v190
	v_and_b32_e32 v19, 7, v190
	v_xor_b32_e32 v232, v19, v17
	v_lshlrev_b32_e32 v232, 4, v232
	v_or_b32_e32 v234, 4, v17
	v_xor_b32_e32 v234, v19, v234
	v_lshlrev_b32_e32 v234, 4, v234
	v_add_u32_e32 v233, 8, v18
	v_lshrrev_b32_e32 v195, 1, v191
	v_xor_b32_e32 v195, v17, v195
	v_lshlrev_b32_e32 v195, 4, v195
	s_lshl_b32 s1, s33, 6
	v_add_u32_e32 v227, s1, v191
	v_lshl_add_u32 v186, v227, 7, v195
	v_xor_b32_e32 v187, 64, v186
	v_lshlrev_b32_e32 v228, 11, v227
	s_lshl_b32 s1, s36, 5
	v_add_u32_e32 v227, s1, v191
	v_lshl_add_u32 v188, v227, 7, v195
	v_add_u32_e32 v188, 0x10000, v188
	v_xor_b32_e32 v189, 64, v188
	s_lshl_b32 s1, s36, 6
	v_lshl_add_u32 v229, v17, 3, s1
	v_add_u32_e32 v237, v228, v229
	v_and_b32_e32 v227, 1, v17
	v_mul_u32_u24_e32 v227, 0x7ff8, v227
	v_add_u32_e32 v236, v237, v227
	s_lshl_b32 s1, s10, 14
	v_lshl_add_u32 v235, v190, 4, s1
	s_mov_b32 s54, 0
.Lplm_tile:
	s_lshr_b32 s1, s51, 5
	s_and_b32 s2, s51, 31
	s_lshr_b32 s58, s2, 3
	s_and_b32 s2, s2, 7
	s_lshl_b32 s1, s1, 3
	s_add_i32 s57, s1, s2
	v_lshl_add_u32 v184, v18, 11, v232
	v_lshl_add_u32 v185, v233, 11, v234
	s_lshl_b32 s1, s57, 19
	s_lshl_b32 s2, s10, 15
	s_add_u32 s1, s1, s2
	s_add_u32 s1, s1, 0x3240000
	s_add_u32 s66, s88, s1
	s_addc_u32 s67, s89, 0
	s_add_u32 s68, s66, 0x40000
	s_addc_u32 s69, s67, 0
	s_lshl_b32 s1, s58, 19
	s_lshl_b32 s2, s10, 15
	s_add_u32 s1, s1, s2
	s_add_u32 s1, s1, 0x27a0000
	s_add_u32 s70, s88, s1
	s_addc_u32 s71, s89, 0
	s_add_u32 s72, s70, 0x40000
	s_addc_u32 s73, s71, 0
	s_add_i32 m0, s39, 0x10000
	s_nop 0
	global_load_lds_dwordx4 v184, s[70:71]
	s_add_i32 m0, s39, 0x10400
	s_nop 0
	global_load_lds_dwordx4 v185, s[70:71]
	s_add_u32 s70, s70, 0x80
	s_addc_u32 s71, s71, 0
	s_add_i32 m0, s39, 0x0
	s_nop 0
	global_load_lds_dwordx4 v184, s[66:67]
	s_add_i32 m0, s39, 0x400
	s_nop 0
	global_load_lds_dwordx4 v185, s[66:67]
	s_add_u32 s66, s66, 0x80
	s_addc_u32 s67, s67, 0
	s_add_i32 m0, s39, 0x14000
	s_nop 0
	global_load_lds_dwordx4 v184, s[72:73]
	s_add_i32 m0, s39, 0x14400
	s_nop 0
	global_load_lds_dwordx4 v185, s[72:73]
	s_add_u32 s72, s72, 0x80
	s_addc_u32 s73, s73, 0
	s_add_i32 m0, s39, 0x4000
	s_nop 0
	global_load_lds_dwordx4 v184, s[68:69]
	s_add_i32 m0, s39, 0x4400
	s_nop 0
	global_load_lds_dwordx4 v185, s[68:69]
	s_add_u32 s68, s68, 0x80
	s_addc_u32 s69, s69, 0
	s_add_i32 m0, s39, 0x18000
	s_nop 0
	global_load_lds_dwordx4 v184, s[70:71]
	s_add_i32 m0, s39, 0x18400
	s_nop 0
	global_load_lds_dwordx4 v185, s[70:71]
	s_add_u32 s70, s70, 0x80
	s_addc_u32 s71, s71, 0
	s_add_i32 m0, s39, 0x8000
	s_nop 0
	global_load_lds_dwordx4 v184, s[66:67]
	s_add_i32 m0, s39, 0x8400
	s_nop 0
	global_load_lds_dwordx4 v185, s[66:67]
	s_add_u32 s66, s66, 0x80
	s_addc_u32 s67, s67, 0
	s_add_i32 m0, s39, 0x1c000
	s_nop 0
	global_load_lds_dwordx4 v184, s[72:73]
	s_add_i32 m0, s39, 0x1c400
	s_nop 0
	global_load_lds_dwordx4 v185, s[72:73]
	s_add_u32 s72, s72, 0x80
	s_addc_u32 s73, s73, 0
	s_waitcnt vmcnt(8)
	s_barrier
	s_cmp_eq_u32 s33, 0
	s_cbranch_scc1 .Lplm_g_lead
	s_barrier
.Lplm_g_lead:
	v_mov_b64_e32 v[24:25], 0
	v_mov_b64_e32 v[26:27], 0
	v_mov_b64_e32 v[28:29], 0
	v_mov_b64_e32 v[30:31], 0
	v_mov_b64_e32 v[32:33], 0
	v_mov_b64_e32 v[34:35], 0
	v_mov_b64_e32 v[36:37], 0
	v_mov_b64_e32 v[38:39], 0
	v_mov_b64_e32 v[40:41], 0
	v_mov_b64_e32 v[42:43], 0
	v_mov_b64_e32 v[44:45], 0
	v_mov_b64_e32 v[46:47], 0
	v_mov_b64_e32 v[48:49], 0
	v_mov_b64_e32 v[50:51], 0
	v_mov_b64_e32 v[52:53], 0
	v_mov_b64_e32 v[54:55], 0
	v_mov_b64_e32 v[56:57], 0
	v_mov_b64_e32 v[58:59], 0
	v_mov_b64_e32 v[60:61], 0
	v_mov_b64_e32 v[62:63], 0
	v_mov_b64_e32 v[64:65], 0
	v_mov_b64_e32 v[66:67], 0
	v_mov_b64_e32 v[68:69], 0
	v_mov_b64_e32 v[70:71], 0
	v_mov_b64_e32 v[72:73], 0
	v_mov_b64_e32 v[74:75], 0
	v_mov_b64_e32 v[76:77], 0
	v_mov_b64_e32 v[78:79], 0
	v_mov_b64_e32 v[80:81], 0
	v_mov_b64_e32 v[82:83], 0
	v_mov_b64_e32 v[84:85], 0
	v_mov_b64_e32 v[86:87], 0
	v_mov_b64_e32 v[88:89], 0
	v_mov_b64_e32 v[90:91], 0
	v_mov_b64_e32 v[92:93], 0
	v_mov_b64_e32 v[94:95], 0
	v_mov_b64_e32 v[96:97], 0
	v_mov_b64_e32 v[98:99], 0
	v_mov_b64_e32 v[100:101], 0
	v_mov_b64_e32 v[102:103], 0
	v_mov_b64_e32 v[104:105], 0
	v_mov_b64_e32 v[106:107], 0
	v_mov_b64_e32 v[108:109], 0
	v_mov_b64_e32 v[110:111], 0
	v_mov_b64_e32 v[112:113], 0
	v_mov_b64_e32 v[114:115], 0
	v_mov_b64_e32 v[116:117], 0
	v_mov_b64_e32 v[118:119], 0
	v_mov_b64_e32 v[120:121], 0
	v_mov_b64_e32 v[122:123], 0
	v_mov_b64_e32 v[124:125], 0
	v_mov_b64_e32 v[126:127], 0
	v_mov_b64_e32 v[128:129], 0
	v_mov_b64_e32 v[130:131], 0
	v_mov_b64_e32 v[132:133], 0
	v_mov_b64_e32 v[134:135], 0
	v_mov_b64_e32 v[136:137], 0
	v_mov_b64_e32 v[138:139], 0
	v_mov_b64_e32 v[140:141], 0
	v_mov_b64_e32 v[142:143], 0
	v_mov_b64_e32 v[144:145], 0
	v_mov_b64_e32 v[146:147], 0
	v_mov_b64_e32 v[148:149], 0
	v_mov_b64_e32 v[150:151], 0
	s_mov_b32 s0, 7

; #define LAS __attribute__((address_space(3)))
; #define BAR() { __builtin_amdgcn_sched_barrier(0); __builtin_amdgcn_s_barrier(); asm volatile("" ::: "memory"); __builtin_amdgcn_sched_barrier(0); }
; DI void gemm_stream2(const bf16_t* __restrict__ A, int lda, const bf16_t* __restrict__ Bt, int ldb, int K, int m0, int n0, ...
;     ...
;     for (int kt = 0; kt < nk; ++kt) {
;         const bool pf = (kt + 2 < nk) || has_next, more = (kt + 1 < nk) || has_next;
;         const bf16_t* pa = (kt + 2 < nk) ? ga + (kt + 2) * 64 : gan + (kt + 2 - nk) * 64;
;         const bf16_t* pb = (kt + 2 < nk) ? gb + (kt + 2) * 64 : gbn + (kt + 2 - nk) * 64;
;         const int plda = (kt + 2 < nk) ? lda : ldan, pldb = (kt + 2 < nk) ? ldb : ldbn;
;         const int s2 = st >= 1 ? st - 1 : 2;
;         const LAS char* base = lds + st * 49152;
; #pragma unroll
;         for (int ks = 0; ks < 2; ++ks) {
;             const unsigned fo = ks ? fo1 : fo0;
;             bf16x8 af[4], bfr[4];
; #pragma unroll
;             for (int i = 0; i < 4; ++i) { af[i] = *(const LAS bf16x8*)(base + aoff + i * 2048 + fo); bfr[i] = *(const LAS bf16x8*)(base + boff + i * 2048 + fo); }
;             if (ks == 1 && more) { if (pf) asm volatile("s_waitcnt vmcnt(3)" ::: "memory"); else asm volatile("s_waitcnt vmcnt(0)" ::: "memory"); }
;             if (pf) { PIECE(s2, ks * 3 + 0); PIECE(s2, ks * 3 + 1); PIECE(s2, ks * 3 + 2); }
;             asm volatile("s_waitcnt lgkmcnt(0)" ::: "memory");
;             BAR();
;             __builtin_amdgcn_s_setprio(1);
; #pragma unroll
;             for (int mi = 0; mi < 4; ++mi)
; #pragma unroll
;                 for (int ni = 0; ni < 4; ++ni) acc[mi][ni] = __builtin_amdgcn_mfma_f32_16x16x32_bf16(bfr[ni], af[mi], acc[mi][ni], 0, 0, 0);
;             __builtin_amdgcn_s_setprio(0);
;             BAR();
;         }
.Lplm_nosw2:
	s_add_i32 m0, s39, 0x4000
	s_nop 0
	global_load_lds_dwordx4 v184, s[68:69]
	s_add_i32 m0, s39, 0x4400
	s_nop 0
	global_load_lds_dwordx4 v185, s[68:69]
	s_add_u32 s68, s68, 0x80
	s_addc_u32 s69, s69, 0
	s_waitcnt lgkmcnt(0)
	s_waitcnt vmcnt(8)
	s_barrier
	s_setprio 1
	v_mfma_f32_16x16x32_bf16 v[24:27], v[0:3], v[152:155], v[24:27]
	v_mfma_f32_16x16x32_bf16 v[28:31], v[8:11], v[152:155], v[28:31]
	v_mfma_f32_16x16x32_bf16 v[32:35], v[0:3], v[160:163], v[32:35]
	v_mfma_f32_16x16x32_bf16 v[36:39], v[8:11], v[160:163], v[36:39]
	v_mfma_f32_16x16x32_bf16 v[40:43], v[0:3], v[168:171], v[40:43]
	v_mfma_f32_16x16x32_bf16 v[44:47], v[8:11], v[168:171], v[44:47]
	v_mfma_f32_16x16x32_bf16 v[48:51], v[0:3], v[176:179], v[48:51]
	v_mfma_f32_16x16x32_bf16 v[52:55], v[8:11], v[176:179], v[52:55]
	v_mfma_f32_16x16x32_bf16 v[24:27], v[4:7], v[156:159], v[24:27]
	v_mfma_f32_16x16x32_bf16 v[28:31], v[12:15], v[156:159], v[28:31]
	v_mfma_f32_16x16x32_bf16 v[32:35], v[4:7], v[164:167], v[32:35]
	v_mfma_f32_16x16x32_bf16 v[36:39], v[12:15], v[164:167], v[36:39]
	v_mfma_f32_16x16x32_bf16 v[40:43], v[4:7], v[172:175], v[40:43]
	v_mfma_f32_16x16x32_bf16 v[44:47], v[12:15], v[172:175], v[44:47]
	v_mfma_f32_16x16x32_bf16 v[48:51], v[4:7], v[180:183], v[48:51]
	v_mfma_f32_16x16x32_bf16 v[52:55], v[12:15], v[180:183], v[52:55]
	v_mfma_f32_16x16x32_bf16 v[56:59], v[196:199], v[152:155], v[56:59]
	v_mfma_f32_16x16x32_bf16 v[60:63], v[204:207], v[152:155], v[60:63]
	v_mfma_f32_16x16x32_bf16 v[64:67], v[196:199], v[160:163], v[64:67]
	v_mfma_f32_16x16x32_bf16 v[68:71], v[204:207], v[160:163], v[68:71]
	v_mfma_f32_16x16x32_bf16 v[72:75], v[196:199], v[168:171], v[72:75]
	v_mfma_f32_16x16x32_bf16 v[76:79], v[204:207], v[168:171], v[76:79]
	v_mfma_f32_16x16x32_bf16 v[80:83], v[196:199], v[176:179], v[80:83]
	v_mfma_f32_16x16x32_bf16 v[84:87], v[204:207], v[176:179], v[84:87]
	v_mfma_f32_16x16x32_bf16 v[56:59], v[200:203], v[156:159], v[56:59]
	v_mfma_f32_16x16x32_bf16 v[60:63], v[208:211], v[156:159], v[60:63]
	v_mfma_f32_16x16x32_bf16 v[64:67], v[200:203], v[164:167], v[64:67]
	v_mfma_f32_16x16x32_bf16 v[68:71], v[208:211], v[164:167], v[68:71]
	v_mfma_f32_16x16x32_bf16 v[72:75], v[200:203], v[172:175], v[72:75]
	v_mfma_f32_16x16x32_bf16 v[76:79], v[208:211], v[172:175], v[76:79]
	v_mfma_f32_16x16x32_bf16 v[80:83], v[200:203], v[180:183], v[80:83]
	v_mfma_f32_16x16x32_bf16 v[84:87], v[208:211], v[180:183], v[84:87]
	s_setprio 0
	s_barrier
	ds_read_b128 v[152:155], v186 offset:49168
	ds_read_b128 v[156:159], v187 offset:49168
	ds_read_b128 v[160:163], v186 offset:51216
	ds_read_b128 v[164:167], v187 offset:51216
	ds_read_b128 v[168:171], v186 offset:53264
	ds_read_b128 v[172:175], v187 offset:53264
	ds_read_b128 v[176:179], v186 offset:55312
	ds_read_b128 v[180:183], v187 offset:55312
	s_add_i32 m0, s39, 0x18000
	s_nop 0
	global_load_lds_dwordx4 v184, s[70:71]
	s_add_i32 m0, s39, 0x18400
	s_nop 0
	global_load_lds_dwordx4 v185, s[70:71]
	s_add_u32 s70, s70, 0x80
	s_addc_u32 s71, s71, 0
	s_add_i32 m0, s39, 0x8000
	s_nop 0
	global_load_lds_dwordx4 v184, s[66:67]
	s_add_i32 m0, s39, 0x8400
	s_nop 0
	global_load_lds_dwordx4 v185, s[66:67]
	s_add_u32 s66, s66, 0x80
	s_addc_u32 s67, s67, 0
	s_add_i32 m0, s39, 0x1c000
	s_nop 0
	global_load_lds_dwordx4 v184, s[72:73]
	s_add_i32 m0, s39, 0x1c400
	s_nop 0
	global_load_lds_dwordx4 v185, s[72:73]
	s_add_u32 s72, s72, 0x80
	s_addc_u32 s73, s73, 0
	s_waitcnt lgkmcnt(0)
	s_waitcnt vmcnt(8)
	s_barrier
	s_setprio 1
	v_mfma_f32_16x16x32_bf16 v[88:91], v[0:3], v[152:155], v[88:91]
	v_mfma_f32_16x16x32_bf16 v[92:95], v[8:11], v[152:155], v[92:95]
	v_mfma_f32_16x16x32_bf16 v[96:99], v[0:3], v[160:163], v[96:99]
	v_mfma_f32_16x16x32_bf16 v[100:103], v[8:11], v[160:163], v[100:103]
	v_mfma_f32_16x16x32_bf16 v[104:107], v[0:3], v[168:171], v[104:107]
	v_mfma_f32_16x16x32_bf16 v[108:111], v[8:11], v[168:171], v[108:111]
	v_mfma_f32_16x16x32_bf16 v[112:115], v[0:3], v[176:179], v[112:115]
	v_mfma_f32_16x16x32_bf16 v[116:119], v[8:11], v[176:179], v[116:119]
	v_mfma_f32_16x16x32_bf16 v[88:91], v[4:7], v[156:159], v[88:91]
	v_mfma_f32_16x16x32_bf16 v[92:95], v[12:15], v[156:159], v[92:95]
	v_mfma_f32_16x16x32_bf16 v[96:99], v[4:7], v[164:167], v[96:99]
	v_mfma_f32_16x16x32_bf16 v[100:103], v[12:15], v[164:167], v[100:103]
	v_mfma_f32_16x16x32_bf16 v[104:107], v[4:7], v[172:175], v[104:107]
	v_mfma_f32_16x16x32_bf16 v[108:111], v[12:15], v[172:175], v[108:111]
	v_mfma_f32_16x16x32_bf16 v[112:115], v[4:7], v[180:183], v[112:115]
	v_mfma_f32_16x16x32_bf16 v[116:119], v[12:15], v[180:183], v[116:119]
	v_mfma_f32_16x16x32_bf16 v[120:123], v[196:199], v[152:155], v[120:123]
	v_mfma_f32_16x16x32_bf16 v[124:127], v[204:207], v[152:155], v[124:127]
	v_mfma_f32_16x16x32_bf16 v[128:131], v[196:199], v[160:163], v[128:131]
	v_mfma_f32_16x16x32_bf16 v[132:135], v[204:207], v[160:163], v[132:135]
	v_mfma_f32_16x16x32_bf16 v[136:139], v[196:199], v[168:171], v[136:139]
	v_mfma_f32_16x16x32_bf16 v[140:143], v[204:207], v[168:171], v[140:143]
	v_mfma_f32_16x16x32_bf16 v[144:147], v[196:199], v[176:179], v[144:147]
	v_mfma_f32_16x16x32_bf16 v[148:151], v[204:207], v[176:179], v[148:151]
	v_mfma_f32_16x16x32_bf16 v[120:123], v[200:203], v[156:159], v[120:123]
	v_mfma_f32_16x16x32_bf16 v[124:127], v[208:211], v[156:159], v[124:127]
	v_mfma_f32_16x16x32_bf16 v[128:131], v[200:203], v[164:167], v[128:131]
	v_mfma_f32_16x16x32_bf16 v[132:135], v[208:211], v[164:167], v[132:135]
	v_mfma_f32_16x16x32_bf16 v[136:139], v[200:203], v[172:175], v[136:139]
	v_mfma_f32_16x16x32_bf16 v[140:143], v[208:211], v[172:175], v[140:143]
	v_mfma_f32_16x16x32_bf16 v[144:147], v[200:203], v[180:183], v[144:147]
	v_mfma_f32_16x16x32_bf16 v[148:151], v[208:211], v[180:183], v[148:151]
	s_setprio 0
	s_barrier
; #define LAS __attribute__((address_space(3)))
; #define BAR() { __builtin_amdgcn_sched_barrier(0); __builtin_amdgcn_s_barrier(); asm volatile("" ::: "memory"); __builtin_amdgcn_sched_barrier(0); }
; DI void gemm_stream2(const bf16_t* __restrict__ A, int lda, const bf16_t* __restrict__ Bt, int ldb, int K, int m0, int n0, ...
;     ...
;     for (int kt = 0; kt < nk; ++kt) {
;         const bool pf = (kt + 2 < nk) || has_next, more = (kt + 1 < nk) || has_next;
;         const bf16_t* pa = (kt + 2 < nk) ? ga + (kt + 2) * 64 : gan + (kt + 2 - nk) * 64;
;         const bf16_t* pb = (kt + 2 < nk) ? gb + (kt + 2) * 64 : gbn + (kt + 2 - nk) * 64;
;         const int plda = (kt + 2 < nk) ? lda : ldan, pldb = (kt + 2 < nk) ? ldb : ldbn;
;         const int s2 = st >= 1 ? st - 1 : 2;
;         const LAS char* base = lds + st * 49152;
; #pragma unroll
;         for (int ks = 0; ks < 2; ++ks) {
;             const unsigned fo = ks ? fo1 : fo0;
;             bf16x8 af[4], bfr[4];
; #pragma unroll
;             for (int i = 0; i < 4; ++i) { af[i] = *(const LAS bf16x8*)(base + aoff + i * 2048 + fo); bfr[i] = *(const LAS bf16x8*)(base + boff + i * 2048 + fo); }
;             if (ks == 1 && more) { if (pf) asm volatile("s_waitcnt vmcnt(3)" ::: "memory"); else asm volatile("s_waitcnt vmcnt(0)" ::: "memory"); }
;             if (pf) { PIECE(s2, ks * 3 + 0); PIECE(s2, ks * 3 + 1); PIECE(s2, ks * 3 + 2); }
;             asm volatile("s_waitcnt lgkmcnt(0)" ::: "memory");
;             BAR();
;             __builtin_amdgcn_s_setprio(1);
; #pragma unroll
;             for (int mi = 0; mi < 4; ++mi)
; #pragma unroll
;                 for (int ni = 0; ni < 4; ++ni) acc[mi][ni] = __builtin_amdgcn_mfma_f32_16x16x32_bf16(bfr[ni], af[mi], acc[mi][ni], 0, 0, 0);
;             __builtin_amdgcn_s_setprio(0);
;             BAR();
;         }
	s_sub_u32 s0, s0, 1
	s_cmp_lg_u32 s0, 0
	s_cbranch_scc1 .Lplm_gloop
	ds_read_b128 v[0:3], v188 offset:16
	ds_read_b128 v[4:7], v189 offset:16
	ds_read_b128 v[8:11], v188 offset:2064
	ds_read_b128 v[12:15], v189 offset:2064
	ds_read_b128 v[196:199], v188 offset:16400
	ds_read_b128 v[200:203], v189 offset:16400
	ds_read_b128 v[204:207], v188 offset:18448
	ds_read_b128 v[208:211], v189 offset:18448
	ds_read_b128 v[152:155], v186 offset:16
	ds_read_b128 v[156:159], v187 offset:16
	ds_read_b128 v[160:163], v186 offset:2064
	ds_read_b128 v[164:167], v187 offset:2064
	ds_read_b128 v[168:171], v186 offset:4112
	ds_read_b128 v[172:175], v187 offset:4112
	ds_read_b128 v[176:179], v186 offset:6160
	ds_read_b128 v[180:183], v187 offset:6160
	s_add_i32 m0, s39, 0xc000
	s_nop 0
	global_load_lds_dwordx4 v184, s[68:69]
	s_add_i32 m0, s39, 0xc400
	s_nop 0
	global_load_lds_dwordx4 v185, s[68:69]
	s_add_u32 s68, s68, 0x80
	s_addc_u32 s69, s69, 0
	s_waitcnt lgkmcnt(0)
	s_waitcnt vmcnt(8)
	s_barrier
	s_setprio 1
	v_mfma_f32_16x16x32_bf16 v[24:27], v[0:3], v[152:155], v[24:27]
	v_mfma_f32_16x16x32_bf16 v[28:31], v[8:11], v[152:155], v[28:31]
	v_mfma_f32_16x16x32_bf16 v[32:35], v[0:3], v[160:163], v[32:35]
	v_mfma_f32_16x16x32_bf16 v[36:39], v[8:11], v[160:163], v[36:39]
	v_mfma_f32_16x16x32_bf16 v[40:43], v[0:3], v[168:171], v[40:43]
	v_mfma_f32_16x16x32_bf16 v[44:47], v[8:11], v[168:171], v[44:47]
	v_mfma_f32_16x16x32_bf16 v[48:51], v[0:3], v[176:179], v[48:51]
	v_mfma_f32_16x16x32_bf16 v[52:55], v[8:11], v[176:179], v[52:55]
	v_mfma_f32_16x16x32_bf16 v[24:27], v[4:7], v[156:159], v[24:27]
	v_mfma_f32_16x16x32_bf16 v[28:31], v[12:15], v[156:159], v[28:31]
	v_mfma_f32_16x16x32_bf16 v[32:35], v[4:7], v[164:167], v[32:35]
	v_mfma_f32_16x16x32_bf16 v[36:39], v[12:15], v[164:167], v[36:39]
	v_mfma_f32_16x16x32_bf16 v[40:43], v[4:7], v[172:175], v[40:43]
	v_mfma_f32_16x16x32_bf16 v[44:47], v[12:15], v[172:175], v[44:47]
	v_mfma_f32_16x16x32_bf16 v[48:51], v[4:7], v[180:183], v[48:51]
	v_mfma_f32_16x16x32_bf16 v[52:55], v[12:15], v[180:183], v[52:55]
	v_mfma_f32_16x16x32_bf16 v[56:59], v[196:199], v[152:155], v[56:59]
	v_mfma_f32_16x16x32_bf16 v[60:63], v[204:207], v[152:155], v[60:63]
	v_mfma_f32_16x16x32_bf16 v[64:67], v[196:199], v[160:163], v[64:67]
	v_mfma_f32_16x16x32_bf16 v[68:71], v[204:207], v[160:163], v[68:71]
	v_mfma_f32_16x16x32_bf16 v[72:75], v[196:199], v[168:171], v[72:75]
	v_mfma_f32_16x16x32_bf16 v[76:79], v[204:207], v[168:171], v[76:79]
	v_mfma_f32_16x16x32_bf16 v[80:83], v[196:199], v[176:179], v[80:83]
	v_mfma_f32_16x16x32_bf16 v[84:87], v[204:207], v[176:179], v[84:87]
	v_mfma_f32_16x16x32_bf16 v[56:59], v[200:203], v[156:159], v[56:59]
	v_mfma_f32_16x16x32_bf16 v[60:63], v[208:211], v[156:159], v[60:63]
	v_mfma_f32_16x16x32_bf16 v[64:67], v[200:203], v[164:167], v[64:67]
	v_mfma_f32_16x16x32_bf16 v[68:71], v[208:211], v[164:167], v[68:71]
	v_mfma_f32_16x16x32_bf16 v[72:75], v[200:203], v[172:175], v[72:75]
	v_mfma_f32_16x16x32_bf16 v[76:79], v[208:211], v[172:175], v[76:79]
	v_mfma_f32_16x16x32_bf16 v[80:83], v[200:203], v[180:183], v[80:83]
	v_mfma_f32_16x16x32_bf16 v[84:87], v[208:211], v[180:183], v[84:87]
	s_setprio 0
	s_barrier
	ds_read_b128 v[152:155], v186 offset:16400
	ds_read_b128 v[156:159], v187 offset:16400
	ds_read_b128 v[160:163], v186 offset:18448
	ds_read_b128 v[164:167], v187 offset:18448
	ds_read_b128 v[168:171], v186 offset:20496
	ds_read_b128 v[172:175], v187 offset:20496
	ds_read_b128 v[176:179], v186 offset:22544
	ds_read_b128 v[180:183], v187 offset:22544
	s_waitcnt lgkmcnt(0)
	s_waitcnt vmcnt(2)
	s_barrier
	s_setprio 1
	v_mfma_f32_16x16x32_bf16 v[88:91], v[0:3], v[152:155], v[88:91]
	v_mfma_f32_16x16x32_bf16 v[92:95], v[8:11], v[152:155], v[92:95]
	v_mfma_f32_16x16x32_bf16 v[96:99], v[0:3], v[160:163], v[96:99]
	v_mfma_f32_16x16x32_bf16 v[100:103], v[8:11], v[160:163], v[100:103]
	v_mfma_f32_16x16x32_bf16 v[104:107], v[0:3], v[168:171], v[104:107]
	v_mfma_f32_16x16x32_bf16 v[108:111], v[8:11], v[168:171], v[108:111]
	v_mfma_f32_16x16x32_bf16 v[112:115], v[0:3], v[176:179], v[112:115]
	v_mfma_f32_16x16x32_bf16 v[116:119], v[8:11], v[176:179], v[116:119]
	v_mfma_f32_16x16x32_bf16 v[88:91], v[4:7], v[156:159], v[88:91]
	v_mfma_f32_16x16x32_bf16 v[92:95], v[12:15], v[156:159], v[92:95]
	v_mfma_f32_16x16x32_bf16 v[96:99], v[4:7], v[164:167], v[96:99]
	v_mfma_f32_16x16x32_bf16 v[100:103], v[12:15], v[164:167], v[100:103]
	v_mfma_f32_16x16x32_bf16 v[104:107], v[4:7], v[172:175], v[104:107]
	v_mfma_f32_16x16x32_bf16 v[108:111], v[12:15], v[172:175], v[108:111]
	v_mfma_f32_16x16x32_bf16 v[112:115], v[4:7], v[180:183], v[112:115]
	v_mfma_f32_16x16x32_bf16 v[116:119], v[12:15], v[180:183], v[116:119]
	v_mfma_f32_16x16x32_bf16 v[120:123], v[196:199], v[152:155], v[120:123]
	v_mfma_f32_16x16x32_bf16 v[124:127], v[204:207], v[152:155], v[124:127]
	v_mfma_f32_16x16x32_bf16 v[128:131], v[196:199], v[160:163], v[128:131]
	v_mfma_f32_16x16x32_bf16 v[132:135], v[204:207], v[160:163], v[132:135]
	v_mfma_f32_16x16x32_bf16 v[136:139], v[196:199], v[168:171], v[136:139]
	v_mfma_f32_16x16x32_bf16 v[140:143], v[204:207], v[168:171], v[140:143]
	v_mfma_f32_16x16x32_bf16 v[144:147], v[196:199], v[176:179], v[144:147]
	v_mfma_f32_16x16x32_bf16 v[148:151], v[204:207], v[176:179], v[148:151]
	v_mfma_f32_16x16x32_bf16 v[120:123], v[200:203], v[156:159], v[120:123]
	v_mfma_f32_16x16x32_bf16 v[124:127], v[208:211], v[156:159], v[124:127]
	v_mfma_f32_16x16x32_bf16 v[128:131], v[200:203], v[164:167], v[128:131]
	v_mfma_f32_16x16x32_bf16 v[132:135], v[208:211], v[164:167], v[132:135]
	v_mfma_f32_16x16x32_bf16 v[136:139], v[200:203], v[172:175], v[136:139]
	v_mfma_f32_16x16x32_bf16 v[140:143], v[208:211], v[172:175], v[140:143]
	v_mfma_f32_16x16x32_bf16 v[144:147], v[200:203], v[180:183], v[144:147]
	v_mfma_f32_16x16x32_bf16 v[148:151], v[208:211], v[180:183], v[148:151]
	s_setprio 0
	s_barrier
; #define LAS __attribute__((address_space(3)))
; #define BAR() { __builtin_amdgcn_sched_barrier(0); __builtin_amdgcn_s_barrier(); asm volatile("" ::: "memory"); __builtin_amdgcn_sched_barrier(0); }
; DI void gemm_stream2(const bf16_t* __restrict__ A, int lda, const bf16_t* __restrict__ Bt, int ldb, int K, int m0, int n0, ...
;     ...
;     for (int kt = 0; kt < nk; ++kt) {
;         const bool pf = (kt + 2 < nk) || has_next, more = (kt + 1 < nk) || has_next;
;         const bf16_t* pa = (kt + 2 < nk) ? ga + (kt + 2) * 64 : gan + (kt + 2 - nk) * 64;
;         const bf16_t* pb = (kt + 2 < nk) ? gb + (kt + 2) * 64 : gbn + (kt + 2 - nk) * 64;
;         const int plda = (kt + 2 < nk) ? lda : ldan, pldb = (kt + 2 < nk) ? ldb : ldbn;
;         const int s2 = st >= 1 ? st - 1 : 2;
;         const LAS char* base = lds + st * 49152;
; #pragma unroll
;         for (int ks = 0; ks < 2; ++ks) {
;             const unsigned fo = ks ? fo1 : fo0;
;             bf16x8 af[4], bfr[4];
; #pragma unroll
;             for (int i = 0; i < 4; ++i) { af[i] = *(const LAS bf16x8*)(base + aoff + i * 2048 + fo); bfr[i] = *(const LAS bf16x8*)(base + boff + i * 2048 + fo); }
;             if (ks == 1 && more) { if (pf) asm volatile("s_waitcnt vmcnt(3)" ::: "memory"); else asm volatile("s_waitcnt vmcnt(0)" ::: "memory"); }
;             if (pf) { PIECE(s2, ks * 3 + 0); PIECE(s2, ks * 3 + 1); PIECE(s2, ks * 3 + 2); }
;             asm volatile("s_waitcnt lgkmcnt(0)" ::: "memory");
;             BAR();
;             __builtin_amdgcn_s_setprio(1);
; #pragma unroll
;             for (int mi = 0; mi < 4; ++mi)
; #pragma unroll
;                 for (int ni = 0; ni < 4; ++ni) acc[mi][ni] = __builtin_amdgcn_mfma_f32_16x16x32_bf16(bfr[ni], af[mi], acc[mi][ni], 0, 0, 0);
;             __builtin_amdgcn_s_setprio(0);
;             BAR();
;         }
;         st = st == 2 ? 0 : st + 1;
;     }
;     if (grp == 0) BAR();
	ds_read_b128 v[0:3], v188 offset:32784
	ds_read_b128 v[4:7], v189 offset:32784
	ds_read_b128 v[8:11], v188 offset:34832
	ds_read_b128 v[12:15], v189 offset:34832
	ds_read_b128 v[196:199], v188 offset:49168
	ds_read_b128 v[200:203], v189 offset:49168
	ds_read_b128 v[204:207], v188 offset:51216
	ds_read_b128 v[208:211], v189 offset:51216
	ds_read_b128 v[152:155], v186 offset:32784
	ds_read_b128 v[156:159], v187 offset:32784
	ds_read_b128 v[160:163], v186 offset:34832
	ds_read_b128 v[164:167], v187 offset:34832
	ds_read_b128 v[168:171], v186 offset:36880
	ds_read_b128 v[172:175], v187 offset:36880
	ds_read_b128 v[176:179], v186 offset:38928
	ds_read_b128 v[180:183], v187 offset:38928
	s_waitcnt lgkmcnt(0)
	s_waitcnt vmcnt(0)
	s_barrier
	s_setprio 1
	v_mfma_f32_16x16x32_bf16 v[24:27], v[0:3], v[152:155], v[24:27]
	v_mfma_f32_16x16x32_bf16 v[28:31], v[8:11], v[152:155], v[28:31]
	v_mfma_f32_16x16x32_bf16 v[32:35], v[0:3], v[160:163], v[32:35]
	v_mfma_f32_16x16x32_bf16 v[36:39], v[8:11], v[160:163], v[36:39]
	v_mfma_f32_16x16x32_bf16 v[40:43], v[0:3], v[168:171], v[40:43]
	v_mfma_f32_16x16x32_bf16 v[44:47], v[8:11], v[168:171], v[44:47]
	v_mfma_f32_16x16x32_bf16 v[48:51], v[0:3], v[176:179], v[48:51]
	v_mfma_f32_16x16x32_bf16 v[52:55], v[8:11], v[176:179], v[52:55]
	v_mfma_f32_16x16x32_bf16 v[24:27], v[4:7], v[156:159], v[24:27]
	v_mfma_f32_16x16x32_bf16 v[28:31], v[12:15], v[156:159], v[28:31]
	v_mfma_f32_16x16x32_bf16 v[32:35], v[4:7], v[164:167], v[32:35]
	v_mfma_f32_16x16x32_bf16 v[36:39], v[12:15], v[164:167], v[36:39]
	v_mfma_f32_16x16x32_bf16 v[40:43], v[4:7], v[172:175], v[40:43]
	v_mfma_f32_16x16x32_bf16 v[44:47], v[12:15], v[172:175], v[44:47]
	v_mfma_f32_16x16x32_bf16 v[48:51], v[4:7], v[180:183], v[48:51]
	v_mfma_f32_16x16x32_bf16 v[52:55], v[12:15], v[180:183], v[52:55]
	v_mfma_f32_16x16x32_bf16 v[56:59], v[196:199], v[152:155], v[56:59]
	v_mfma_f32_16x16x32_bf16 v[60:63], v[204:207], v[152:155], v[60:63]
	v_mfma_f32_16x16x32_bf16 v[64:67], v[196:199], v[160:163], v[64:67]
	v_mfma_f32_16x16x32_bf16 v[68:71], v[204:207], v[160:163], v[68:71]
	v_mfma_f32_16x16x32_bf16 v[72:75], v[196:199], v[168:171], v[72:75]
	v_mfma_f32_16x16x32_bf16 v[76:79], v[204:207], v[168:171], v[76:79]
	v_mfma_f32_16x16x32_bf16 v[80:83], v[196:199], v[176:179], v[80:83]
	v_mfma_f32_16x16x32_bf16 v[84:87], v[204:207], v[176:179], v[84:87]
	v_mfma_f32_16x16x32_bf16 v[56:59], v[200:203], v[156:159], v[56:59]
	v_mfma_f32_16x16x32_bf16 v[60:63], v[208:211], v[156:159], v[60:63]
	v_mfma_f32_16x16x32_bf16 v[64:67], v[200:203], v[164:167], v[64:67]
	v_mfma_f32_16x16x32_bf16 v[68:71], v[208:211], v[164:167], v[68:71]
	v_mfma_f32_16x16x32_bf16 v[72:75], v[200:203], v[172:175], v[72:75]
	v_mfma_f32_16x16x32_bf16 v[76:79], v[208:211], v[172:175], v[76:79]
	v_mfma_f32_16x16x32_bf16 v[80:83], v[200:203], v[180:183], v[80:83]
	v_mfma_f32_16x16x32_bf16 v[84:87], v[208:211], v[180:183], v[84:87]
	s_setprio 0
	s_barrier
	ds_read_b128 v[152:155], v186 offset:49168
	ds_read_b128 v[156:159], v187 offset:49168
	ds_read_b128 v[160:163], v186 offset:51216
	ds_read_b128 v[164:167], v187 offset:51216
	ds_read_b128 v[168:171], v186 offset:53264
	ds_read_b128 v[172:175], v187 offset:53264
	ds_read_b128 v[176:179], v186 offset:55312
	ds_read_b128 v[180:183], v187 offset:55312
	s_waitcnt lgkmcnt(0)
	s_barrier
	s_setprio 1
	v_mfma_f32_16x16x32_bf16 v[88:91], v[0:3], v[152:155], v[88:91]
	v_mfma_f32_16x16x32_bf16 v[92:95], v[8:11], v[152:155], v[92:95]
	v_mfma_f32_16x16x32_bf16 v[96:99], v[0:3], v[160:163], v[96:99]
	v_mfma_f32_16x16x32_bf16 v[100:103], v[8:11], v[160:163], v[100:103]
	v_mfma_f32_16x16x32_bf16 v[104:107], v[0:3], v[168:171], v[104:107]
	v_mfma_f32_16x16x32_bf16 v[108:111], v[8:11], v[168:171], v[108:111]
	v_mfma_f32_16x16x32_bf16 v[112:115], v[0:3], v[176:179], v[112:115]
	v_mfma_f32_16x16x32_bf16 v[116:119], v[8:11], v[176:179], v[116:119]
	v_mfma_f32_16x16x32_bf16 v[88:91], v[4:7], v[156:159], v[88:91]
	v_mfma_f32_16x16x32_bf16 v[92:95], v[12:15], v[156:159], v[92:95]
	v_mfma_f32_16x16x32_bf16 v[96:99], v[4:7], v[164:167], v[96:99]
	v_mfma_f32_16x16x32_bf16 v[100:103], v[12:15], v[164:167], v[100:103]
	v_mfma_f32_16x16x32_bf16 v[104:107], v[4:7], v[172:175], v[104:107]
	v_mfma_f32_16x16x32_bf16 v[108:111], v[12:15], v[172:175], v[108:111]
	v_mfma_f32_16x16x32_bf16 v[112:115], v[4:7], v[180:183], v[112:115]
	v_mfma_f32_16x16x32_bf16 v[116:119], v[12:15], v[180:183], v[116:119]
	v_mfma_f32_16x16x32_bf16 v[120:123], v[196:199], v[152:155], v[120:123]
	v_mfma_f32_16x16x32_bf16 v[124:127], v[204:207], v[152:155], v[124:127]
	v_mfma_f32_16x16x32_bf16 v[128:131], v[196:199], v[160:163], v[128:131]
	v_mfma_f32_16x16x32_bf16 v[132:135], v[204:207], v[160:163], v[132:135]
	v_mfma_f32_16x16x32_bf16 v[136:139], v[196:199], v[168:171], v[136:139]
	v_mfma_f32_16x16x32_bf16 v[140:143], v[204:207], v[168:171], v[140:143]
	v_mfma_f32_16x16x32_bf16 v[144:147], v[196:199], v[176:179], v[144:147]
	v_mfma_f32_16x16x32_bf16 v[148:151], v[204:207], v[176:179], v[148:151]
	v_mfma_f32_16x16x32_bf16 v[120:123], v[200:203], v[156:159], v[120:123]
	v_mfma_f32_16x16x32_bf16 v[124:127], v[208:211], v[156:159], v[124:127]
	v_mfma_f32_16x16x32_bf16 v[128:131], v[200:203], v[164:167], v[128:131]
	v_mfma_f32_16x16x32_bf16 v[132:135], v[208:211], v[164:167], v[132:135]
	v_mfma_f32_16x16x32_bf16 v[136:139], v[200:203], v[172:175], v[136:139]
	v_mfma_f32_16x16x32_bf16 v[140:143], v[208:211], v[172:175], v[140:143]
	v_mfma_f32_16x16x32_bf16 v[144:147], v[200:203], v[180:183], v[144:147]
	v_mfma_f32_16x16x32_bf16 v[148:151], v[208:211], v[180:183], v[148:151]
	s_setprio 0
	s_barrier
	s_cmp_lg_u32 s33, 0
	s_cbranch_scc1 .Lplm_gdone
	s_barrier
; DI unsigned pk2(float lo, float hi) { const f32x2 v = {lo, hi}; return __builtin_bit_cast(unsigned, __builtin_convertvector(v, bf2_t)); }
; DI void gemm_ple(const Params& p, int bid, int nb, char* smem, const int tid) {
;     ...
; #pragma unroll
;             for (int i = 0; i < 4; ++i)
; #pragma unroll
;                 for (int j = 0; j < 4; ++j) {
;                     float g[4];
; #pragma unroll
;                     for (int e = 0; e < 4; ++e) g[e] = __builtin_amdgcn_rcpf(1.0f + __builtin_amdgcn_exp2f(-LOG2E * gate[i][j][e]));
;                     gpk[i][j].x = pk2(g[0], g[1]); gpk[i][j].y = pk2(g[2], g[3]);
;                 }
;         }
;         f32x4 acc[4][4]; zero_acc(acc);
;         gemm_stream2(PB, 256, WP, 256, 256, m0, n0, have, XN, 1024, WG, 1024, tm2 * 256, tn2 * 128, smem, acc, tid, rg);
.Lplm_gdone:
	v_lshl_add_u32 v184, v18, 9, v232
	v_lshl_add_u32 v185, v233, 9, v234
	s_lshl_b32 s1, s57, 17
	s_lshl_b32 s2, s10, 13
	s_add_u32 s1, s1, s2
	s_add_u32 s1, s1, 0x2a20000
	s_add_u32 s66, s88, s1
	s_addc_u32 s67, s89, 0
	s_add_u32 s68, s66, 0x10000
	s_addc_u32 s69, s67, 0
	s_lshl_b32 s1, s58, 17
	s_lshl_b32 s2, s10, 13
	s_add_u32 s1, s1, s2
	s_add_u32 s1, s1, 0x29a0000
	s_add_u32 s70, s88, s1
	s_addc_u32 s71, s89, 0
	s_add_u32 s72, s70, 0x10000
	s_addc_u32 s73, s71, 0
	s_add_i32 m0, s39, 0x10000
	s_nop 0
	global_load_lds_dwordx4 v184, s[70:71]
	s_add_i32 m0, s39, 0x10400
	s_nop 0
	global_load_lds_dwordx4 v185, s[70:71]
	s_add_u32 s70, s70, 0x80
	s_addc_u32 s71, s71, 0
	s_add_i32 m0, s39, 0x0
	s_nop 0
	global_load_lds_dwordx4 v184, s[66:67]
	s_add_i32 m0, s39, 0x400
	s_nop 0
	global_load_lds_dwordx4 v185, s[66:67]
	s_add_u32 s66, s66, 0x80
	s_addc_u32 s67, s67, 0
	s_add_i32 m0, s39, 0x14000
	s_nop 0
	global_load_lds_dwordx4 v184, s[72:73]
	s_add_i32 m0, s39, 0x14400
	s_nop 0
	global_load_lds_dwordx4 v185, s[72:73]
	s_add_u32 s72, s72, 0x80
	s_addc_u32 s73, s73, 0
	s_add_i32 m0, s39, 0x4000
	s_nop 0
	global_load_lds_dwordx4 v184, s[68:69]
	s_add_i32 m0, s39, 0x4400
	s_nop 0
	global_load_lds_dwordx4 v185, s[68:69]
	s_add_u32 s68, s68, 0x80
	s_addc_u32 s69, s69, 0
	s_add_i32 m0, s39, 0x18000
	s_nop 0
	global_load_lds_dwordx4 v184, s[70:71]
	s_add_i32 m0, s39, 0x18400
	s_nop 0
	global_load_lds_dwordx4 v185, s[70:71]
	s_add_u32 s70, s70, 0x80
	s_addc_u32 s71, s71, 0
	s_add_i32 m0, s39, 0x8000
	s_nop 0
	global_load_lds_dwordx4 v184, s[66:67]
	s_add_i32 m0, s39, 0x8400
	s_nop 0
	global_load_lds_dwordx4 v185, s[66:67]
	s_add_u32 s66, s66, 0x80
	s_addc_u32 s67, s67, 0
	s_add_i32 m0, s39, 0x1c000
	s_nop 0
	global_load_lds_dwordx4 v184, s[72:73]
	s_add_i32 m0, s39, 0x1c400
	s_nop 0
	global_load_lds_dwordx4 v185, s[72:73]
	s_add_u32 s72, s72, 0x80
	s_addc_u32 s73, s73, 0
	s_lshl_b32 s1, s51, 17
	s_add_u32 s1, s1, 0x52c0000
	s_add_u32 s2, s88, s1
	s_addc_u32 s3, s89, 0
	s_nop 7
	s_nop 7
	v_mul_f32_e32 v152, 0xbfb8aa3b, v24
	v_mul_f32_e32 v153, 0xbfb8aa3b, v25
	v_mul_f32_e32 v154, 0xbfb8aa3b, v26
	v_mul_f32_e32 v155, 0xbfb8aa3b, v27
	v_mul_f32_e32 v156, 0xbfb8aa3b, v32
	v_mul_f32_e32 v157, 0xbfb8aa3b, v33
	v_mul_f32_e32 v158, 0xbfb8aa3b, v34
	v_mul_f32_e32 v159, 0xbfb8aa3b, v35
	v_exp_f32_e32 v152, v152
	v_exp_f32_e32 v153, v153
	v_exp_f32_e32 v154, v154
	v_exp_f32_e32 v155, v155
	v_exp_f32_e32 v156, v156
	v_exp_f32_e32 v157, v157
	v_exp_f32_e32 v158, v158
	v_exp_f32_e32 v159, v159
	v_add_f32_e32 v152, 1.0, v152
	v_add_f32_e32 v153, 1.0, v153
	v_add_f32_e32 v154, 1.0, v154
	v_add_f32_e32 v155, 1.0, v155
	v_add_f32_e32 v156, 1.0, v156
	v_add_f32_e32 v157, 1.0, v157
	v_add_f32_e32 v158, 1.0, v158
	v_add_f32_e32 v159, 1.0, v159
	v_rcp_f32_e32 v152, v152
	v_rcp_f32_e32 v153, v153
	v_rcp_f32_e32 v154, v154
	v_rcp_f32_e32 v155, v155
	v_rcp_f32_e32 v156, v156
	v_rcp_f32_e32 v157, v157
	v_rcp_f32_e32 v158, v158
	v_rcp_f32_e32 v159, v159
	s_nop 0
	v_cvt_pk_bf16_f32 v152, v152, v153
	v_cvt_pk_bf16_f32 v153, v154, v155
	v_cvt_pk_bf16_f32 v154, v156, v157
	v_cvt_pk_bf16_f32 v155, v158, v159
	global_store_dwordx4 v235, v[152:155], s[2:3] offset:0
	v_mul_f32_e32 v160, 0xbfb8aa3b, v28
	v_mul_f32_e32 v161, 0xbfb8aa3b, v29
	v_mul_f32_e32 v162, 0xbfb8aa3b, v30
	v_mul_f32_e32 v163, 0xbfb8aa3b, v31
	v_mul_f32_e32 v164, 0xbfb8aa3b, v36
	v_mul_f32_e32 v165, 0xbfb8aa3b, v37
	v_mul_f32_e32 v166, 0xbfb8aa3b, v38
	v_mul_f32_e32 v167, 0xbfb8aa3b, v39
	v_exp_f32_e32 v160, v160
	v_exp_f32_e32 v161, v161
	v_exp_f32_e32 v162, v162
	v_exp_f32_e32 v163, v163
	v_exp_f32_e32 v164, v164
	v_exp_f32_e32 v165, v165
	v_exp_f32_e32 v166, v166
	v_exp_f32_e32 v167, v167
	v_add_f32_e32 v160, 1.0, v160
	v_add_f32_e32 v161, 1.0, v161
	v_add_f32_e32 v162, 1.0, v162
	v_add_f32_e32 v163, 1.0, v163
	v_add_f32_e32 v164, 1.0, v164
	v_add_f32_e32 v165, 1.0, v165
	v_add_f32_e32 v166, 1.0, v166
	v_add_f32_e32 v167, 1.0, v167
	v_rcp_f32_e32 v160, v160
	v_rcp_f32_e32 v161, v161
	v_rcp_f32_e32 v162, v162
	v_rcp_f32_e32 v163, v163
	v_rcp_f32_e32 v164, v164
	v_rcp_f32_e32 v165, v165
	v_rcp_f32_e32 v166, v166
	v_rcp_f32_e32 v167, v167
	s_nop 0
	v_cvt_pk_bf16_f32 v160, v160, v161
	v_cvt_pk_bf16_f32 v161, v162, v163
	v_cvt_pk_bf16_f32 v162, v164, v165
	v_cvt_pk_bf16_f32 v163, v166, v167
	global_store_dwordx4 v235, v[160:163], s[2:3] offset:1024
	v_mul_f32_e32 v168, 0xbfb8aa3b, v56
	v_mul_f32_e32 v169, 0xbfb8aa3b, v57
	v_mul_f32_e32 v170, 0xbfb8aa3b, v58
	v_mul_f32_e32 v171, 0xbfb8aa3b, v59
	v_mul_f32_e32 v172, 0xbfb8aa3b, v64
	v_mul_f32_e32 v173, 0xbfb8aa3b, v65
	v_mul_f32_e32 v174, 0xbfb8aa3b, v66
	v_mul_f32_e32 v175, 0xbfb8aa3b, v67
	v_exp_f32_e32 v168, v168
	v_exp_f32_e32 v169, v169
	v_exp_f32_e32 v170, v170
	v_exp_f32_e32 v171, v171
	v_exp_f32_e32 v172, v172
	v_exp_f32_e32 v173, v173
	v_exp_f32_e32 v174, v174
	v_exp_f32_e32 v175, v175
	v_add_f32_e32 v168, 1.0, v168
	v_add_f32_e32 v169, 1.0, v169
	v_add_f32_e32 v170, 1.0, v170
	v_add_f32_e32 v171, 1.0, v171
	v_add_f32_e32 v172, 1.0, v172
	v_add_f32_e32 v173, 1.0, v173
	v_add_f32_e32 v174, 1.0, v174
	v_add_f32_e32 v175, 1.0, v175
	v_rcp_f32_e32 v168, v168
	v_rcp_f32_e32 v169, v169
	v_rcp_f32_e32 v170, v170
	v_rcp_f32_e32 v171, v171
	v_rcp_f32_e32 v172, v172
	v_rcp_f32_e32 v173, v173
	v_rcp_f32_e32 v174, v174
	v_rcp_f32_e32 v175, v175
	s_nop 0
	v_cvt_pk_bf16_f32 v168, v168, v169
	v_cvt_pk_bf16_f32 v169, v170, v171
	v_cvt_pk_bf16_f32 v170, v172, v173
	v_cvt_pk_bf16_f32 v171, v174, v175
	global_store_dwordx4 v235, v[168:171], s[2:3] offset:2048
	v_mul_f32_e32 v176, 0xbfb8aa3b, v60
	v_mul_f32_e32 v177, 0xbfb8aa3b, v61
	v_mul_f32_e32 v178, 0xbfb8aa3b, v62
; DI unsigned pk2(float lo, float hi) { const f32x2 v = {lo, hi}; return __builtin_bit_cast(unsigned, __builtin_convertvector(v, bf2_t)); }
; DI void gemm_ple(const Params& p, int bid, int nb, char* smem, const int tid) {
;     ...
; #pragma unroll
;             for (int i = 0; i < 4; ++i)
; #pragma unroll
;                 for (int j = 0; j < 4; ++j) {
;                     float g[4];
; #pragma unroll
;                     for (int e = 0; e < 4; ++e) g[e] = __builtin_amdgcn_rcpf(1.0f + __builtin_amdgcn_exp2f(-LOG2E * gate[i][j][e]));
;                     gpk[i][j].x = pk2(g[0], g[1]); gpk[i][j].y = pk2(g[2], g[3]);
;                 }
	v_mul_f32_e32 v179, 0xbfb8aa3b, v63
	v_mul_f32_e32 v180, 0xbfb8aa3b, v68
	v_mul_f32_e32 v181, 0xbfb8aa3b, v69
	v_mul_f32_e32 v182, 0xbfb8aa3b, v70
	v_mul_f32_e32 v183, 0xbfb8aa3b, v71
	v_exp_f32_e32 v176, v176
	v_exp_f32_e32 v177, v177
	v_exp_f32_e32 v178, v178
	v_exp_f32_e32 v179, v179
	v_exp_f32_e32 v180, v180
	v_exp_f32_e32 v181, v181
	v_exp_f32_e32 v182, v182
	v_exp_f32_e32 v183, v183
	v_add_f32_e32 v176, 1.0, v176
	v_add_f32_e32 v177, 1.0, v177
	v_add_f32_e32 v178, 1.0, v178
	v_add_f32_e32 v179, 1.0, v179
	v_add_f32_e32 v180, 1.0, v180
	v_add_f32_e32 v181, 1.0, v181
	v_add_f32_e32 v182, 1.0, v182
	v_add_f32_e32 v183, 1.0, v183
	v_rcp_f32_e32 v176, v176
	v_rcp_f32_e32 v177, v177
	v_rcp_f32_e32 v178, v178
	v_rcp_f32_e32 v179, v179
	v_rcp_f32_e32 v180, v180
	v_rcp_f32_e32 v181, v181
	v_rcp_f32_e32 v182, v182
	v_rcp_f32_e32 v183, v183
	s_nop 0
	v_cvt_pk_bf16_f32 v176, v176, v177
	v_cvt_pk_bf16_f32 v177, v178, v179
	v_cvt_pk_bf16_f32 v178, v180, v181
	v_cvt_pk_bf16_f32 v179, v182, v183
	global_store_dwordx4 v235, v[176:179], s[2:3] offset:3072
	s_add_u32 s2, s2, 0x1000
	s_addc_u32 s3, s3, 0
	v_mul_f32_e32 v152, 0xbfb8aa3b, v40
	v_mul_f32_e32 v153, 0xbfb8aa3b, v41
	v_mul_f32_e32 v154, 0xbfb8aa3b, v42
	v_mul_f32_e32 v155, 0xbfb8aa3b, v43
	v_mul_f32_e32 v156, 0xbfb8aa3b, v48
	v_mul_f32_e32 v157, 0xbfb8aa3b, v49
	v_mul_f32_e32 v158, 0xbfb8aa3b, v50
	v_mul_f32_e32 v159, 0xbfb8aa3b, v51
	v_exp_f32_e32 v152, v152
	v_exp_f32_e32 v153, v153
	v_exp_f32_e32 v154, v154
	v_exp_f32_e32 v155, v155
	v_exp_f32_e32 v156, v156
	v_exp_f32_e32 v157, v157
	v_exp_f32_e32 v158, v158
	v_exp_f32_e32 v159, v159
	v_add_f32_e32 v152, 1.0, v152
	v_add_f32_e32 v153, 1.0, v153
	v_add_f32_e32 v154, 1.0, v154
	v_add_f32_e32 v155, 1.0, v155
	v_add_f32_e32 v156, 1.0, v156
	v_add_f32_e32 v157, 1.0, v157
	v_add_f32_e32 v158, 1.0, v158
	v_add_f32_e32 v159, 1.0, v159
	v_rcp_f32_e32 v152, v152
	v_rcp_f32_e32 v153, v153
	v_rcp_f32_e32 v154, v154
	v_rcp_f32_e32 v155, v155
	v_rcp_f32_e32 v156, v156
	v_rcp_f32_e32 v157, v157
	v_rcp_f32_e32 v158, v158
	v_rcp_f32_e32 v159, v159
	s_nop 0
	v_cvt_pk_bf16_f32 v152, v152, v153
	v_cvt_pk_bf16_f32 v153, v154, v155
	v_cvt_pk_bf16_f32 v154, v156, v157
	v_cvt_pk_bf16_f32 v155, v158, v159
	global_store_dwordx4 v235, v[152:155], s[2:3] offset:0
	v_mul_f32_e32 v160, 0xbfb8aa3b, v44
	v_mul_f32_e32 v161, 0xbfb8aa3b, v45
	v_mul_f32_e32 v162, 0xbfb8aa3b, v46
	v_mul_f32_e32 v163, 0xbfb8aa3b, v47
	v_mul_f32_e32 v164, 0xbfb8aa3b, v52
	v_mul_f32_e32 v165, 0xbfb8aa3b, v53
	v_mul_f32_e32 v166, 0xbfb8aa3b, v54
	v_mul_f32_e32 v167, 0xbfb8aa3b, v55
	v_exp_f32_e32 v160, v160
	v_exp_f32_e32 v161, v161
	v_exp_f32_e32 v162, v162
	v_exp_f32_e32 v163, v163
	v_exp_f32_e32 v164, v164
	v_exp_f32_e32 v165, v165
	v_exp_f32_e32 v166, v166
	v_exp_f32_e32 v167, v167
	v_add_f32_e32 v160, 1.0, v160
	v_add_f32_e32 v161, 1.0, v161
	v_add_f32_e32 v162, 1.0, v162
	v_add_f32_e32 v163, 1.0, v163
	v_add_f32_e32 v164, 1.0, v164
	v_add_f32_e32 v165, 1.0, v165
	v_add_f32_e32 v166, 1.0, v166
	v_add_f32_e32 v167, 1.0, v167
	v_rcp_f32_e32 v160, v160
	v_rcp_f32_e32 v161, v161
	v_rcp_f32_e32 v162, v162
	v_rcp_f32_e32 v163, v163
	v_rcp_f32_e32 v164, v164
	v_rcp_f32_e32 v165, v165
	v_rcp_f32_e32 v166, v166
	v_rcp_f32_e32 v167, v167
	s_nop 0
	v_cvt_pk_bf16_f32 v160, v160, v161
	v_cvt_pk_bf16_f32 v161, v162, v163
	v_cvt_pk_bf16_f32 v162, v164, v165
	v_cvt_pk_bf16_f32 v163, v166, v167
	global_store_dwordx4 v235, v[160:163], s[2:3] offset:1024
	v_mul_f32_e32 v168, 0xbfb8aa3b, v72
	v_mul_f32_e32 v169, 0xbfb8aa3b, v73
	v_mul_f32_e32 v170, 0xbfb8aa3b, v74
	v_mul_f32_e32 v171, 0xbfb8aa3b, v75
	v_mul_f32_e32 v172, 0xbfb8aa3b, v80
	v_mul_f32_e32 v173, 0xbfb8aa3b, v81
	v_mul_f32_e32 v174, 0xbfb8aa3b, v82
	v_mul_f32_e32 v175, 0xbfb8aa3b, v83
	v_exp_f32_e32 v168, v168
	v_exp_f32_e32 v169, v169
	v_exp_f32_e32 v170, v170
	v_exp_f32_e32 v171, v171
	v_exp_f32_e32 v172, v172
	v_exp_f32_e32 v173, v173
	v_exp_f32_e32 v174, v174
	v_exp_f32_e32 v175, v175
	v_add_f32_e32 v168, 1.0, v168
	v_add_f32_e32 v169, 1.0, v169
	v_add_f32_e32 v170, 1.0, v170
	v_add_f32_e32 v171, 1.0, v171
	v_add_f32_e32 v172, 1.0, v172
	v_add_f32_e32 v173, 1.0, v173
	v_add_f32_e32 v174, 1.0, v174
	v_add_f32_e32 v175, 1.0, v175
	v_rcp_f32_e32 v168, v168
	v_rcp_f32_e32 v169, v169
	v_rcp_f32_e32 v170, v170
	v_rcp_f32_e32 v171, v171
	v_rcp_f32_e32 v172, v172
	v_rcp_f32_e32 v173, v173
	v_rcp_f32_e32 v174, v174
	v_rcp_f32_e32 v175, v175
	s_nop 0
	v_cvt_pk_bf16_f32 v168, v168, v169
	v_cvt_pk_bf16_f32 v169, v170, v171
	v_cvt_pk_bf16_f32 v170, v172, v173
	v_cvt_pk_bf16_f32 v171, v174, v175
	global_store_dwordx4 v235, v[168:171], s[2:3] offset:2048
	v_mul_f32_e32 v176, 0xbfb8aa3b, v76
	v_mul_f32_e32 v177, 0xbfb8aa3b, v77
	v_mul_f32_e32 v178, 0xbfb8aa3b, v78
	v_mul_f32_e32 v179, 0xbfb8aa3b, v79
	v_mul_f32_e32 v180, 0xbfb8aa3b, v84
	v_mul_f32_e32 v181, 0xbfb8aa3b, v85
	v_mul_f32_e32 v182, 0xbfb8aa3b, v86
	v_mul_f32_e32 v183, 0xbfb8aa3b, v87
	v_exp_f32_e32 v176, v176
	v_exp_f32_e32 v177, v177
	v_exp_f32_e32 v178, v178
	v_exp_f32_e32 v179, v179
	v_exp_f32_e32 v180, v180
	v_exp_f32_e32 v181, v181
	v_exp_f32_e32 v182, v182
	v_exp_f32_e32 v183, v183
	v_add_f32_e32 v176, 1.0, v176
	v_add_f32_e32 v177, 1.0, v177
	v_add_f32_e32 v178, 1.0, v178
	v_add_f32_e32 v179, 1.0, v179
	v_add_f32_e32 v180, 1.0, v180
	v_add_f32_e32 v181, 1.0, v181
	v_add_f32_e32 v182, 1.0, v182
	v_add_f32_e32 v183, 1.0, v183
	v_rcp_f32_e32 v176, v176
	v_rcp_f32_e32 v177, v177
	v_rcp_f32_e32 v178, v178
	v_rcp_f32_e32 v179, v179
	v_rcp_f32_e32 v180, v180
	v_rcp_f32_e32 v181, v181
	v_rcp_f32_e32 v182, v182
	v_rcp_f32_e32 v183, v183
	s_nop 0
	v_cvt_pk_bf16_f32 v176, v176, v177
; DI unsigned pk2(float lo, float hi) { const f32x2 v = {lo, hi}; return __builtin_bit_cast(unsigned, __builtin_convertvector(v, bf2_t)); }
; DI void gemm_ple(const Params& p, int bid, int nb, char* smem, const int tid) {
;     ...
; #pragma unroll
;             for (int i = 0; i < 4; ++i)
; #pragma unroll
;                 for (int j = 0; j < 4; ++j) {
;                     float g[4];
; #pragma unroll
;                     for (int e = 0; e < 4; ++e) g[e] = __builtin_amdgcn_rcpf(1.0f + __builtin_amdgcn_exp2f(-LOG2E * gate[i][j][e]));
;                     gpk[i][j].x = pk2(g[0], g[1]); gpk[i][j].y = pk2(g[2], g[3]);
;                 }
	v_cvt_pk_bf16_f32 v177, v178, v179
	v_cvt_pk_bf16_f32 v178, v180, v181
	v_cvt_pk_bf16_f32 v179, v182, v183
	global_store_dwordx4 v235, v[176:179], s[2:3] offset:3072
	s_add_u32 s2, s2, 0x1000
	s_addc_u32 s3, s3, 0
	v_mul_f32_e32 v152, 0xbfb8aa3b, v88
	v_mul_f32_e32 v153, 0xbfb8aa3b, v89
	v_mul_f32_e32 v154, 0xbfb8aa3b, v90
	v_mul_f32_e32 v155, 0xbfb8aa3b, v91
	v_mul_f32_e32 v156, 0xbfb8aa3b, v96
	v_mul_f32_e32 v157, 0xbfb8aa3b, v97
	v_mul_f32_e32 v158, 0xbfb8aa3b, v98
	v_mul_f32_e32 v159, 0xbfb8aa3b, v99
	v_exp_f32_e32 v152, v152
	v_exp_f32_e32 v153, v153
	v_exp_f32_e32 v154, v154
	v_exp_f32_e32 v155, v155
	v_exp_f32_e32 v156, v156
	v_exp_f32_e32 v157, v157
	v_exp_f32_e32 v158, v158
	v_exp_f32_e32 v159, v159
	v_add_f32_e32 v152, 1.0, v152
	v_add_f32_e32 v153, 1.0, v153
	v_add_f32_e32 v154, 1.0, v154
	v_add_f32_e32 v155, 1.0, v155
	v_add_f32_e32 v156, 1.0, v156
	v_add_f32_e32 v157, 1.0, v157
	v_add_f32_e32 v158, 1.0, v158
	v_add_f32_e32 v159, 1.0, v159
	v_rcp_f32_e32 v152, v152
	v_rcp_f32_e32 v153, v153
	v_rcp_f32_e32 v154, v154
	v_rcp_f32_e32 v155, v155
	v_rcp_f32_e32 v156, v156
	v_rcp_f32_e32 v157, v157
	v_rcp_f32_e32 v158, v158
	v_rcp_f32_e32 v159, v159
	s_nop 0
	v_cvt_pk_bf16_f32 v152, v152, v153
	v_cvt_pk_bf16_f32 v153, v154, v155
	v_cvt_pk_bf16_f32 v154, v156, v157
	v_cvt_pk_bf16_f32 v155, v158, v159
	global_store_dwordx4 v235, v[152:155], s[2:3] offset:0
	v_mul_f32_e32 v160, 0xbfb8aa3b, v92
	v_mul_f32_e32 v161, 0xbfb8aa3b, v93
	v_mul_f32_e32 v162, 0xbfb8aa3b, v94
	v_mul_f32_e32 v163, 0xbfb8aa3b, v95
	v_mul_f32_e32 v164, 0xbfb8aa3b, v100
	v_mul_f32_e32 v165, 0xbfb8aa3b, v101
	v_mul_f32_e32 v166, 0xbfb8aa3b, v102
	v_mul_f32_e32 v167, 0xbfb8aa3b, v103
	v_exp_f32_e32 v160, v160
	v_exp_f32_e32 v161, v161
	v_exp_f32_e32 v162, v162
	v_exp_f32_e32 v163, v163
	v_exp_f32_e32 v164, v164
	v_exp_f32_e32 v165, v165
	v_exp_f32_e32 v166, v166
	v_exp_f32_e32 v167, v167
	v_add_f32_e32 v160, 1.0, v160
	v_add_f32_e32 v161, 1.0, v161
	v_add_f32_e32 v162, 1.0, v162
	v_add_f32_e32 v163, 1.0, v163
	v_add_f32_e32 v164, 1.0, v164
	v_add_f32_e32 v165, 1.0, v165
	v_add_f32_e32 v166, 1.0, v166
	v_add_f32_e32 v167, 1.0, v167
	v_rcp_f32_e32 v160, v160
	v_rcp_f32_e32 v161, v161
	v_rcp_f32_e32 v162, v162
	v_rcp_f32_e32 v163, v163
	v_rcp_f32_e32 v164, v164
	v_rcp_f32_e32 v165, v165
	v_rcp_f32_e32 v166, v166
	v_rcp_f32_e32 v167, v167
	s_nop 0
	v_cvt_pk_bf16_f32 v160, v160, v161
	v_cvt_pk_bf16_f32 v161, v162, v163
	v_cvt_pk_bf16_f32 v162, v164, v165
	v_cvt_pk_bf16_f32 v163, v166, v167
	global_store_dwordx4 v235, v[160:163], s[2:3] offset:1024
	v_mul_f32_e32 v168, 0xbfb8aa3b, v120
	v_mul_f32_e32 v169, 0xbfb8aa3b, v121
	v_mul_f32_e32 v170, 0xbfb8aa3b, v122
	v_mul_f32_e32 v171, 0xbfb8aa3b, v123
	v_mul_f32_e32 v172, 0xbfb8aa3b, v128
	v_mul_f32_e32 v173, 0xbfb8aa3b, v129
	v_mul_f32_e32 v174, 0xbfb8aa3b, v130
	v_mul_f32_e32 v175, 0xbfb8aa3b, v131
	v_exp_f32_e32 v168, v168
	v_exp_f32_e32 v169, v169
	v_exp_f32_e32 v170, v170
	v_exp_f32_e32 v171, v171
	v_exp_f32_e32 v172, v172
	v_exp_f32_e32 v173, v173
	v_exp_f32_e32 v174, v174
	v_exp_f32_e32 v175, v175
	v_add_f32_e32 v168, 1.0, v168
	v_add_f32_e32 v169, 1.0, v169
	v_add_f32_e32 v170, 1.0, v170
	v_add_f32_e32 v171, 1.0, v171
	v_add_f32_e32 v172, 1.0, v172
	v_add_f32_e32 v173, 1.0, v173
	v_add_f32_e32 v174, 1.0, v174
	v_add_f32_e32 v175, 1.0, v175
	v_rcp_f32_e32 v168, v168
	v_rcp_f32_e32 v169, v169
	v_rcp_f32_e32 v170, v170
	v_rcp_f32_e32 v171, v171
	v_rcp_f32_e32 v172, v172
	v_rcp_f32_e32 v173, v173
	v_rcp_f32_e32 v174, v174
	v_rcp_f32_e32 v175, v175
	s_nop 0
	v_cvt_pk_bf16_f32 v168, v168, v169
	v_cvt_pk_bf16_f32 v169, v170, v171
	v_cvt_pk_bf16_f32 v170, v172, v173
	v_cvt_pk_bf16_f32 v171, v174, v175
	global_store_dwordx4 v235, v[168:171], s[2:3] offset:2048
	v_mul_f32_e32 v176, 0xbfb8aa3b, v124
	v_mul_f32_e32 v177, 0xbfb8aa3b, v125
	v_mul_f32_e32 v178, 0xbfb8aa3b, v126
	v_mul_f32_e32 v179, 0xbfb8aa3b, v127
	v_mul_f32_e32 v180, 0xbfb8aa3b, v132
	v_mul_f32_e32 v181, 0xbfb8aa3b, v133
	v_mul_f32_e32 v182, 0xbfb8aa3b, v134
	v_mul_f32_e32 v183, 0xbfb8aa3b, v135
	v_exp_f32_e32 v176, v176
	v_exp_f32_e32 v177, v177
	v_exp_f32_e32 v178, v178
	v_exp_f32_e32 v179, v179
	v_exp_f32_e32 v180, v180
	v_exp_f32_e32 v181, v181
	v_exp_f32_e32 v182, v182
	v_exp_f32_e32 v183, v183
	v_add_f32_e32 v176, 1.0, v176
	v_add_f32_e32 v177, 1.0, v177
	v_add_f32_e32 v178, 1.0, v178
	v_add_f32_e32 v179, 1.0, v179
	v_add_f32_e32 v180, 1.0, v180
	v_add_f32_e32 v181, 1.0, v181
	v_add_f32_e32 v182, 1.0, v182
	v_add_f32_e32 v183, 1.0, v183
	v_rcp_f32_e32 v176, v176
	v_rcp_f32_e32 v177, v177
	v_rcp_f32_e32 v178, v178
	v_rcp_f32_e32 v179, v179
	v_rcp_f32_e32 v180, v180
	v_rcp_f32_e32 v181, v181
	v_rcp_f32_e32 v182, v182
	v_rcp_f32_e32 v183, v183
	s_nop 0
	v_cvt_pk_bf16_f32 v176, v176, v177
	v_cvt_pk_bf16_f32 v177, v178, v179
	v_cvt_pk_bf16_f32 v178, v180, v181
	v_cvt_pk_bf16_f32 v179, v182, v183
	global_store_dwordx4 v235, v[176:179], s[2:3] offset:3072
	s_add_u32 s2, s2, 0x1000
	s_addc_u32 s3, s3, 0
	v_mul_f32_e32 v152, 0xbfb8aa3b, v104
	v_mul_f32_e32 v153, 0xbfb8aa3b, v105
	v_mul_f32_e32 v154, 0xbfb8aa3b, v106
	v_mul_f32_e32 v155, 0xbfb8aa3b, v107
	v_mul_f32_e32 v156, 0xbfb8aa3b, v112
	v_mul_f32_e32 v157, 0xbfb8aa3b, v113
	v_mul_f32_e32 v158, 0xbfb8aa3b, v114
	v_mul_f32_e32 v159, 0xbfb8aa3b, v115
	v_exp_f32_e32 v152, v152
	v_exp_f32_e32 v153, v153
	v_exp_f32_e32 v154, v154
	v_exp_f32_e32 v155, v155
	v_exp_f32_e32 v156, v156
	v_exp_f32_e32 v157, v157
	v_exp_f32_e32 v158, v158
	v_exp_f32_e32 v159, v159
	v_add_f32_e32 v152, 1.0, v152
	v_add_f32_e32 v153, 1.0, v153
	v_add_f32_e32 v154, 1.0, v154
	v_add_f32_e32 v155, 1.0, v155
	v_add_f32_e32 v156, 1.0, v156
; DI unsigned pk2(float lo, float hi) { const f32x2 v = {lo, hi}; return __builtin_bit_cast(unsigned, __builtin_convertvector(v, bf2_t)); }
; #define BAR() { __builtin_amdgcn_sched_barrier(0); __builtin_amdgcn_s_barrier(); asm volatile("" ::: "memory"); __builtin_amdgcn_sched_barrier(0); }
; DI void gemm_stream2(const bf16_t* __restrict__ A, int lda, const bf16_t* __restrict__ Bt, int ldb, int K, int m0, int n0, ...
;     ...
;     int st = rg.st;
;     if (!rg.primed) {
;         const int s1p = st == 2 ? 0 : st + 1;
;         BAR();
;         STAGE(st, 0);
;         STAGE(s1p, 1);
;         asm volatile("s_waitcnt vmcnt(6)" ::: "memory");
;         BAR();
;     }
;     if (grp == 1) BAR();
; DI void gemm_ple(const Params& p, int bid, int nb, char* smem, const int tid) {
;     ...
; #pragma unroll
;             for (int i = 0; i < 4; ++i)
; #pragma unroll
;                 for (int j = 0; j < 4; ++j) {
;                     float g[4];
; #pragma unroll
;                     for (int e = 0; e < 4; ++e) g[e] = __builtin_amdgcn_rcpf(1.0f + __builtin_amdgcn_exp2f(-LOG2E * gate[i][j][e]));
;                     gpk[i][j].x = pk2(g[0], g[1]); gpk[i][j].y = pk2(g[2], g[3]);
;                 }
	v_add_f32_e32 v157, 1.0, v157
	v_add_f32_e32 v158, 1.0, v158
	v_add_f32_e32 v159, 1.0, v159
	v_rcp_f32_e32 v152, v152
	v_rcp_f32_e32 v153, v153
	v_rcp_f32_e32 v154, v154
	v_rcp_f32_e32 v155, v155
	v_rcp_f32_e32 v156, v156
	v_rcp_f32_e32 v157, v157
	v_rcp_f32_e32 v158, v158
	v_rcp_f32_e32 v159, v159
	s_nop 0
	v_cvt_pk_bf16_f32 v152, v152, v153
	v_cvt_pk_bf16_f32 v153, v154, v155
	v_cvt_pk_bf16_f32 v154, v156, v157
	v_cvt_pk_bf16_f32 v155, v158, v159
	global_store_dwordx4 v235, v[152:155], s[2:3] offset:0
	v_mul_f32_e32 v160, 0xbfb8aa3b, v108
	v_mul_f32_e32 v161, 0xbfb8aa3b, v109
	v_mul_f32_e32 v162, 0xbfb8aa3b, v110
	v_mul_f32_e32 v163, 0xbfb8aa3b, v111
	v_mul_f32_e32 v164, 0xbfb8aa3b, v116
	v_mul_f32_e32 v165, 0xbfb8aa3b, v117
	v_mul_f32_e32 v166, 0xbfb8aa3b, v118
	v_mul_f32_e32 v167, 0xbfb8aa3b, v119
	v_exp_f32_e32 v160, v160
	v_exp_f32_e32 v161, v161
	v_exp_f32_e32 v162, v162
	v_exp_f32_e32 v163, v163
	v_exp_f32_e32 v164, v164
	v_exp_f32_e32 v165, v165
	v_exp_f32_e32 v166, v166
	v_exp_f32_e32 v167, v167
	v_add_f32_e32 v160, 1.0, v160
	v_add_f32_e32 v161, 1.0, v161
	v_add_f32_e32 v162, 1.0, v162
	v_add_f32_e32 v163, 1.0, v163
	v_add_f32_e32 v164, 1.0, v164
	v_add_f32_e32 v165, 1.0, v165
	v_add_f32_e32 v166, 1.0, v166
	v_add_f32_e32 v167, 1.0, v167
	v_rcp_f32_e32 v160, v160
	v_rcp_f32_e32 v161, v161
	v_rcp_f32_e32 v162, v162
	v_rcp_f32_e32 v163, v163
	v_rcp_f32_e32 v164, v164
	v_rcp_f32_e32 v165, v165
	v_rcp_f32_e32 v166, v166
	v_rcp_f32_e32 v167, v167
	s_nop 0
	v_cvt_pk_bf16_f32 v160, v160, v161
	v_cvt_pk_bf16_f32 v161, v162, v163
	v_cvt_pk_bf16_f32 v162, v164, v165
	v_cvt_pk_bf16_f32 v163, v166, v167
	global_store_dwordx4 v235, v[160:163], s[2:3] offset:1024
	v_mul_f32_e32 v168, 0xbfb8aa3b, v136
	v_mul_f32_e32 v169, 0xbfb8aa3b, v137
	v_mul_f32_e32 v170, 0xbfb8aa3b, v138
	v_mul_f32_e32 v171, 0xbfb8aa3b, v139
	v_mul_f32_e32 v172, 0xbfb8aa3b, v144
	v_mul_f32_e32 v173, 0xbfb8aa3b, v145
	v_mul_f32_e32 v174, 0xbfb8aa3b, v146
	v_mul_f32_e32 v175, 0xbfb8aa3b, v147
	v_exp_f32_e32 v168, v168
	v_exp_f32_e32 v169, v169
	v_exp_f32_e32 v170, v170
	v_exp_f32_e32 v171, v171
	v_exp_f32_e32 v172, v172
	v_exp_f32_e32 v173, v173
	v_exp_f32_e32 v174, v174
	v_exp_f32_e32 v175, v175
	v_add_f32_e32 v168, 1.0, v168
	v_add_f32_e32 v169, 1.0, v169
	v_add_f32_e32 v170, 1.0, v170
	v_add_f32_e32 v171, 1.0, v171
	v_add_f32_e32 v172, 1.0, v172
	v_add_f32_e32 v173, 1.0, v173
	v_add_f32_e32 v174, 1.0, v174
	v_add_f32_e32 v175, 1.0, v175
	v_rcp_f32_e32 v168, v168
	v_rcp_f32_e32 v169, v169
	v_rcp_f32_e32 v170, v170
	v_rcp_f32_e32 v171, v171
	v_rcp_f32_e32 v172, v172
	v_rcp_f32_e32 v173, v173
	v_rcp_f32_e32 v174, v174
	v_rcp_f32_e32 v175, v175
	s_nop 0
	v_cvt_pk_bf16_f32 v168, v168, v169
	v_cvt_pk_bf16_f32 v169, v170, v171
	v_cvt_pk_bf16_f32 v170, v172, v173
	v_cvt_pk_bf16_f32 v171, v174, v175
	global_store_dwordx4 v235, v[168:171], s[2:3] offset:2048
	v_mul_f32_e32 v176, 0xbfb8aa3b, v140
	v_mul_f32_e32 v177, 0xbfb8aa3b, v141
	v_mul_f32_e32 v178, 0xbfb8aa3b, v142
	v_mul_f32_e32 v179, 0xbfb8aa3b, v143
	v_mul_f32_e32 v180, 0xbfb8aa3b, v148
	v_mul_f32_e32 v181, 0xbfb8aa3b, v149
	v_mul_f32_e32 v182, 0xbfb8aa3b, v150
	v_mul_f32_e32 v183, 0xbfb8aa3b, v151
	v_exp_f32_e32 v176, v176
	v_exp_f32_e32 v177, v177
	v_exp_f32_e32 v178, v178
	v_exp_f32_e32 v179, v179
	v_exp_f32_e32 v180, v180
	v_exp_f32_e32 v181, v181
	v_exp_f32_e32 v182, v182
	v_exp_f32_e32 v183, v183
	v_add_f32_e32 v176, 1.0, v176
	v_add_f32_e32 v177, 1.0, v177
	v_add_f32_e32 v178, 1.0, v178
	v_add_f32_e32 v179, 1.0, v179
	v_add_f32_e32 v180, 1.0, v180
	v_add_f32_e32 v181, 1.0, v181
	v_add_f32_e32 v182, 1.0, v182
	v_add_f32_e32 v183, 1.0, v183
	v_rcp_f32_e32 v176, v176
	v_rcp_f32_e32 v177, v177
	v_rcp_f32_e32 v178, v178
	v_rcp_f32_e32 v179, v179
	v_rcp_f32_e32 v180, v180
	v_rcp_f32_e32 v181, v181
	v_rcp_f32_e32 v182, v182
	v_rcp_f32_e32 v183, v183
	s_nop 0
	v_cvt_pk_bf16_f32 v176, v176, v177
	v_cvt_pk_bf16_f32 v177, v178, v179
	v_cvt_pk_bf16_f32 v178, v180, v181
	v_cvt_pk_bf16_f32 v179, v182, v183
	global_store_dwordx4 v235, v[176:179], s[2:3] offset:3072
	s_waitcnt vmcnt(24)
	s_barrier
	s_cmp_eq_u32 s33, 0
	s_cbranch_scc1 .Lplm_plead
	s_barrier
; #define LAS __attribute__((address_space(3)))
; #define BAR() { __builtin_amdgcn_sched_barrier(0); __builtin_amdgcn_s_barrier(); asm volatile("" ::: "memory"); __builtin_amdgcn_sched_barrier(0); }
; DI void gemm_stream2(const bf16_t* __restrict__ A, int lda, const bf16_t* __restrict__ Bt, int ldb, int K, int m0, int n0, ...
;     ...
;     for (int kt = 0; kt < nk; ++kt) {
;         const bool pf = (kt + 2 < nk) || has_next, more = (kt + 1 < nk) || has_next;
;         const bf16_t* pa = (kt + 2 < nk) ? ga + (kt + 2) * 64 : gan + (kt + 2 - nk) * 64;
;         const bf16_t* pb = (kt + 2 < nk) ? gb + (kt + 2) * 64 : gbn + (kt + 2 - nk) * 64;
;         const int plda = (kt + 2 < nk) ? lda : ldan, pldb = (kt + 2 < nk) ? ldb : ldbn;
;         const int s2 = st >= 1 ? st - 1 : 2;
;         const LAS char* base = lds + st * 49152;
; #pragma unroll
;         for (int ks = 0; ks < 2; ++ks) {
;             const unsigned fo = ks ? fo1 : fo0;
;             bf16x8 af[4], bfr[4];
; #pragma unroll
;             for (int i = 0; i < 4; ++i) { af[i] = *(const LAS bf16x8*)(base + aoff + i * 2048 + fo); bfr[i] = *(const LAS bf16x8*)(base + boff + i * 2048 + fo); }
;             if (ks == 1 && more) { if (pf) asm volatile("s_waitcnt vmcnt(3)" ::: "memory"); else asm volatile("s_waitcnt vmcnt(0)" ::: "memory"); }
;             if (pf) { PIECE(s2, ks * 3 + 0); PIECE(s2, ks * 3 + 1); PIECE(s2, ks * 3 + 2); }
;             asm volatile("s_waitcnt lgkmcnt(0)" ::: "memory");
;             BAR();
;             __builtin_amdgcn_s_setprio(1);
; #pragma unroll
;             for (int mi = 0; mi < 4; ++mi)
; #pragma unroll
;                 for (int ni = 0; ni < 4; ++ni) acc[mi][ni] = __builtin_amdgcn_mfma_f32_16x16x32_bf16(bfr[ni], af[mi], acc[mi][ni], 0, 0, 0);
;             __builtin_amdgcn_s_setprio(0);
;             BAR();
;         }
; DI void gemm_ple(const Params& p, int bid, int nb, char* smem, const int tid) {
;     ...
;         f32x4 acc[4][4]; zero_acc(acc);
;         gemm_stream2(PB, 256, WP, 256, 256, m0, n0, have, XN, 1024, WG, 1024, tm2 * 256, tn2 * 128, smem, acc, tid, rg);
.Lplm_plead:
	v_mov_b64_e32 v[24:25], 0
	v_mov_b64_e32 v[26:27], 0
	v_mov_b64_e32 v[28:29], 0
	v_mov_b64_e32 v[30:31], 0
	v_mov_b64_e32 v[32:33], 0
	v_mov_b64_e32 v[34:35], 0
	v_mov_b64_e32 v[36:37], 0
	v_mov_b64_e32 v[38:39], 0
	v_mov_b64_e32 v[40:41], 0
	v_mov_b64_e32 v[42:43], 0
	v_mov_b64_e32 v[44:45], 0
	v_mov_b64_e32 v[46:47], 0
	v_mov_b64_e32 v[48:49], 0
	v_mov_b64_e32 v[50:51], 0
	v_mov_b64_e32 v[52:53], 0
	v_mov_b64_e32 v[54:55], 0
	v_mov_b64_e32 v[56:57], 0
	v_mov_b64_e32 v[58:59], 0
	v_mov_b64_e32 v[60:61], 0
	v_mov_b64_e32 v[62:63], 0
	v_mov_b64_e32 v[64:65], 0
	v_mov_b64_e32 v[66:67], 0
	v_mov_b64_e32 v[68:69], 0
	v_mov_b64_e32 v[70:71], 0
	v_mov_b64_e32 v[72:73], 0
	v_mov_b64_e32 v[74:75], 0
	v_mov_b64_e32 v[76:77], 0
	v_mov_b64_e32 v[78:79], 0
	v_mov_b64_e32 v[80:81], 0
	v_mov_b64_e32 v[82:83], 0
	v_mov_b64_e32 v[84:85], 0
	v_mov_b64_e32 v[86:87], 0
	v_mov_b64_e32 v[88:89], 0
	v_mov_b64_e32 v[90:91], 0
	v_mov_b64_e32 v[92:93], 0
	v_mov_b64_e32 v[94:95], 0
	v_mov_b64_e32 v[96:97], 0
	v_mov_b64_e32 v[98:99], 0
	v_mov_b64_e32 v[100:101], 0
	v_mov_b64_e32 v[102:103], 0
	v_mov_b64_e32 v[104:105], 0
	v_mov_b64_e32 v[106:107], 0
	v_mov_b64_e32 v[108:109], 0
	v_mov_b64_e32 v[110:111], 0
	v_mov_b64_e32 v[112:113], 0
	v_mov_b64_e32 v[114:115], 0
	v_mov_b64_e32 v[116:117], 0
	v_mov_b64_e32 v[118:119], 0
	v_mov_b64_e32 v[120:121], 0
	v_mov_b64_e32 v[122:123], 0
	v_mov_b64_e32 v[124:125], 0
	v_mov_b64_e32 v[126:127], 0
	v_mov_b64_e32 v[128:129], 0
	v_mov_b64_e32 v[130:131], 0
	v_mov_b64_e32 v[132:133], 0
	v_mov_b64_e32 v[134:135], 0
	v_mov_b64_e32 v[136:137], 0
	v_mov_b64_e32 v[138:139], 0
	v_mov_b64_e32 v[140:141], 0
	v_mov_b64_e32 v[142:143], 0
	v_mov_b64_e32 v[144:145], 0
	v_mov_b64_e32 v[146:147], 0
	v_mov_b64_e32 v[148:149], 0
	v_mov_b64_e32 v[150:151], 0
	s_mov_b32 s0, 1
	ds_read_b128 v[0:3], v188 offset:16
	ds_read_b128 v[4:7], v189 offset:16
	ds_read_b128 v[8:11], v188 offset:2064
	ds_read_b128 v[12:15], v189 offset:2064
	ds_read_b128 v[196:199], v188 offset:16400
	ds_read_b128 v[200:203], v189 offset:16400
	ds_read_b128 v[204:207], v188 offset:18448
	ds_read_b128 v[208:211], v189 offset:18448
	ds_read_b128 v[152:155], v186 offset:16
	ds_read_b128 v[156:159], v187 offset:16
	ds_read_b128 v[160:163], v186 offset:2064
	ds_read_b128 v[164:167], v187 offset:2064
	ds_read_b128 v[168:171], v186 offset:4112
	ds_read_b128 v[172:175], v187 offset:4112
	ds_read_b128 v[176:179], v186 offset:6160
	ds_read_b128 v[180:183], v187 offset:6160
	s_add_i32 m0, s39, 0xc000
	s_nop 0
	global_load_lds_dwordx4 v184, s[68:69]
	s_add_i32 m0, s39, 0xc400
	s_nop 0
	global_load_lds_dwordx4 v185, s[68:69]
	s_add_u32 s68, s68, 0x80
	s_addc_u32 s69, s69, 0
	s_waitcnt lgkmcnt(0)
	s_waitcnt vmcnt(8)
	s_barrier
	s_setprio 1
	v_mfma_f32_16x16x32_bf16 v[24:27], v[0:3], v[152:155], v[24:27]
	v_mfma_f32_16x16x32_bf16 v[28:31], v[8:11], v[152:155], v[28:31]
	v_mfma_f32_16x16x32_bf16 v[32:35], v[0:3], v[160:163], v[32:35]
	v_mfma_f32_16x16x32_bf16 v[36:39], v[8:11], v[160:163], v[36:39]
	v_mfma_f32_16x16x32_bf16 v[40:43], v[0:3], v[168:171], v[40:43]
	v_mfma_f32_16x16x32_bf16 v[44:47], v[8:11], v[168:171], v[44:47]
	v_mfma_f32_16x16x32_bf16 v[48:51], v[0:3], v[176:179], v[48:51]
	v_mfma_f32_16x16x32_bf16 v[52:55], v[8:11], v[176:179], v[52:55]
	v_mfma_f32_16x16x32_bf16 v[24:27], v[4:7], v[156:159], v[24:27]
	v_mfma_f32_16x16x32_bf16 v[28:31], v[12:15], v[156:159], v[28:31]
	v_mfma_f32_16x16x32_bf16 v[32:35], v[4:7], v[164:167], v[32:35]
	v_mfma_f32_16x16x32_bf16 v[36:39], v[12:15], v[164:167], v[36:39]
	v_mfma_f32_16x16x32_bf16 v[40:43], v[4:7], v[172:175], v[40:43]
	v_mfma_f32_16x16x32_bf16 v[44:47], v[12:15], v[172:175], v[44:47]
	v_mfma_f32_16x16x32_bf16 v[48:51], v[4:7], v[180:183], v[48:51]
	v_mfma_f32_16x16x32_bf16 v[52:55], v[12:15], v[180:183], v[52:55]
	v_mfma_f32_16x16x32_bf16 v[56:59], v[196:199], v[152:155], v[56:59]
	v_mfma_f32_16x16x32_bf16 v[60:63], v[204:207], v[152:155], v[60:63]
	v_mfma_f32_16x16x32_bf16 v[64:67], v[196:199], v[160:163], v[64:67]
	v_mfma_f32_16x16x32_bf16 v[68:71], v[204:207], v[160:163], v[68:71]
	v_mfma_f32_16x16x32_bf16 v[72:75], v[196:199], v[168:171], v[72:75]
	v_mfma_f32_16x16x32_bf16 v[76:79], v[204:207], v[168:171], v[76:79]
	v_mfma_f32_16x16x32_bf16 v[80:83], v[196:199], v[176:179], v[80:83]
	v_mfma_f32_16x16x32_bf16 v[84:87], v[204:207], v[176:179], v[84:87]
	v_mfma_f32_16x16x32_bf16 v[56:59], v[200:203], v[156:159], v[56:59]
	v_mfma_f32_16x16x32_bf16 v[60:63], v[208:211], v[156:159], v[60:63]
	v_mfma_f32_16x16x32_bf16 v[64:67], v[200:203], v[164:167], v[64:67]
	v_mfma_f32_16x16x32_bf16 v[68:71], v[208:211], v[164:167], v[68:71]
	v_mfma_f32_16x16x32_bf16 v[72:75], v[200:203], v[172:175], v[72:75]
	v_mfma_f32_16x16x32_bf16 v[76:79], v[208:211], v[172:175], v[76:79]
	v_mfma_f32_16x16x32_bf16 v[80:83], v[200:203], v[180:183], v[80:83]
	v_mfma_f32_16x16x32_bf16 v[84:87], v[208:211], v[180:183], v[84:87]
	s_setprio 0
	s_barrier
	ds_read_b128 v[152:155], v186 offset:16400
	ds_read_b128 v[156:159], v187 offset:16400
	ds_read_b128 v[160:163], v186 offset:18448
	ds_read_b128 v[164:167], v187 offset:18448
	ds_read_b128 v[168:171], v186 offset:20496
	ds_read_b128 v[172:175], v187 offset:20496
	ds_read_b128 v[176:179], v186 offset:22544
	ds_read_b128 v[180:183], v187 offset:22544
	s_cmp_lg_u32 s0, s54
	s_cbranch_scc1 .Lplm_nosw3
	s_mov_b64 s[66:67], s[74:75]
	s_mov_b64 s[70:71], s[80:81]
	s_mov_b64 s[72:73], s[82:83]

; #define LAS __attribute__((address_space(3)))
; #define BAR() { __builtin_amdgcn_sched_barrier(0); __builtin_amdgcn_s_barrier(); asm volatile("" ::: "memory"); __builtin_amdgcn_sched_barrier(0); }
; DI void gemm_stream2(const bf16_t* __restrict__ A, int lda, const bf16_t* __restrict__ Bt, int ldb, int K, int m0, int n0, ...
;     ...
;     for (int kt = 0; kt < nk; ++kt) {
;         const bool pf = (kt + 2 < nk) || has_next, more = (kt + 1 < nk) || has_next;
;         const bf16_t* pa = (kt + 2 < nk) ? ga + (kt + 2) * 64 : gan + (kt + 2 - nk) * 64;
;         const bf16_t* pb = (kt + 2 < nk) ? gb + (kt + 2) * 64 : gbn + (kt + 2 - nk) * 64;
;         const int plda = (kt + 2 < nk) ? lda : ldan, pldb = (kt + 2 < nk) ? ldb : ldbn;
;         const int s2 = st >= 1 ? st - 1 : 2;
;         const LAS char* base = lds + st * 49152;
; #pragma unroll
;         for (int ks = 0; ks < 2; ++ks) {
;             const unsigned fo = ks ? fo1 : fo0;
;             bf16x8 af[4], bfr[4];
; #pragma unroll
;             for (int i = 0; i < 4; ++i) { af[i] = *(const LAS bf16x8*)(base + aoff + i * 2048 + fo); bfr[i] = *(const LAS bf16x8*)(base + boff + i * 2048 + fo); }
;             if (ks == 1 && more) { if (pf) asm volatile("s_waitcnt vmcnt(3)" ::: "memory"); else asm volatile("s_waitcnt vmcnt(0)" ::: "memory"); }
;             if (pf) { PIECE(s2, ks * 3 + 0); PIECE(s2, ks * 3 + 1); PIECE(s2, ks * 3 + 2); }
;             asm volatile("s_waitcnt lgkmcnt(0)" ::: "memory");
;             BAR();
;             __builtin_amdgcn_s_setprio(1);
; #pragma unroll
;             for (int mi = 0; mi < 4; ++mi)
; #pragma unroll
;                 for (int ni = 0; ni < 4; ++ni) acc[mi][ni] = __builtin_amdgcn_mfma_f32_16x16x32_bf16(bfr[ni], af[mi], acc[mi][ni], 0, 0, 0);
;             __builtin_amdgcn_s_setprio(0);
;             BAR();
;         }
;         st = st == 2 ? 0 : st + 1;
;     }
.Lplm_nosw4:
	s_add_i32 m0, s39, 0x4000
	s_nop 0
	global_load_lds_dwordx4 v184, s[68:69]
	s_add_i32 m0, s39, 0x4400
	s_nop 0
	global_load_lds_dwordx4 v185, s[68:69]
	s_add_u32 s68, s68, 0x80
	s_addc_u32 s69, s69, 0
	s_waitcnt lgkmcnt(0)
	s_waitcnt vmcnt(8)
	s_barrier
	s_setprio 1
	v_mfma_f32_16x16x32_bf16 v[24:27], v[0:3], v[152:155], v[24:27]
	v_mfma_f32_16x16x32_bf16 v[28:31], v[8:11], v[152:155], v[28:31]
	v_mfma_f32_16x16x32_bf16 v[32:35], v[0:3], v[160:163], v[32:35]
	v_mfma_f32_16x16x32_bf16 v[36:39], v[8:11], v[160:163], v[36:39]
	v_mfma_f32_16x16x32_bf16 v[40:43], v[0:3], v[168:171], v[40:43]
	v_mfma_f32_16x16x32_bf16 v[44:47], v[8:11], v[168:171], v[44:47]
	v_mfma_f32_16x16x32_bf16 v[48:51], v[0:3], v[176:179], v[48:51]
	v_mfma_f32_16x16x32_bf16 v[52:55], v[8:11], v[176:179], v[52:55]
	v_mfma_f32_16x16x32_bf16 v[24:27], v[4:7], v[156:159], v[24:27]
	v_mfma_f32_16x16x32_bf16 v[28:31], v[12:15], v[156:159], v[28:31]
	v_mfma_f32_16x16x32_bf16 v[32:35], v[4:7], v[164:167], v[32:35]
	v_mfma_f32_16x16x32_bf16 v[36:39], v[12:15], v[164:167], v[36:39]
	v_mfma_f32_16x16x32_bf16 v[40:43], v[4:7], v[172:175], v[40:43]
	v_mfma_f32_16x16x32_bf16 v[44:47], v[12:15], v[172:175], v[44:47]
	v_mfma_f32_16x16x32_bf16 v[48:51], v[4:7], v[180:183], v[48:51]
	v_mfma_f32_16x16x32_bf16 v[52:55], v[12:15], v[180:183], v[52:55]
	v_mfma_f32_16x16x32_bf16 v[56:59], v[196:199], v[152:155], v[56:59]
	v_mfma_f32_16x16x32_bf16 v[60:63], v[204:207], v[152:155], v[60:63]
	v_mfma_f32_16x16x32_bf16 v[64:67], v[196:199], v[160:163], v[64:67]
	v_mfma_f32_16x16x32_bf16 v[68:71], v[204:207], v[160:163], v[68:71]
	v_mfma_f32_16x16x32_bf16 v[72:75], v[196:199], v[168:171], v[72:75]
	v_mfma_f32_16x16x32_bf16 v[76:79], v[204:207], v[168:171], v[76:79]
	v_mfma_f32_16x16x32_bf16 v[80:83], v[196:199], v[176:179], v[80:83]
	v_mfma_f32_16x16x32_bf16 v[84:87], v[204:207], v[176:179], v[84:87]
	v_mfma_f32_16x16x32_bf16 v[56:59], v[200:203], v[156:159], v[56:59]
	v_mfma_f32_16x16x32_bf16 v[60:63], v[208:211], v[156:159], v[60:63]
	v_mfma_f32_16x16x32_bf16 v[64:67], v[200:203], v[164:167], v[64:67]
	v_mfma_f32_16x16x32_bf16 v[68:71], v[208:211], v[164:167], v[68:71]
	v_mfma_f32_16x16x32_bf16 v[72:75], v[200:203], v[172:175], v[72:75]
	v_mfma_f32_16x16x32_bf16 v[76:79], v[208:211], v[172:175], v[76:79]
	v_mfma_f32_16x16x32_bf16 v[80:83], v[200:203], v[180:183], v[80:83]
	v_mfma_f32_16x16x32_bf16 v[84:87], v[208:211], v[180:183], v[84:87]
	s_setprio 0
	s_barrier
	ds_read_b128 v[152:155], v186 offset:49168
	ds_read_b128 v[156:159], v187 offset:49168
	ds_read_b128 v[160:163], v186 offset:51216
	ds_read_b128 v[164:167], v187 offset:51216
	ds_read_b128 v[168:171], v186 offset:53264
	ds_read_b128 v[172:175], v187 offset:53264
	ds_read_b128 v[176:179], v186 offset:55312
	ds_read_b128 v[180:183], v187 offset:55312
	s_add_i32 m0, s39, 0x18000
	s_nop 0
	global_load_lds_dwordx4 v184, s[70:71]
	s_add_i32 m0, s39, 0x18400
	s_nop 0
	global_load_lds_dwordx4 v185, s[70:71]
	s_add_u32 s70, s70, 0x80
	s_addc_u32 s71, s71, 0
	s_add_i32 m0, s39, 0x8000
	s_nop 0
	global_load_lds_dwordx4 v184, s[66:67]
	s_add_i32 m0, s39, 0x8400
	s_nop 0
	global_load_lds_dwordx4 v185, s[66:67]
	s_add_u32 s66, s66, 0x80
	s_addc_u32 s67, s67, 0
	s_add_i32 m0, s39, 0x1c000
	s_nop 0
	global_load_lds_dwordx4 v184, s[72:73]
	s_add_i32 m0, s39, 0x1c400
	s_nop 0
	global_load_lds_dwordx4 v185, s[72:73]
	s_add_u32 s72, s72, 0x80
	s_addc_u32 s73, s73, 0
	s_waitcnt lgkmcnt(0)
	s_waitcnt vmcnt(8)
	s_barrier
	s_setprio 1
	v_mfma_f32_16x16x32_bf16 v[88:91], v[0:3], v[152:155], v[88:91]
	v_mfma_f32_16x16x32_bf16 v[92:95], v[8:11], v[152:155], v[92:95]
	v_mfma_f32_16x16x32_bf16 v[96:99], v[0:3], v[160:163], v[96:99]
	v_mfma_f32_16x16x32_bf16 v[100:103], v[8:11], v[160:163], v[100:103]
	v_mfma_f32_16x16x32_bf16 v[104:107], v[0:3], v[168:171], v[104:107]
	v_mfma_f32_16x16x32_bf16 v[108:111], v[8:11], v[168:171], v[108:111]
	v_mfma_f32_16x16x32_bf16 v[112:115], v[0:3], v[176:179], v[112:115]
	v_mfma_f32_16x16x32_bf16 v[116:119], v[8:11], v[176:179], v[116:119]
	v_mfma_f32_16x16x32_bf16 v[88:91], v[4:7], v[156:159], v[88:91]
	v_mfma_f32_16x16x32_bf16 v[92:95], v[12:15], v[156:159], v[92:95]
	v_mfma_f32_16x16x32_bf16 v[96:99], v[4:7], v[164:167], v[96:99]
	v_mfma_f32_16x16x32_bf16 v[100:103], v[12:15], v[164:167], v[100:103]
	v_mfma_f32_16x16x32_bf16 v[104:107], v[4:7], v[172:175], v[104:107]
	v_mfma_f32_16x16x32_bf16 v[108:111], v[12:15], v[172:175], v[108:111]
	v_mfma_f32_16x16x32_bf16 v[112:115], v[4:7], v[180:183], v[112:115]
	v_mfma_f32_16x16x32_bf16 v[116:119], v[12:15], v[180:183], v[116:119]
	v_mfma_f32_16x16x32_bf16 v[120:123], v[196:199], v[152:155], v[120:123]
	v_mfma_f32_16x16x32_bf16 v[124:127], v[204:207], v[152:155], v[124:127]
	v_mfma_f32_16x16x32_bf16 v[128:131], v[196:199], v[160:163], v[128:131]
	v_mfma_f32_16x16x32_bf16 v[132:135], v[204:207], v[160:163], v[132:135]
	v_mfma_f32_16x16x32_bf16 v[136:139], v[196:199], v[168:171], v[136:139]
	v_mfma_f32_16x16x32_bf16 v[140:143], v[204:207], v[168:171], v[140:143]
	v_mfma_f32_16x16x32_bf16 v[144:147], v[196:199], v[176:179], v[144:147]
	v_mfma_f32_16x16x32_bf16 v[148:151], v[204:207], v[176:179], v[148:151]
	v_mfma_f32_16x16x32_bf16 v[120:123], v[200:203], v[156:159], v[120:123]
	v_mfma_f32_16x16x32_bf16 v[124:127], v[208:211], v[156:159], v[124:127]
	v_mfma_f32_16x16x32_bf16 v[128:131], v[200:203], v[164:167], v[128:131]
	v_mfma_f32_16x16x32_bf16 v[132:135], v[208:211], v[164:167], v[132:135]
	v_mfma_f32_16x16x32_bf16 v[136:139], v[200:203], v[172:175], v[136:139]
	v_mfma_f32_16x16x32_bf16 v[140:143], v[208:211], v[172:175], v[140:143]
	v_mfma_f32_16x16x32_bf16 v[144:147], v[200:203], v[180:183], v[144:147]
	v_mfma_f32_16x16x32_bf16 v[148:151], v[208:211], v[180:183], v[148:151]
	s_setprio 0
	s_barrier
; #define LAS __attribute__((address_space(3)))
; #define BAR() { __builtin_amdgcn_sched_barrier(0); __builtin_amdgcn_s_barrier(); asm volatile("" ::: "memory"); __builtin_amdgcn_sched_barrier(0); }
; DI void gemm_stream2(const bf16_t* __restrict__ A, int lda, const bf16_t* __restrict__ Bt, int ldb, int K, int m0, int n0, ...
;     ...
;     for (int kt = 0; kt < nk; ++kt) {
;         const bool pf = (kt + 2 < nk) || has_next, more = (kt + 1 < nk) || has_next;
;         const bf16_t* pa = (kt + 2 < nk) ? ga + (kt + 2) * 64 : gan + (kt + 2 - nk) * 64;
;         const bf16_t* pb = (kt + 2 < nk) ? gb + (kt + 2) * 64 : gbn + (kt + 2 - nk) * 64;
;         const int plda = (kt + 2 < nk) ? lda : ldan, pldb = (kt + 2 < nk) ? ldb : ldbn;
;         const int s2 = st >= 1 ? st - 1 : 2;
;         const LAS char* base = lds + st * 49152;
; #pragma unroll
;         for (int ks = 0; ks < 2; ++ks) {
;             const unsigned fo = ks ? fo1 : fo0;
;             bf16x8 af[4], bfr[4];
; #pragma unroll
;             for (int i = 0; i < 4; ++i) { af[i] = *(const LAS bf16x8*)(base + aoff + i * 2048 + fo); bfr[i] = *(const LAS bf16x8*)(base + boff + i * 2048 + fo); }
;             if (ks == 1 && more) { if (pf) asm volatile("s_waitcnt vmcnt(3)" ::: "memory"); else asm volatile("s_waitcnt vmcnt(0)" ::: "memory"); }
;             if (pf) { PIECE(s2, ks * 3 + 0); PIECE(s2, ks * 3 + 1); PIECE(s2, ks * 3 + 2); }
;             asm volatile("s_waitcnt lgkmcnt(0)" ::: "memory");
;             BAR();
;             __builtin_amdgcn_s_setprio(1);
; #pragma unroll
;             for (int mi = 0; mi < 4; ++mi)
; #pragma unroll
;                 for (int ni = 0; ni < 4; ++ni) acc[mi][ni] = __builtin_amdgcn_mfma_f32_16x16x32_bf16(bfr[ni], af[mi], acc[mi][ni], 0, 0, 0);
;             __builtin_amdgcn_s_setprio(0);
;             BAR();
;         }
;         st = st == 2 ? 0 : st + 1;
;     }
	ds_read_b128 v[0:3], v188 offset:16
	ds_read_b128 v[4:7], v189 offset:16
	ds_read_b128 v[8:11], v188 offset:2064
	ds_read_b128 v[12:15], v189 offset:2064
	ds_read_b128 v[196:199], v188 offset:16400
	ds_read_b128 v[200:203], v189 offset:16400
	ds_read_b128 v[204:207], v188 offset:18448
	ds_read_b128 v[208:211], v189 offset:18448
	ds_read_b128 v[152:155], v186 offset:16
	ds_read_b128 v[156:159], v187 offset:16
	ds_read_b128 v[160:163], v186 offset:2064
	ds_read_b128 v[164:167], v187 offset:2064
	ds_read_b128 v[168:171], v186 offset:4112
	ds_read_b128 v[172:175], v187 offset:4112
	ds_read_b128 v[176:179], v186 offset:6160
	ds_read_b128 v[180:183], v187 offset:6160
	s_add_i32 m0, s39, 0xc000
	s_nop 0
	global_load_lds_dwordx4 v184, s[68:69]
	s_add_i32 m0, s39, 0xc400
	s_nop 0
	global_load_lds_dwordx4 v185, s[68:69]
	s_add_u32 s68, s68, 0x80
	s_addc_u32 s69, s69, 0
	s_waitcnt lgkmcnt(0)
	s_waitcnt vmcnt(8)
	s_barrier
	s_setprio 1
	v_mfma_f32_16x16x32_bf16 v[24:27], v[0:3], v[152:155], v[24:27]
	v_mfma_f32_16x16x32_bf16 v[28:31], v[8:11], v[152:155], v[28:31]
	v_mfma_f32_16x16x32_bf16 v[32:35], v[0:3], v[160:163], v[32:35]
	v_mfma_f32_16x16x32_bf16 v[36:39], v[8:11], v[160:163], v[36:39]
	v_mfma_f32_16x16x32_bf16 v[40:43], v[0:3], v[168:171], v[40:43]
	v_mfma_f32_16x16x32_bf16 v[44:47], v[8:11], v[168:171], v[44:47]
	v_mfma_f32_16x16x32_bf16 v[48:51], v[0:3], v[176:179], v[48:51]
	v_mfma_f32_16x16x32_bf16 v[52:55], v[8:11], v[176:179], v[52:55]
	v_mfma_f32_16x16x32_bf16 v[24:27], v[4:7], v[156:159], v[24:27]
	v_mfma_f32_16x16x32_bf16 v[28:31], v[12:15], v[156:159], v[28:31]
	v_mfma_f32_16x16x32_bf16 v[32:35], v[4:7], v[164:167], v[32:35]
	v_mfma_f32_16x16x32_bf16 v[36:39], v[12:15], v[164:167], v[36:39]
	v_mfma_f32_16x16x32_bf16 v[40:43], v[4:7], v[172:175], v[40:43]
	v_mfma_f32_16x16x32_bf16 v[44:47], v[12:15], v[172:175], v[44:47]
	v_mfma_f32_16x16x32_bf16 v[48:51], v[4:7], v[180:183], v[48:51]
	v_mfma_f32_16x16x32_bf16 v[52:55], v[12:15], v[180:183], v[52:55]
	v_mfma_f32_16x16x32_bf16 v[56:59], v[196:199], v[152:155], v[56:59]
	v_mfma_f32_16x16x32_bf16 v[60:63], v[204:207], v[152:155], v[60:63]
	v_mfma_f32_16x16x32_bf16 v[64:67], v[196:199], v[160:163], v[64:67]
	v_mfma_f32_16x16x32_bf16 v[68:71], v[204:207], v[160:163], v[68:71]
	v_mfma_f32_16x16x32_bf16 v[72:75], v[196:199], v[168:171], v[72:75]
	v_mfma_f32_16x16x32_bf16 v[76:79], v[204:207], v[168:171], v[76:79]
	v_mfma_f32_16x16x32_bf16 v[80:83], v[196:199], v[176:179], v[80:83]
	v_mfma_f32_16x16x32_bf16 v[84:87], v[204:207], v[176:179], v[84:87]
	v_mfma_f32_16x16x32_bf16 v[56:59], v[200:203], v[156:159], v[56:59]
	v_mfma_f32_16x16x32_bf16 v[60:63], v[208:211], v[156:159], v[60:63]
	v_mfma_f32_16x16x32_bf16 v[64:67], v[200:203], v[164:167], v[64:67]
	v_mfma_f32_16x16x32_bf16 v[68:71], v[208:211], v[164:167], v[68:71]
	v_mfma_f32_16x16x32_bf16 v[72:75], v[200:203], v[172:175], v[72:75]
	v_mfma_f32_16x16x32_bf16 v[76:79], v[208:211], v[172:175], v[76:79]
	v_mfma_f32_16x16x32_bf16 v[80:83], v[200:203], v[180:183], v[80:83]
	v_mfma_f32_16x16x32_bf16 v[84:87], v[208:211], v[180:183], v[84:87]
	s_setprio 0
	s_barrier
	ds_read_b128 v[152:155], v186 offset:16400
	ds_read_b128 v[156:159], v187 offset:16400
	ds_read_b128 v[160:163], v186 offset:18448
	ds_read_b128 v[164:167], v187 offset:18448
	ds_read_b128 v[168:171], v186 offset:20496
	ds_read_b128 v[172:175], v187 offset:20496
	ds_read_b128 v[176:179], v186 offset:22544
	ds_read_b128 v[180:183], v187 offset:22544
	s_waitcnt lgkmcnt(0)
	s_waitcnt vmcnt(2)
	s_barrier
	s_setprio 1
	v_mfma_f32_16x16x32_bf16 v[88:91], v[0:3], v[152:155], v[88:91]
	v_mfma_f32_16x16x32_bf16 v[92:95], v[8:11], v[152:155], v[92:95]
	v_mfma_f32_16x16x32_bf16 v[96:99], v[0:3], v[160:163], v[96:99]
	v_mfma_f32_16x16x32_bf16 v[100:103], v[8:11], v[160:163], v[100:103]
	v_mfma_f32_16x16x32_bf16 v[104:107], v[0:3], v[168:171], v[104:107]
	v_mfma_f32_16x16x32_bf16 v[108:111], v[8:11], v[168:171], v[108:111]
	v_mfma_f32_16x16x32_bf16 v[112:115], v[0:3], v[176:179], v[112:115]
	v_mfma_f32_16x16x32_bf16 v[116:119], v[8:11], v[176:179], v[116:119]
	v_mfma_f32_16x16x32_bf16 v[88:91], v[4:7], v[156:159], v[88:91]
	v_mfma_f32_16x16x32_bf16 v[92:95], v[12:15], v[156:159], v[92:95]
	v_mfma_f32_16x16x32_bf16 v[96:99], v[4:7], v[164:167], v[96:99]
	v_mfma_f32_16x16x32_bf16 v[100:103], v[12:15], v[164:167], v[100:103]
	v_mfma_f32_16x16x32_bf16 v[104:107], v[4:7], v[172:175], v[104:107]
	v_mfma_f32_16x16x32_bf16 v[108:111], v[12:15], v[172:175], v[108:111]
	v_mfma_f32_16x16x32_bf16 v[112:115], v[4:7], v[180:183], v[112:115]
	v_mfma_f32_16x16x32_bf16 v[116:119], v[12:15], v[180:183], v[116:119]
	v_mfma_f32_16x16x32_bf16 v[120:123], v[196:199], v[152:155], v[120:123]
	v_mfma_f32_16x16x32_bf16 v[124:127], v[204:207], v[152:155], v[124:127]
	v_mfma_f32_16x16x32_bf16 v[128:131], v[196:199], v[160:163], v[128:131]
	v_mfma_f32_16x16x32_bf16 v[132:135], v[204:207], v[160:163], v[132:135]
	v_mfma_f32_16x16x32_bf16 v[136:139], v[196:199], v[168:171], v[136:139]
	v_mfma_f32_16x16x32_bf16 v[140:143], v[204:207], v[168:171], v[140:143]
	v_mfma_f32_16x16x32_bf16 v[144:147], v[196:199], v[176:179], v[144:147]
	v_mfma_f32_16x16x32_bf16 v[148:151], v[204:207], v[176:179], v[148:151]
	v_mfma_f32_16x16x32_bf16 v[120:123], v[200:203], v[156:159], v[120:123]
	v_mfma_f32_16x16x32_bf16 v[124:127], v[208:211], v[156:159], v[124:127]
	v_mfma_f32_16x16x32_bf16 v[128:131], v[200:203], v[164:167], v[128:131]
	v_mfma_f32_16x16x32_bf16 v[132:135], v[208:211], v[164:167], v[132:135]
	v_mfma_f32_16x16x32_bf16 v[136:139], v[200:203], v[172:175], v[136:139]
	v_mfma_f32_16x16x32_bf16 v[140:143], v[208:211], v[172:175], v[140:143]
	v_mfma_f32_16x16x32_bf16 v[144:147], v[200:203], v[180:183], v[144:147]
	v_mfma_f32_16x16x32_bf16 v[148:151], v[208:211], v[180:183], v[148:151]
	s_setprio 0
	s_barrier
; #define LAS __attribute__((address_space(3)))
; #define BAR() { __builtin_amdgcn_sched_barrier(0); __builtin_amdgcn_s_barrier(); asm volatile("" ::: "memory"); __builtin_amdgcn_sched_barrier(0); }
; DI void gemm_stream2(const bf16_t* __restrict__ A, int lda, const bf16_t* __restrict__ Bt, int ldb, int K, int m0, int n0, ...
;     ...
;     for (int kt = 0; kt < nk; ++kt) {
;         const bool pf = (kt + 2 < nk) || has_next, more = (kt + 1 < nk) || has_next;
;         const bf16_t* pa = (kt + 2 < nk) ? ga + (kt + 2) * 64 : gan + (kt + 2 - nk) * 64;
;         const bf16_t* pb = (kt + 2 < nk) ? gb + (kt + 2) * 64 : gbn + (kt + 2 - nk) * 64;
;         const int plda = (kt + 2 < nk) ? lda : ldan, pldb = (kt + 2 < nk) ? ldb : ldbn;
;         const int s2 = st >= 1 ? st - 1 : 2;
;         const LAS char* base = lds + st * 49152;
; #pragma unroll
;         for (int ks = 0; ks < 2; ++ks) {
;             const unsigned fo = ks ? fo1 : fo0;
;             bf16x8 af[4], bfr[4];
; #pragma unroll
;             for (int i = 0; i < 4; ++i) { af[i] = *(const LAS bf16x8*)(base + aoff + i * 2048 + fo); bfr[i] = *(const LAS bf16x8*)(base + boff + i * 2048 + fo); }
;             if (ks == 1 && more) { if (pf) asm volatile("s_waitcnt vmcnt(3)" ::: "memory"); else asm volatile("s_waitcnt vmcnt(0)" ::: "memory"); }
;             if (pf) { PIECE(s2, ks * 3 + 0); PIECE(s2, ks * 3 + 1); PIECE(s2, ks * 3 + 2); }
;             asm volatile("s_waitcnt lgkmcnt(0)" ::: "memory");
;             BAR();
;             __builtin_amdgcn_s_setprio(1);
; #pragma unroll
;             for (int mi = 0; mi < 4; ++mi)
; #pragma unroll
;                 for (int ni = 0; ni < 4; ++ni) acc[mi][ni] = __builtin_amdgcn_mfma_f32_16x16x32_bf16(bfr[ni], af[mi], acc[mi][ni], 0, 0, 0);
;             __builtin_amdgcn_s_setprio(0);
;             BAR();
;         }
;         st = st == 2 ? 0 : st + 1;
;     }
;     if (grp == 0) BAR();
	ds_read_b128 v[0:3], v188 offset:32784
	ds_read_b128 v[4:7], v189 offset:32784
	ds_read_b128 v[8:11], v188 offset:34832
	ds_read_b128 v[12:15], v189 offset:34832
	ds_read_b128 v[196:199], v188 offset:49168
	ds_read_b128 v[200:203], v189 offset:49168
	ds_read_b128 v[204:207], v188 offset:51216
	ds_read_b128 v[208:211], v189 offset:51216
	ds_read_b128 v[152:155], v186 offset:32784
	ds_read_b128 v[156:159], v187 offset:32784
	ds_read_b128 v[160:163], v186 offset:34832
	ds_read_b128 v[164:167], v187 offset:34832
	ds_read_b128 v[168:171], v186 offset:36880
	ds_read_b128 v[172:175], v187 offset:36880
	ds_read_b128 v[176:179], v186 offset:38928
	ds_read_b128 v[180:183], v187 offset:38928
	s_waitcnt lgkmcnt(0)
	s_waitcnt vmcnt(0)
	s_barrier
	s_setprio 1
	v_mfma_f32_16x16x32_bf16 v[24:27], v[0:3], v[152:155], v[24:27]
	v_mfma_f32_16x16x32_bf16 v[28:31], v[8:11], v[152:155], v[28:31]
	v_mfma_f32_16x16x32_bf16 v[32:35], v[0:3], v[160:163], v[32:35]
	v_mfma_f32_16x16x32_bf16 v[36:39], v[8:11], v[160:163], v[36:39]
	v_mfma_f32_16x16x32_bf16 v[40:43], v[0:3], v[168:171], v[40:43]
	v_mfma_f32_16x16x32_bf16 v[44:47], v[8:11], v[168:171], v[44:47]
	v_mfma_f32_16x16x32_bf16 v[48:51], v[0:3], v[176:179], v[48:51]
	v_mfma_f32_16x16x32_bf16 v[52:55], v[8:11], v[176:179], v[52:55]
	v_mfma_f32_16x16x32_bf16 v[24:27], v[4:7], v[156:159], v[24:27]
	v_mfma_f32_16x16x32_bf16 v[28:31], v[12:15], v[156:159], v[28:31]
	v_mfma_f32_16x16x32_bf16 v[32:35], v[4:7], v[164:167], v[32:35]
	v_mfma_f32_16x16x32_bf16 v[36:39], v[12:15], v[164:167], v[36:39]
	v_mfma_f32_16x16x32_bf16 v[40:43], v[4:7], v[172:175], v[40:43]
	v_mfma_f32_16x16x32_bf16 v[44:47], v[12:15], v[172:175], v[44:47]
	v_mfma_f32_16x16x32_bf16 v[48:51], v[4:7], v[180:183], v[48:51]
	v_mfma_f32_16x16x32_bf16 v[52:55], v[12:15], v[180:183], v[52:55]
	v_mfma_f32_16x16x32_bf16 v[56:59], v[196:199], v[152:155], v[56:59]
	v_mfma_f32_16x16x32_bf16 v[60:63], v[204:207], v[152:155], v[60:63]
	v_mfma_f32_16x16x32_bf16 v[64:67], v[196:199], v[160:163], v[64:67]
	v_mfma_f32_16x16x32_bf16 v[68:71], v[204:207], v[160:163], v[68:71]
	v_mfma_f32_16x16x32_bf16 v[72:75], v[196:199], v[168:171], v[72:75]
	v_mfma_f32_16x16x32_bf16 v[76:79], v[204:207], v[168:171], v[76:79]
	v_mfma_f32_16x16x32_bf16 v[80:83], v[196:199], v[176:179], v[80:83]
	v_mfma_f32_16x16x32_bf16 v[84:87], v[204:207], v[176:179], v[84:87]
	v_mfma_f32_16x16x32_bf16 v[56:59], v[200:203], v[156:159], v[56:59]
	v_mfma_f32_16x16x32_bf16 v[60:63], v[208:211], v[156:159], v[60:63]
	v_mfma_f32_16x16x32_bf16 v[64:67], v[200:203], v[164:167], v[64:67]
	v_mfma_f32_16x16x32_bf16 v[68:71], v[208:211], v[164:167], v[68:71]
	v_mfma_f32_16x16x32_bf16 v[72:75], v[200:203], v[172:175], v[72:75]
	v_mfma_f32_16x16x32_bf16 v[76:79], v[208:211], v[172:175], v[76:79]
	v_mfma_f32_16x16x32_bf16 v[80:83], v[200:203], v[180:183], v[80:83]
	v_mfma_f32_16x16x32_bf16 v[84:87], v[208:211], v[180:183], v[84:87]
	s_setprio 0
	s_barrier
	ds_read_b128 v[152:155], v186 offset:49168
	ds_read_b128 v[156:159], v187 offset:49168
	ds_read_b128 v[160:163], v186 offset:51216
	ds_read_b128 v[164:167], v187 offset:51216
	ds_read_b128 v[168:171], v186 offset:53264
	ds_read_b128 v[172:175], v187 offset:53264
	ds_read_b128 v[176:179], v186 offset:55312
	ds_read_b128 v[180:183], v187 offset:55312
	s_waitcnt lgkmcnt(0)
	s_barrier
	s_setprio 1
	v_mfma_f32_16x16x32_bf16 v[88:91], v[0:3], v[152:155], v[88:91]
	v_mfma_f32_16x16x32_bf16 v[92:95], v[8:11], v[152:155], v[92:95]
	v_mfma_f32_16x16x32_bf16 v[96:99], v[0:3], v[160:163], v[96:99]
	v_mfma_f32_16x16x32_bf16 v[100:103], v[8:11], v[160:163], v[100:103]
	v_mfma_f32_16x16x32_bf16 v[104:107], v[0:3], v[168:171], v[104:107]
	v_mfma_f32_16x16x32_bf16 v[108:111], v[8:11], v[168:171], v[108:111]
	v_mfma_f32_16x16x32_bf16 v[112:115], v[0:3], v[176:179], v[112:115]
	v_mfma_f32_16x16x32_bf16 v[116:119], v[8:11], v[176:179], v[116:119]
	v_mfma_f32_16x16x32_bf16 v[88:91], v[4:7], v[156:159], v[88:91]
	v_mfma_f32_16x16x32_bf16 v[92:95], v[12:15], v[156:159], v[92:95]
	v_mfma_f32_16x16x32_bf16 v[96:99], v[4:7], v[164:167], v[96:99]
	v_mfma_f32_16x16x32_bf16 v[100:103], v[12:15], v[164:167], v[100:103]
	v_mfma_f32_16x16x32_bf16 v[104:107], v[4:7], v[172:175], v[104:107]
	v_mfma_f32_16x16x32_bf16 v[108:111], v[12:15], v[172:175], v[108:111]
	v_mfma_f32_16x16x32_bf16 v[112:115], v[4:7], v[180:183], v[112:115]
	v_mfma_f32_16x16x32_bf16 v[116:119], v[12:15], v[180:183], v[116:119]
	v_mfma_f32_16x16x32_bf16 v[120:123], v[196:199], v[152:155], v[120:123]
	v_mfma_f32_16x16x32_bf16 v[124:127], v[204:207], v[152:155], v[124:127]
	v_mfma_f32_16x16x32_bf16 v[128:131], v[196:199], v[160:163], v[128:131]
	v_mfma_f32_16x16x32_bf16 v[132:135], v[204:207], v[160:163], v[132:135]
	v_mfma_f32_16x16x32_bf16 v[136:139], v[196:199], v[168:171], v[136:139]
	v_mfma_f32_16x16x32_bf16 v[140:143], v[204:207], v[168:171], v[140:143]
	v_mfma_f32_16x16x32_bf16 v[144:147], v[196:199], v[176:179], v[144:147]
	v_mfma_f32_16x16x32_bf16 v[148:151], v[204:207], v[176:179], v[148:151]
	v_mfma_f32_16x16x32_bf16 v[120:123], v[200:203], v[156:159], v[120:123]
	v_mfma_f32_16x16x32_bf16 v[124:127], v[208:211], v[156:159], v[124:127]
	v_mfma_f32_16x16x32_bf16 v[128:131], v[200:203], v[164:167], v[128:131]
	v_mfma_f32_16x16x32_bf16 v[132:135], v[208:211], v[164:167], v[132:135]
	v_mfma_f32_16x16x32_bf16 v[136:139], v[200:203], v[172:175], v[136:139]
	v_mfma_f32_16x16x32_bf16 v[140:143], v[208:211], v[172:175], v[140:143]
	v_mfma_f32_16x16x32_bf16 v[144:147], v[200:203], v[180:183], v[144:147]
	v_mfma_f32_16x16x32_bf16 v[148:151], v[208:211], v[180:183], v[148:151]
	s_setprio 0
	s_barrier
	s_cmp_lg_u32 s33, 0
	s_cbranch_scc1 .Lplm_pdone
	s_barrier
; DI unsigned pk2(float lo, float hi) { const f32x2 v = {lo, hi}; return __builtin_bit_cast(unsigned, __builtin_convertvector(v, bf2_t)); }
;     ...
; #pragma unroll
;     for (int mi = 0; mi < 4; ++mi) {
;         const int row = m0 + wm * 64 + mi * 16 + r;
; #pragma unroll
;         for (int ni = 0; ni < 4; ++ni) {
;             const int col = n0 + wn * 64 + ni * 16 + q * 4;
;             if (MODE == 0) {
;                 u32x2 w; w.x = pk2(acc[mi][ni][0], acc[mi][ni][1]); w.y = pk2(acc[mi][ni][2], acc[mi][ni][3]);
;                 *(u32x2*)(Y + (size_t)row * DM + col) = w;
; DI void gemm_ple(const Params& p, int bid, int nb, char* smem, const int tid) {
;     ...
; #pragma unroll
;         for (int i = 0; i < 4; ++i)
; #pragma unroll
;             for (int j = 0; j < 4; ++j) {
;                 acc[i][j][0] *= __uint_as_float(gpk[i][j].x << 16); acc[i][j][1] *= __uint_as_float(gpk[i][j].x & 0xffff0000u);
;                 acc[i][j][2] *= __uint_as_float(gpk[i][j].y << 16); acc[i][j][3] *= __uint_as_float(gpk[i][j].y & 0xffff0000u);
;             }
;         if (m0 < NP) epi_y<0>(p, acc, m0, n0, tid); else epi_y<1>(p, acc, m0, n0, tid);
.Lplm_pdone:
	s_lshl_b32 s1, s51, 17
	s_add_u32 s1, s1, 0x52c0000
	s_add_u32 s2, s88, s1
	s_addc_u32 s3, s89, 0
	global_load_dwordx4 v[152:155], v235, s[2:3] offset:0
	global_load_dwordx4 v[156:159], v235, s[2:3] offset:1024
	global_load_dwordx4 v[160:163], v235, s[2:3] offset:2048
	global_load_dwordx4 v[164:167], v235, s[2:3] offset:3072
	s_add_u32 s2, s2, 0x1000
	s_addc_u32 s3, s3, 0
	global_load_dwordx4 v[168:171], v235, s[2:3] offset:0
	global_load_dwordx4 v[172:175], v235, s[2:3] offset:1024
	global_load_dwordx4 v[176:179], v235, s[2:3] offset:2048
	global_load_dwordx4 v[180:183], v235, s[2:3] offset:3072
	s_add_u32 s2, s2, 0x1000
	s_addc_u32 s3, s3, 0
	global_load_dwordx4 v[0:3], v235, s[2:3] offset:0
	global_load_dwordx4 v[4:7], v235, s[2:3] offset:1024
	global_load_dwordx4 v[8:11], v235, s[2:3] offset:2048
	global_load_dwordx4 v[12:15], v235, s[2:3] offset:3072
	s_add_u32 s2, s2, 0x1000
	s_addc_u32 s3, s3, 0
	global_load_dwordx4 v[196:199], v235, s[2:3] offset:0
	global_load_dwordx4 v[200:203], v235, s[2:3] offset:1024
	global_load_dwordx4 v[204:207], v235, s[2:3] offset:2048
	global_load_dwordx4 v[208:211], v235, s[2:3] offset:3072
	s_lshl_b32 s1, s57, 19
	s_lshl_b32 s62, s58, 9
	s_add_u32 s1, s1, s62
	s_add_u32 s1, s1, 0xac20000
	s_add_u32 s2, s88, s1
	s_addc_u32 s3, s89, 0
	s_nop 7
	s_nop 7
	s_waitcnt vmcnt(15)
	v_lshlrev_b32_e32 v227, 16, v152
	v_and_b32_e32 v228, 0xffff0000, v152
	v_mul_f32_e32 v24, v24, v227
	v_mul_f32_e32 v25, v25, v228
	v_lshlrev_b32_e32 v227, 16, v153
	v_and_b32_e32 v228, 0xffff0000, v153
	v_mul_f32_e32 v26, v26, v227
	v_mul_f32_e32 v27, v27, v228
	v_lshlrev_b32_e32 v227, 16, v154
	v_and_b32_e32 v228, 0xffff0000, v154
	v_mul_f32_e32 v32, v32, v227
	v_mul_f32_e32 v33, v33, v228
	v_lshlrev_b32_e32 v227, 16, v155
	v_and_b32_e32 v228, 0xffff0000, v155
	v_mul_f32_e32 v34, v34, v227
	v_mul_f32_e32 v35, v35, v228
	v_cvt_pk_bf16_f32 v152, v24, v25
	v_cvt_pk_bf16_f32 v153, v26, v27
	v_cvt_pk_bf16_f32 v154, v32, v33
	v_cvt_pk_bf16_f32 v155, v34, v35
	s_nop 1
	v_permlane16_swap_b32_e32 v152, v154
	v_permlane16_swap_b32_e32 v153, v155
	global_store_dwordx4 v236, v[152:155], s[2:3] offset:0
	s_waitcnt vmcnt(15)
	v_lshlrev_b32_e32 v227, 16, v156
	v_and_b32_e32 v228, 0xffff0000, v156
	v_mul_f32_e32 v28, v28, v227
	v_mul_f32_e32 v29, v29, v228
	v_lshlrev_b32_e32 v227, 16, v157
	v_and_b32_e32 v228, 0xffff0000, v157
	v_mul_f32_e32 v30, v30, v227
	v_mul_f32_e32 v31, v31, v228
	v_lshlrev_b32_e32 v227, 16, v158
	v_and_b32_e32 v228, 0xffff0000, v158
	v_mul_f32_e32 v36, v36, v227
	v_mul_f32_e32 v37, v37, v228
	v_lshlrev_b32_e32 v227, 16, v159
	v_and_b32_e32 v228, 0xffff0000, v159
	v_mul_f32_e32 v38, v38, v227
	v_mul_f32_e32 v39, v39, v228
	v_cvt_pk_bf16_f32 v156, v28, v29
	v_cvt_pk_bf16_f32 v157, v30, v31
	v_cvt_pk_bf16_f32 v158, v36, v37
	v_cvt_pk_bf16_f32 v159, v38, v39
	s_nop 1
	v_permlane16_swap_b32_e32 v156, v158
	v_permlane16_swap_b32_e32 v157, v159
	global_store_dwordx4 v236, v[156:159], s[2:3] offset:32
	s_waitcnt vmcnt(15)
	v_lshlrev_b32_e32 v227, 16, v160
	v_and_b32_e32 v228, 0xffff0000, v160
	v_mul_f32_e32 v56, v56, v227
	v_mul_f32_e32 v57, v57, v228
	v_lshlrev_b32_e32 v227, 16, v161
	v_and_b32_e32 v228, 0xffff0000, v161
	v_mul_f32_e32 v58, v58, v227
	v_mul_f32_e32 v59, v59, v228
	v_lshlrev_b32_e32 v227, 16, v162
	v_and_b32_e32 v228, 0xffff0000, v162
	v_mul_f32_e32 v64, v64, v227
	v_mul_f32_e32 v65, v65, v228
	v_lshlrev_b32_e32 v227, 16, v163
	v_and_b32_e32 v228, 0xffff0000, v163
	v_mul_f32_e32 v66, v66, v227
	v_mul_f32_e32 v67, v67, v228
	v_cvt_pk_bf16_f32 v160, v56, v57
	v_cvt_pk_bf16_f32 v161, v58, v59
	v_cvt_pk_bf16_f32 v162, v64, v65
	v_cvt_pk_bf16_f32 v163, v66, v67
	s_nop 1
	v_permlane16_swap_b32_e32 v160, v162
	v_permlane16_swap_b32_e32 v161, v163
	global_store_dwordx4 v236, v[160:163], s[2:3] offset:256
	s_waitcnt vmcnt(15)
	v_lshlrev_b32_e32 v227, 16, v164
	v_and_b32_e32 v228, 0xffff0000, v164
	v_mul_f32_e32 v60, v60, v227
	v_mul_f32_e32 v61, v61, v228
	v_lshlrev_b32_e32 v227, 16, v165
	v_and_b32_e32 v228, 0xffff0000, v165
	v_mul_f32_e32 v62, v62, v227
	v_mul_f32_e32 v63, v63, v228
	v_lshlrev_b32_e32 v227, 16, v166
	v_and_b32_e32 v228, 0xffff0000, v166
	v_mul_f32_e32 v68, v68, v227
	v_mul_f32_e32 v69, v69, v228
	v_lshlrev_b32_e32 v227, 16, v167
	v_and_b32_e32 v228, 0xffff0000, v167
	v_mul_f32_e32 v70, v70, v227
	v_mul_f32_e32 v71, v71, v228
	v_cvt_pk_bf16_f32 v164, v60, v61
	v_cvt_pk_bf16_f32 v165, v62, v63
	v_cvt_pk_bf16_f32 v166, v68, v69
	v_cvt_pk_bf16_f32 v167, v70, v71
	s_nop 1
	v_permlane16_swap_b32_e32 v164, v166
	v_permlane16_swap_b32_e32 v165, v167
	global_store_dwordx4 v236, v[164:167], s[2:3] offset:288
	s_add_u32 s2, s2, 0x10000
	s_addc_u32 s3, s3, 0
	s_waitcnt vmcnt(15)
	v_lshlrev_b32_e32 v227, 16, v168
	v_and_b32_e32 v228, 0xffff0000, v168
	v_mul_f32_e32 v40, v40, v227
	v_mul_f32_e32 v41, v41, v228
	v_lshlrev_b32_e32 v227, 16, v169
	v_and_b32_e32 v228, 0xffff0000, v169
	v_mul_f32_e32 v42, v42, v227
	v_mul_f32_e32 v43, v43, v228
	v_lshlrev_b32_e32 v227, 16, v170
	v_and_b32_e32 v228, 0xffff0000, v170
	v_mul_f32_e32 v48, v48, v227
	v_mul_f32_e32 v49, v49, v228
	v_lshlrev_b32_e32 v227, 16, v171
	v_and_b32_e32 v228, 0xffff0000, v171
	v_mul_f32_e32 v50, v50, v227
	v_mul_f32_e32 v51, v51, v228
	v_cvt_pk_bf16_f32 v168, v40, v41
	v_cvt_pk_bf16_f32 v169, v42, v43
	v_cvt_pk_bf16_f32 v170, v48, v49
	v_cvt_pk_bf16_f32 v171, v50, v51
	s_nop 1
	v_permlane16_swap_b32_e32 v168, v170
	v_permlane16_swap_b32_e32 v169, v171
	global_store_dwordx4 v236, v[168:171], s[2:3] offset:0
	s_waitcnt vmcnt(15)
; DI unsigned pk2(float lo, float hi) { const f32x2 v = {lo, hi}; return __builtin_bit_cast(unsigned, __builtin_convertvector(v, bf2_t)); }
;     ...
; #pragma unroll
;     for (int mi = 0; mi < 4; ++mi) {
;         const int row = m0 + wm * 64 + mi * 16 + r;
; #pragma unroll
;         for (int ni = 0; ni < 4; ++ni) {
;             const int col = n0 + wn * 64 + ni * 16 + q * 4;
;             if (MODE == 0) {
;                 u32x2 w; w.x = pk2(acc[mi][ni][0], acc[mi][ni][1]); w.y = pk2(acc[mi][ni][2], acc[mi][ni][3]);
;                 *(u32x2*)(Y + (size_t)row * DM + col) = w;
; DI void gemm_ple(const Params& p, int bid, int nb, char* smem, const int tid) {
;     ...
; #pragma unroll
;         for (int i = 0; i < 4; ++i)
; #pragma unroll
;             for (int j = 0; j < 4; ++j) {
;                 acc[i][j][0] *= __uint_as_float(gpk[i][j].x << 16); acc[i][j][1] *= __uint_as_float(gpk[i][j].x & 0xffff0000u);
;                 acc[i][j][2] *= __uint_as_float(gpk[i][j].y << 16); acc[i][j][3] *= __uint_as_float(gpk[i][j].y & 0xffff0000u);
;             }
	v_lshlrev_b32_e32 v227, 16, v172
	v_and_b32_e32 v228, 0xffff0000, v172
	v_mul_f32_e32 v44, v44, v227
	v_mul_f32_e32 v45, v45, v228
	v_lshlrev_b32_e32 v227, 16, v173
	v_and_b32_e32 v228, 0xffff0000, v173
	v_mul_f32_e32 v46, v46, v227
	v_mul_f32_e32 v47, v47, v228
	v_lshlrev_b32_e32 v227, 16, v174
	v_and_b32_e32 v228, 0xffff0000, v174
	v_mul_f32_e32 v52, v52, v227
	v_mul_f32_e32 v53, v53, v228
	v_lshlrev_b32_e32 v227, 16, v175
	v_and_b32_e32 v228, 0xffff0000, v175
	v_mul_f32_e32 v54, v54, v227
	v_mul_f32_e32 v55, v55, v228
	v_cvt_pk_bf16_f32 v172, v44, v45
	v_cvt_pk_bf16_f32 v173, v46, v47
	v_cvt_pk_bf16_f32 v174, v52, v53
	v_cvt_pk_bf16_f32 v175, v54, v55
	s_nop 1
	v_permlane16_swap_b32_e32 v172, v174
	v_permlane16_swap_b32_e32 v173, v175
	global_store_dwordx4 v236, v[172:175], s[2:3] offset:32
	s_waitcnt vmcnt(15)
	v_lshlrev_b32_e32 v227, 16, v176
	v_and_b32_e32 v228, 0xffff0000, v176
	v_mul_f32_e32 v72, v72, v227
	v_mul_f32_e32 v73, v73, v228
	v_lshlrev_b32_e32 v227, 16, v177
	v_and_b32_e32 v228, 0xffff0000, v177
	v_mul_f32_e32 v74, v74, v227
	v_mul_f32_e32 v75, v75, v228
	v_lshlrev_b32_e32 v227, 16, v178
	v_and_b32_e32 v228, 0xffff0000, v178
	v_mul_f32_e32 v80, v80, v227
	v_mul_f32_e32 v81, v81, v228
	v_lshlrev_b32_e32 v227, 16, v179
	v_and_b32_e32 v228, 0xffff0000, v179
	v_mul_f32_e32 v82, v82, v227
	v_mul_f32_e32 v83, v83, v228
	v_cvt_pk_bf16_f32 v176, v72, v73
	v_cvt_pk_bf16_f32 v177, v74, v75
	v_cvt_pk_bf16_f32 v178, v80, v81
	v_cvt_pk_bf16_f32 v179, v82, v83
	s_nop 1
	v_permlane16_swap_b32_e32 v176, v178
	v_permlane16_swap_b32_e32 v177, v179
	global_store_dwordx4 v236, v[176:179], s[2:3] offset:256
	s_waitcnt vmcnt(15)
	v_lshlrev_b32_e32 v227, 16, v180
	v_and_b32_e32 v228, 0xffff0000, v180
	v_mul_f32_e32 v76, v76, v227
	v_mul_f32_e32 v77, v77, v228
	v_lshlrev_b32_e32 v227, 16, v181
	v_and_b32_e32 v228, 0xffff0000, v181
	v_mul_f32_e32 v78, v78, v227
	v_mul_f32_e32 v79, v79, v228
	v_lshlrev_b32_e32 v227, 16, v182
	v_and_b32_e32 v228, 0xffff0000, v182
	v_mul_f32_e32 v84, v84, v227
	v_mul_f32_e32 v85, v85, v228
	v_lshlrev_b32_e32 v227, 16, v183
	v_and_b32_e32 v228, 0xffff0000, v183
	v_mul_f32_e32 v86, v86, v227
	v_mul_f32_e32 v87, v87, v228
	v_cvt_pk_bf16_f32 v180, v76, v77
	v_cvt_pk_bf16_f32 v181, v78, v79
	v_cvt_pk_bf16_f32 v182, v84, v85
	v_cvt_pk_bf16_f32 v183, v86, v87
	s_nop 1
	v_permlane16_swap_b32_e32 v180, v182
	v_permlane16_swap_b32_e32 v181, v183
	global_store_dwordx4 v236, v[180:183], s[2:3] offset:288
	s_add_u32 s2, s2, 0x30000
	s_addc_u32 s3, s3, 0
	s_waitcnt vmcnt(15)
	v_lshlrev_b32_e32 v227, 16, v0
	v_and_b32_e32 v228, 0xffff0000, v0
	v_mul_f32_e32 v88, v88, v227
	v_mul_f32_e32 v89, v89, v228
	v_lshlrev_b32_e32 v227, 16, v1
	v_and_b32_e32 v228, 0xffff0000, v1
	v_mul_f32_e32 v90, v90, v227
	v_mul_f32_e32 v91, v91, v228
	v_lshlrev_b32_e32 v227, 16, v2
	v_and_b32_e32 v228, 0xffff0000, v2
	v_mul_f32_e32 v96, v96, v227
	v_mul_f32_e32 v97, v97, v228
	v_lshlrev_b32_e32 v227, 16, v3
	v_and_b32_e32 v228, 0xffff0000, v3
	v_mul_f32_e32 v98, v98, v227
	v_mul_f32_e32 v99, v99, v228
	v_cvt_pk_bf16_f32 v0, v88, v89
	v_cvt_pk_bf16_f32 v1, v90, v91
	v_cvt_pk_bf16_f32 v2, v96, v97
	v_cvt_pk_bf16_f32 v3, v98, v99
	s_nop 1
	v_permlane16_swap_b32_e32 v0, v2
	v_permlane16_swap_b32_e32 v1, v3
	global_store_dwordx4 v236, v[0:3], s[2:3] offset:0
	s_waitcnt vmcnt(15)
	v_lshlrev_b32_e32 v227, 16, v4
	v_and_b32_e32 v228, 0xffff0000, v4
	v_mul_f32_e32 v92, v92, v227
	v_mul_f32_e32 v93, v93, v228
	v_lshlrev_b32_e32 v227, 16, v5
	v_and_b32_e32 v228, 0xffff0000, v5
	v_mul_f32_e32 v94, v94, v227
	v_mul_f32_e32 v95, v95, v228
	v_lshlrev_b32_e32 v227, 16, v6
	v_and_b32_e32 v228, 0xffff0000, v6
	v_mul_f32_e32 v100, v100, v227
	v_mul_f32_e32 v101, v101, v228
	v_lshlrev_b32_e32 v227, 16, v7
	v_and_b32_e32 v228, 0xffff0000, v7
	v_mul_f32_e32 v102, v102, v227
	v_mul_f32_e32 v103, v103, v228
	v_cvt_pk_bf16_f32 v4, v92, v93
	v_cvt_pk_bf16_f32 v5, v94, v95
	v_cvt_pk_bf16_f32 v6, v100, v101
	v_cvt_pk_bf16_f32 v7, v102, v103
	s_nop 1
	v_permlane16_swap_b32_e32 v4, v6
	v_permlane16_swap_b32_e32 v5, v7
	global_store_dwordx4 v236, v[4:7], s[2:3] offset:32
	s_waitcnt vmcnt(15)
	v_lshlrev_b32_e32 v227, 16, v8
	v_and_b32_e32 v228, 0xffff0000, v8
	v_mul_f32_e32 v120, v120, v227
	v_mul_f32_e32 v121, v121, v228
	v_lshlrev_b32_e32 v227, 16, v9
	v_and_b32_e32 v228, 0xffff0000, v9
	v_mul_f32_e32 v122, v122, v227
	v_mul_f32_e32 v123, v123, v228
	v_lshlrev_b32_e32 v227, 16, v10
	v_and_b32_e32 v228, 0xffff0000, v10
	v_mul_f32_e32 v128, v128, v227
	v_mul_f32_e32 v129, v129, v228
	v_lshlrev_b32_e32 v227, 16, v11
	v_and_b32_e32 v228, 0xffff0000, v11
	v_mul_f32_e32 v130, v130, v227
	v_mul_f32_e32 v131, v131, v228
	v_cvt_pk_bf16_f32 v8, v120, v121
	v_cvt_pk_bf16_f32 v9, v122, v123
	v_cvt_pk_bf16_f32 v10, v128, v129
	v_cvt_pk_bf16_f32 v11, v130, v131
	s_nop 1
	v_permlane16_swap_b32_e32 v8, v10
	v_permlane16_swap_b32_e32 v9, v11
	global_store_dwordx4 v236, v[8:11], s[2:3] offset:256
	s_waitcnt vmcnt(15)
	v_lshlrev_b32_e32 v227, 16, v12
	v_and_b32_e32 v228, 0xffff0000, v12
	v_mul_f32_e32 v124, v124, v227
	v_mul_f32_e32 v125, v125, v228
	v_lshlrev_b32_e32 v227, 16, v13
	v_and_b32_e32 v228, 0xffff0000, v13
	v_mul_f32_e32 v126, v126, v227
	v_mul_f32_e32 v127, v127, v228
	v_lshlrev_b32_e32 v227, 16, v14
	v_and_b32_e32 v228, 0xffff0000, v14
	v_mul_f32_e32 v132, v132, v227
	v_mul_f32_e32 v133, v133, v228
	v_lshlrev_b32_e32 v227, 16, v15
	v_and_b32_e32 v228, 0xffff0000, v15
	v_mul_f32_e32 v134, v134, v227
	v_mul_f32_e32 v135, v135, v228
	v_cvt_pk_bf16_f32 v12, v124, v125
	v_cvt_pk_bf16_f32 v13, v126, v127
	v_cvt_pk_bf16_f32 v14, v132, v133
	v_cvt_pk_bf16_f32 v15, v134, v135
	s_nop 1
	v_permlane16_swap_b32_e32 v12, v14
	v_permlane16_swap_b32_e32 v13, v15
	global_store_dwordx4 v236, v[12:15], s[2:3] offset:288
	s_add_u32 s2, s2, 0x10000
	s_addc_u32 s3, s3, 0
	s_waitcnt vmcnt(15)
; DI void gemm_stream2(const bf16_t* __restrict__ A, int lda, const bf16_t* __restrict__ Bt, int ldb, int K, int m0, int n0, ...
;     ...
;     const int wave = __builtin_amdgcn_readfirstlane(tid >> 6), lane = tid & 63, wm = wave >> 1, wn = wave & 1, r = lane & 15, q = lane >> 4;
;     const int sc0 = ((lane & 7) ^ (lane >> 4)) * 8, sc1 = ((lane & 7) ^ (4 | (lane >> 4))) * 8;
;     const bf16_t* ga = A + (size_t)(m0 + wave * 32 + (lane >> 3)) * lda;
;     const bf16_t* gb = Bt + (size_t)(n0 + wave * 16 + (lane >> 3)) * ldb;
;     const bf16_t* gan = An + (size_t)(m0n + wave * 32 + (lane >> 3)) * ldan;
;     const bf16_t* gbn = Btn + (size_t)(n0n + wave * 16 + (lane >> 3)) * ldbn;
;     const unsigned wa = (unsigned)wave * 4096u, wbb = 32768u + (unsigned)wave * 2048u;
; DI void gemm_ple(const Params& p, int bid, int nb, char* smem, const int tid) {
;     ...
;     for (; have; tm = tm2, tn = tn2) {
;         have = ti.next(tm2, tn2);
;         const int m0 = tm * 256, n0 = tn * 128;
;         u32x2 gpk[4][4];
;         {
;             f32x4 gate[4][4]; zero_acc(gate);
;             gemm_stream2(XN, 1024, WG, 1024, 1024, m0, n0, true, PB, 256, WP, 256, m0, n0, smem, gate, tid, rg);
	v_lshlrev_b32_e32 v227, 16, v196
	v_and_b32_e32 v228, 0xffff0000, v196
	v_mul_f32_e32 v104, v104, v227
	v_mul_f32_e32 v105, v105, v228
	v_lshlrev_b32_e32 v227, 16, v197
	v_and_b32_e32 v228, 0xffff0000, v197
	v_mul_f32_e32 v106, v106, v227
	v_mul_f32_e32 v107, v107, v228
	v_lshlrev_b32_e32 v227, 16, v198
	v_and_b32_e32 v228, 0xffff0000, v198
	v_mul_f32_e32 v112, v112, v227
	v_mul_f32_e32 v113, v113, v228
	v_lshlrev_b32_e32 v227, 16, v199
	v_and_b32_e32 v228, 0xffff0000, v199
	v_mul_f32_e32 v114, v114, v227
	v_mul_f32_e32 v115, v115, v228
	v_cvt_pk_bf16_f32 v196, v104, v105
	v_cvt_pk_bf16_f32 v197, v106, v107
	v_cvt_pk_bf16_f32 v198, v112, v113
	v_cvt_pk_bf16_f32 v199, v114, v115
	s_nop 1
	v_permlane16_swap_b32_e32 v196, v198
	v_permlane16_swap_b32_e32 v197, v199
	global_store_dwordx4 v236, v[196:199], s[2:3] offset:0
	s_waitcnt vmcnt(15)
	v_lshlrev_b32_e32 v227, 16, v200
	v_and_b32_e32 v228, 0xffff0000, v200
	v_mul_f32_e32 v108, v108, v227
	v_mul_f32_e32 v109, v109, v228
	v_lshlrev_b32_e32 v227, 16, v201
	v_and_b32_e32 v228, 0xffff0000, v201
	v_mul_f32_e32 v110, v110, v227
	v_mul_f32_e32 v111, v111, v228
	v_lshlrev_b32_e32 v227, 16, v202
	v_and_b32_e32 v228, 0xffff0000, v202
	v_mul_f32_e32 v116, v116, v227
	v_mul_f32_e32 v117, v117, v228
	v_lshlrev_b32_e32 v227, 16, v203
	v_and_b32_e32 v228, 0xffff0000, v203
	v_mul_f32_e32 v118, v118, v227
	v_mul_f32_e32 v119, v119, v228
	v_cvt_pk_bf16_f32 v200, v108, v109
	v_cvt_pk_bf16_f32 v201, v110, v111
	v_cvt_pk_bf16_f32 v202, v116, v117
	v_cvt_pk_bf16_f32 v203, v118, v119
	s_nop 1
	v_permlane16_swap_b32_e32 v200, v202
	v_permlane16_swap_b32_e32 v201, v203
	global_store_dwordx4 v236, v[200:203], s[2:3] offset:32
	s_waitcnt vmcnt(15)
	v_lshlrev_b32_e32 v227, 16, v204
	v_and_b32_e32 v228, 0xffff0000, v204
	v_mul_f32_e32 v136, v136, v227
	v_mul_f32_e32 v137, v137, v228
	v_lshlrev_b32_e32 v227, 16, v205
	v_and_b32_e32 v228, 0xffff0000, v205
	v_mul_f32_e32 v138, v138, v227
	v_mul_f32_e32 v139, v139, v228
	v_lshlrev_b32_e32 v227, 16, v206
	v_and_b32_e32 v228, 0xffff0000, v206
	v_mul_f32_e32 v144, v144, v227
	v_mul_f32_e32 v145, v145, v228
	v_lshlrev_b32_e32 v227, 16, v207
	v_and_b32_e32 v228, 0xffff0000, v207
	v_mul_f32_e32 v146, v146, v227
	v_mul_f32_e32 v147, v147, v228
	v_cvt_pk_bf16_f32 v204, v136, v137
	v_cvt_pk_bf16_f32 v205, v138, v139
	v_cvt_pk_bf16_f32 v206, v144, v145
	v_cvt_pk_bf16_f32 v207, v146, v147
	s_nop 1
	v_permlane16_swap_b32_e32 v204, v206
	v_permlane16_swap_b32_e32 v205, v207
	global_store_dwordx4 v236, v[204:207], s[2:3] offset:256
	s_waitcnt vmcnt(15)
	v_lshlrev_b32_e32 v227, 16, v208
	v_and_b32_e32 v228, 0xffff0000, v208
	v_mul_f32_e32 v140, v140, v227
	v_mul_f32_e32 v141, v141, v228
	v_lshlrev_b32_e32 v227, 16, v209
	v_and_b32_e32 v228, 0xffff0000, v209
	v_mul_f32_e32 v142, v142, v227
	v_mul_f32_e32 v143, v143, v228
	v_lshlrev_b32_e32 v227, 16, v210
	v_and_b32_e32 v228, 0xffff0000, v210
	v_mul_f32_e32 v148, v148, v227
	v_mul_f32_e32 v149, v149, v228
	v_lshlrev_b32_e32 v227, 16, v211
	v_and_b32_e32 v228, 0xffff0000, v211
	v_mul_f32_e32 v150, v150, v227
	v_mul_f32_e32 v151, v151, v228
	v_cvt_pk_bf16_f32 v208, v140, v141
	v_cvt_pk_bf16_f32 v209, v142, v143
	v_cvt_pk_bf16_f32 v210, v148, v149
	v_cvt_pk_bf16_f32 v211, v150, v151
	s_nop 1
	v_permlane16_swap_b32_e32 v208, v210
	v_permlane16_swap_b32_e32 v209, v211
	global_store_dwordx4 v236, v[208:211], s[2:3] offset:288
	s_nop 1
	s_add_u32 s51, s51, s53
	s_cmp_lt_u32 s51, s52
	s_cbranch_scc0 .Lpls_entry
	s_waitcnt vmcnt(0)
	s_branch .Lplm_tile
.Lpls_entry:
	v_readlane_b32 s51, v240, 0
	s_nop 3
	s_cmp_lt_u32 s51, 20
	s_cbranch_scc0 .Lple_exit
	v_readfirstlane_b32 s10, v193
	s_nop 3
	s_lshr_b32 s10, s10, 6
	s_lshr_b32 s33, s10, 2
	s_and_b32 s36, s10, 3
	s_lshl_b32 s39, s10, 11
	s_add_i32 s39, s39, 16
	s_and_b32 s58, s51, 3
	s_lshr_b32 s37, s51, 2
	s_add_u32 s57, s37, 1
	s_mov_b32 s54, 0
	v_and_b32_e32 v190, 63, v193
	v_and_b32_e32 v191, 15, v190
	v_lshrrev_b32_e32 v17, 4, v190
	v_lshrrev_b32_e32 v18, 3, v190
	v_and_b32_e32 v19, 7, v190
	v_xor_b32_e32 v195, v19, v17
	v_lshlrev_b32_e32 v195, 4, v195
	v_or_b32_e32 v227, 4, v17
	v_xor_b32_e32 v227, v19, v227
	v_lshlrev_b32_e32 v227, 4, v227
	v_add_u32_e32 v228, 8, v18
	s_cmp_eq_u32 s37, 4
	s_cbranch_scc1 .Lpls_proj
	v_lshl_add_u32 v184, v18, 11, v195
	v_lshl_add_u32 v185, v228, 11, v227
	s_lshl_b32 s2, s10, 15
	s_lshl_b32 s3, s37, 9
	s_add_u32 s2, s2, s3
	s_add_u32 s1, s2, 0x5240000
	s_add_u32 s66, s88, s1
	s_addc_u32 s67, s89, 0
	s_add_u32 s68, s66, 0x40000
	s_addc_u32 s69, s67, 0
	s_lshl_b32 s1, s58, 19
	s_add_u32 s1, s1, s2
	s_add_u32 s1, s1, 0x27a0000
	s_add_u32 s70, s88, s1
	s_addc_u32 s71, s89, 0
	s_add_u32 s72, s70, 0x40000
	s_addc_u32 s73, s71, 0
	s_branch .Lpls_ptrs
.Lpls_proj:
	v_lshl_add_u32 v184, v18, 9, v195
	v_lshl_add_u32 v185, v228, 9, v227
	s_lshl_b32 s2, s10, 13
	s_add_u32 s1, s2, 0x3220000
	s_add_u32 s66, s88, s1
	s_addc_u32 s67, s89, 0
	s_add_u32 s68, s66, 0x10000
	s_addc_u32 s69, s67, 0
	s_lshl_b32 s1, s58, 17
	s_add_u32 s1, s1, s2
	s_add_u32 s1, s1, 0x29a0000
	s_add_u32 s70, s88, s1
	s_addc_u32 s71, s89, 0
	s_add_u32 s72, s70, 0x10000
	s_addc_u32 s73, s71, 0
; #define BAR() { __builtin_amdgcn_sched_barrier(0); __builtin_amdgcn_s_barrier(); asm volatile("" ::: "memory"); __builtin_amdgcn_sched_barrier(0); }
; DI void gemm_stream2(const bf16_t* __restrict__ A, int lda, const bf16_t* __restrict__ Bt, int ldb, int K, int m0, int n0, ...
;     ...
;     const int wave = __builtin_amdgcn_readfirstlane(tid >> 6), lane = tid & 63, wm = wave >> 1, wn = wave & 1, r = lane & 15, q = lane >> 4;
;     const int sc0 = ((lane & 7) ^ (lane >> 4)) * 8, sc1 = ((lane & 7) ^ (4 | (lane >> 4))) * 8;
;     const bf16_t* ga = A + (size_t)(m0 + wave * 32 + (lane >> 3)) * lda;
;     const bf16_t* gb = Bt + (size_t)(n0 + wave * 16 + (lane >> 3)) * ldb;
;     const bf16_t* gan = An + (size_t)(m0n + wave * 32 + (lane >> 3)) * ldan;
;     const bf16_t* gbn = Btn + (size_t)(n0n + wave * 16 + (lane >> 3)) * ldbn;
;     const unsigned wa = (unsigned)wave * 4096u, wbb = 32768u + (unsigned)wave * 2048u;
;     ...
;     const int sw = r >> 1;
;     const unsigned fo0 = (unsigned)(r * 128 + ((q ^ sw) << 4)), fo1 = (unsigned)(r * 128 + (((q ^ sw) ^ 4) << 4));
;     const unsigned aoff = (unsigned)(wm * 64) * 128u, boff = 32768u + (unsigned)(wn * 64) * 128u;
;     const int nk = K / 64;
;     const int grp = wave >> 2;
;     ...
;     int st = rg.st;
;     if (!rg.primed) {
;         const int s1p = st == 2 ? 0 : st + 1;
;         BAR();
;         STAGE(st, 0);
;         STAGE(s1p, 1);
;         asm volatile("s_waitcnt vmcnt(6)" ::: "memory");
;         BAR();
;     }
;     if (grp == 1) BAR();
.Lpls_ptrs:
	v_lshrrev_b32_e32 v195, 1, v191
	v_xor_b32_e32 v195, v17, v195
	v_lshlrev_b32_e32 v195, 4, v195
	s_lshl_b32 s1, s33, 6
	v_add_u32_e32 v227, s1, v191
	v_lshl_add_u32 v186, v227, 7, v195
	v_xor_b32_e32 v187, 64, v186
	v_lshlrev_b32_e32 v228, 11, v227
	s_lshl_b32 s1, s36, 5
	v_add_u32_e32 v227, s1, v191
	v_lshl_add_u32 v188, v227, 7, v195
	v_add_u32_e32 v188, 0x10000, v188
	v_xor_b32_e32 v189, 64, v188
	s_lshl_b32 s1, s36, 6
	v_lshl_add_u32 v229, v17, 3, s1
	v_add_u32_e32 v237, v228, v229
	s_add_i32 m0, s39, 0x10000
	s_nop 0
	global_load_lds_dwordx4 v184, s[70:71]
	s_add_i32 m0, s39, 0x10400
	s_nop 0
	global_load_lds_dwordx4 v185, s[70:71]
	s_add_u32 s70, s70, 0x80
	s_addc_u32 s71, s71, 0
	s_add_i32 m0, s39, 0x0
	s_nop 0
	global_load_lds_dwordx4 v184, s[66:67]
	s_add_i32 m0, s39, 0x400
	s_nop 0
	global_load_lds_dwordx4 v185, s[66:67]
	s_add_u32 s66, s66, 0x80
	s_addc_u32 s67, s67, 0
	s_add_i32 m0, s39, 0x14000
	s_nop 0
	global_load_lds_dwordx4 v184, s[72:73]
	s_add_i32 m0, s39, 0x14400
	s_nop 0
	global_load_lds_dwordx4 v185, s[72:73]
	s_add_u32 s72, s72, 0x80
	s_addc_u32 s73, s73, 0
	s_add_i32 m0, s39, 0x4000
	s_nop 0
	global_load_lds_dwordx4 v184, s[68:69]
	s_add_i32 m0, s39, 0x4400
	s_nop 0
	global_load_lds_dwordx4 v185, s[68:69]
	s_add_u32 s68, s68, 0x80
	s_addc_u32 s69, s69, 0
	s_cmp_eq_u32 s33, 0
	s_cbranch_scc1 .Lpls_lead
	s_barrier
.Lpls_lead:
	s_waitcnt vmcnt(4)
	s_barrier
	s_add_i32 m0, s39, 0x18000
	s_nop 0
	global_load_lds_dwordx4 v184, s[70:71]
	s_add_i32 m0, s39, 0x18400
	s_nop 0
	global_load_lds_dwordx4 v185, s[70:71]
	s_add_u32 s70, s70, 0x80
	s_addc_u32 s71, s71, 0
	s_add_i32 m0, s39, 0x8000
	s_nop 0
	global_load_lds_dwordx4 v184, s[66:67]
	s_add_i32 m0, s39, 0x8400
	s_nop 0
	global_load_lds_dwordx4 v185, s[66:67]
	s_add_u32 s66, s66, 0x80
	s_addc_u32 s67, s67, 0
	s_add_i32 m0, s39, 0x1c000
	s_nop 0
	global_load_lds_dwordx4 v184, s[72:73]
	s_add_i32 m0, s39, 0x1c400
	s_nop 0
	global_load_lds_dwordx4 v185, s[72:73]
	s_add_u32 s72, s72, 0x80
	s_addc_u32 s73, s73, 0
	s_waitcnt vmcnt(6)
	s_barrier
	v_mov_b64_e32 v[24:25], 0
	v_mov_b64_e32 v[26:27], 0
	v_mov_b64_e32 v[28:29], 0
	v_mov_b64_e32 v[30:31], 0
	v_mov_b64_e32 v[32:33], 0
	v_mov_b64_e32 v[34:35], 0
	v_mov_b64_e32 v[36:37], 0
	v_mov_b64_e32 v[38:39], 0
	v_mov_b64_e32 v[40:41], 0
	v_mov_b64_e32 v[42:43], 0
	v_mov_b64_e32 v[44:45], 0
	v_mov_b64_e32 v[46:47], 0
	v_mov_b64_e32 v[48:49], 0
	v_mov_b64_e32 v[50:51], 0
	v_mov_b64_e32 v[52:53], 0
	v_mov_b64_e32 v[54:55], 0
	v_mov_b64_e32 v[56:57], 0
	v_mov_b64_e32 v[58:59], 0
	v_mov_b64_e32 v[60:61], 0
	v_mov_b64_e32 v[62:63], 0
	v_mov_b64_e32 v[64:65], 0
	v_mov_b64_e32 v[66:67], 0
	v_mov_b64_e32 v[68:69], 0
	v_mov_b64_e32 v[70:71], 0
	v_mov_b64_e32 v[72:73], 0
	v_mov_b64_e32 v[74:75], 0
	v_mov_b64_e32 v[76:77], 0
	v_mov_b64_e32 v[78:79], 0
	v_mov_b64_e32 v[80:81], 0
	v_mov_b64_e32 v[82:83], 0
	v_mov_b64_e32 v[84:85], 0
	v_mov_b64_e32 v[86:87], 0
	v_mov_b64_e32 v[88:89], 0
	v_mov_b64_e32 v[90:91], 0
	v_mov_b64_e32 v[92:93], 0
	v_mov_b64_e32 v[94:95], 0
	v_mov_b64_e32 v[96:97], 0
	v_mov_b64_e32 v[98:99], 0
	v_mov_b64_e32 v[100:101], 0
	v_mov_b64_e32 v[102:103], 0
	v_mov_b64_e32 v[104:105], 0
	v_mov_b64_e32 v[106:107], 0
	v_mov_b64_e32 v[108:109], 0
	v_mov_b64_e32 v[110:111], 0
	v_mov_b64_e32 v[112:113], 0
	v_mov_b64_e32 v[114:115], 0
	v_mov_b64_e32 v[116:117], 0
	v_mov_b64_e32 v[118:119], 0
	v_mov_b64_e32 v[120:121], 0
	v_mov_b64_e32 v[122:123], 0
	v_mov_b64_e32 v[124:125], 0
	v_mov_b64_e32 v[126:127], 0
	v_mov_b64_e32 v[128:129], 0
	v_mov_b64_e32 v[130:131], 0
	v_mov_b64_e32 v[132:133], 0
	v_mov_b64_e32 v[134:135], 0
	v_mov_b64_e32 v[136:137], 0
	v_mov_b64_e32 v[138:139], 0
	v_mov_b64_e32 v[140:141], 0
	v_mov_b64_e32 v[142:143], 0
	v_mov_b64_e32 v[144:145], 0
	v_mov_b64_e32 v[146:147], 0
	v_mov_b64_e32 v[148:149], 0
	v_mov_b64_e32 v[150:151], 0
	s_mov_b32 s0, 1
	ds_read_b128 v[0:3], v188 offset:16
	ds_read_b128 v[4:7], v189 offset:16
	ds_read_b128 v[8:11], v188 offset:2064
	ds_read_b128 v[12:15], v189 offset:2064
	ds_read_b128 v[152:155], v186 offset:16
	ds_read_b128 v[156:159], v187 offset:16
	ds_read_b128 v[160:163], v186 offset:2064
	ds_read_b128 v[164:167], v187 offset:2064
	ds_read_b128 v[168:171], v186 offset:4112
	ds_read_b128 v[172:175], v187 offset:4112
	ds_read_b128 v[176:179], v186 offset:6160
	ds_read_b128 v[180:183], v187 offset:6160
	s_add_i32 m0, s39, 0xc000
	s_nop 0
	global_load_lds_dwordx4 v184, s[68:69]
	s_add_i32 m0, s39, 0xc400
	s_nop 0
	global_load_lds_dwordx4 v185, s[68:69]
	s_add_u32 s68, s68, 0x80
	s_addc_u32 s69, s69, 0
	s_cmp_lg_u32 s0, s54
	s_cbranch_scc1 .Lpls_nosw1
	s_mov_b64 s[66:67], s[74:75]
	s_mov_b64 s[68:69], s[78:79]
	s_mov_b64 s[70:71], s[80:81]
	s_mov_b64 s[72:73], s[82:83]
; #define LAS __attribute__((address_space(3)))
; #define BAR() { __builtin_amdgcn_sched_barrier(0); __builtin_amdgcn_s_barrier(); asm volatile("" ::: "memory"); __builtin_amdgcn_sched_barrier(0); }
; DI void gemm_stream2(const bf16_t* __restrict__ A, int lda, const bf16_t* __restrict__ Bt, int ldb, int K, int m0, int n0, ...
;     ...
;     for (int kt = 0; kt < nk; ++kt) {
;         const bool pf = (kt + 2 < nk) || has_next, more = (kt + 1 < nk) || has_next;
;         const bf16_t* pa = (kt + 2 < nk) ? ga + (kt + 2) * 64 : gan + (kt + 2 - nk) * 64;
;         const bf16_t* pb = (kt + 2 < nk) ? gb + (kt + 2) * 64 : gbn + (kt + 2 - nk) * 64;
;         const int plda = (kt + 2 < nk) ? lda : ldan, pldb = (kt + 2 < nk) ? ldb : ldbn;
;         const int s2 = st >= 1 ? st - 1 : 2;
;         const LAS char* base = lds + st * 49152;
; #pragma unroll
;         for (int ks = 0; ks < 2; ++ks) {
;             const unsigned fo = ks ? fo1 : fo0;
;             bf16x8 af[4], bfr[4];
; #pragma unroll
;             for (int i = 0; i < 4; ++i) { af[i] = *(const LAS bf16x8*)(base + aoff + i * 2048 + fo); bfr[i] = *(const LAS bf16x8*)(base + boff + i * 2048 + fo); }
;             if (ks == 1 && more) { if (pf) asm volatile("s_waitcnt vmcnt(3)" ::: "memory"); else asm volatile("s_waitcnt vmcnt(0)" ::: "memory"); }
;             if (pf) { PIECE(s2, ks * 3 + 0); PIECE(s2, ks * 3 + 1); PIECE(s2, ks * 3 + 2); }
;             asm volatile("s_waitcnt lgkmcnt(0)" ::: "memory");
;             BAR();
;             __builtin_amdgcn_s_setprio(1);
; #pragma unroll
;             for (int mi = 0; mi < 4; ++mi)
; #pragma unroll
;                 for (int ni = 0; ni < 4; ++ni) acc[mi][ni] = __builtin_amdgcn_mfma_f32_16x16x32_bf16(bfr[ni], af[mi], acc[mi][ni], 0, 0, 0);
;             __builtin_amdgcn_s_setprio(0);
;             BAR();
;         }
;         st = st == 2 ? 0 : st + 1;
;     }
.Lpls_nosw1:
	s_waitcnt lgkmcnt(8)
	s_barrier
	s_waitcnt lgkmcnt(0)
	s_setprio 1
	v_mfma_f32_16x16x32_bf16 v[24:27], v[0:3], v[152:155], v[24:27]
	v_mfma_f32_16x16x32_bf16 v[28:31], v[8:11], v[152:155], v[28:31]
	v_mfma_f32_16x16x32_bf16 v[32:35], v[0:3], v[160:163], v[32:35]
	v_mfma_f32_16x16x32_bf16 v[36:39], v[8:11], v[160:163], v[36:39]
	v_mfma_f32_16x16x32_bf16 v[40:43], v[0:3], v[168:171], v[40:43]
	v_mfma_f32_16x16x32_bf16 v[44:47], v[8:11], v[168:171], v[44:47]
	v_mfma_f32_16x16x32_bf16 v[48:51], v[0:3], v[176:179], v[48:51]
	v_mfma_f32_16x16x32_bf16 v[52:55], v[8:11], v[176:179], v[52:55]
	v_mfma_f32_16x16x32_bf16 v[24:27], v[4:7], v[156:159], v[24:27]
	v_mfma_f32_16x16x32_bf16 v[28:31], v[12:15], v[156:159], v[28:31]
	v_mfma_f32_16x16x32_bf16 v[32:35], v[4:7], v[164:167], v[32:35]
	v_mfma_f32_16x16x32_bf16 v[36:39], v[12:15], v[164:167], v[36:39]
	v_mfma_f32_16x16x32_bf16 v[40:43], v[4:7], v[172:175], v[40:43]
	v_mfma_f32_16x16x32_bf16 v[44:47], v[12:15], v[172:175], v[44:47]
	v_mfma_f32_16x16x32_bf16 v[48:51], v[4:7], v[180:183], v[48:51]
	v_mfma_f32_16x16x32_bf16 v[52:55], v[12:15], v[180:183], v[52:55]
	s_setprio 0
	s_barrier
	ds_read_b128 v[196:199], v188 offset:16400
	ds_read_b128 v[200:203], v189 offset:16400
	ds_read_b128 v[204:207], v188 offset:18448
	ds_read_b128 v[208:211], v189 offset:18448
	s_add_i32 m0, s39, 0x10000
	s_nop 0
	global_load_lds_dwordx4 v184, s[70:71]
	s_add_i32 m0, s39, 0x10400
	s_nop 0
	global_load_lds_dwordx4 v185, s[70:71]
	s_add_u32 s70, s70, 0x80
	s_addc_u32 s71, s71, 0
	s_barrier
	s_waitcnt lgkmcnt(0)
	s_setprio 1
	v_mfma_f32_16x16x32_bf16 v[56:59], v[196:199], v[152:155], v[56:59]
	v_mfma_f32_16x16x32_bf16 v[60:63], v[204:207], v[152:155], v[60:63]
	v_mfma_f32_16x16x32_bf16 v[64:67], v[196:199], v[160:163], v[64:67]
	v_mfma_f32_16x16x32_bf16 v[68:71], v[204:207], v[160:163], v[68:71]
	v_mfma_f32_16x16x32_bf16 v[72:75], v[196:199], v[168:171], v[72:75]
	v_mfma_f32_16x16x32_bf16 v[76:79], v[204:207], v[168:171], v[76:79]
	v_mfma_f32_16x16x32_bf16 v[80:83], v[196:199], v[176:179], v[80:83]
	v_mfma_f32_16x16x32_bf16 v[84:87], v[204:207], v[176:179], v[84:87]
	v_mfma_f32_16x16x32_bf16 v[56:59], v[200:203], v[156:159], v[56:59]
	v_mfma_f32_16x16x32_bf16 v[60:63], v[208:211], v[156:159], v[60:63]
	v_mfma_f32_16x16x32_bf16 v[64:67], v[200:203], v[164:167], v[64:67]
	v_mfma_f32_16x16x32_bf16 v[68:71], v[208:211], v[164:167], v[68:71]
	v_mfma_f32_16x16x32_bf16 v[72:75], v[200:203], v[172:175], v[72:75]
	v_mfma_f32_16x16x32_bf16 v[76:79], v[208:211], v[172:175], v[76:79]
	v_mfma_f32_16x16x32_bf16 v[80:83], v[200:203], v[180:183], v[80:83]
	v_mfma_f32_16x16x32_bf16 v[84:87], v[208:211], v[180:183], v[84:87]
	s_setprio 0
	s_barrier
	ds_read_b128 v[152:155], v186 offset:16400
	ds_read_b128 v[156:159], v187 offset:16400
	ds_read_b128 v[160:163], v186 offset:18448
	ds_read_b128 v[164:167], v187 offset:18448
	ds_read_b128 v[168:171], v186 offset:20496
	ds_read_b128 v[172:175], v187 offset:20496
	ds_read_b128 v[176:179], v186 offset:22544
	ds_read_b128 v[180:183], v187 offset:22544
	s_add_i32 m0, s39, 0x0
	s_nop 0
	global_load_lds_dwordx4 v184, s[66:67]
	s_add_i32 m0, s39, 0x400
	s_nop 0
	global_load_lds_dwordx4 v185, s[66:67]
	s_add_u32 s66, s66, 0x80
	s_addc_u32 s67, s67, 0
	s_barrier
	s_waitcnt lgkmcnt(0)
	s_setprio 1
	v_mfma_f32_16x16x32_bf16 v[88:91], v[0:3], v[152:155], v[88:91]
	v_mfma_f32_16x16x32_bf16 v[92:95], v[8:11], v[152:155], v[92:95]
	v_mfma_f32_16x16x32_bf16 v[96:99], v[0:3], v[160:163], v[96:99]
	v_mfma_f32_16x16x32_bf16 v[100:103], v[8:11], v[160:163], v[100:103]
	v_mfma_f32_16x16x32_bf16 v[104:107], v[0:3], v[168:171], v[104:107]
	v_mfma_f32_16x16x32_bf16 v[108:111], v[8:11], v[168:171], v[108:111]
	v_mfma_f32_16x16x32_bf16 v[112:115], v[0:3], v[176:179], v[112:115]
	v_mfma_f32_16x16x32_bf16 v[116:119], v[8:11], v[176:179], v[116:119]
	v_mfma_f32_16x16x32_bf16 v[88:91], v[4:7], v[156:159], v[88:91]
	v_mfma_f32_16x16x32_bf16 v[92:95], v[12:15], v[156:159], v[92:95]
	v_mfma_f32_16x16x32_bf16 v[96:99], v[4:7], v[164:167], v[96:99]
	v_mfma_f32_16x16x32_bf16 v[100:103], v[12:15], v[164:167], v[100:103]
	v_mfma_f32_16x16x32_bf16 v[104:107], v[4:7], v[172:175], v[104:107]
	v_mfma_f32_16x16x32_bf16 v[108:111], v[12:15], v[172:175], v[108:111]
	v_mfma_f32_16x16x32_bf16 v[112:115], v[4:7], v[180:183], v[112:115]
	v_mfma_f32_16x16x32_bf16 v[116:119], v[12:15], v[180:183], v[116:119]
	s_setprio 0
	s_barrier
	s_add_i32 m0, s39, 0x14000
	s_nop 0
	global_load_lds_dwordx4 v184, s[72:73]
	s_add_i32 m0, s39, 0x14400
	s_nop 0
	global_load_lds_dwordx4 v185, s[72:73]
	s_add_u32 s72, s72, 0x80
	s_addc_u32 s73, s73, 0
	s_waitcnt vmcnt(6)
	s_barrier
	s_setprio 1
	v_mfma_f32_16x16x32_bf16 v[120:123], v[196:199], v[152:155], v[120:123]
	v_mfma_f32_16x16x32_bf16 v[124:127], v[204:207], v[152:155], v[124:127]
	v_mfma_f32_16x16x32_bf16 v[128:131], v[196:199], v[160:163], v[128:131]
	v_mfma_f32_16x16x32_bf16 v[132:135], v[204:207], v[160:163], v[132:135]
	v_mfma_f32_16x16x32_bf16 v[136:139], v[196:199], v[168:171], v[136:139]
	v_mfma_f32_16x16x32_bf16 v[140:143], v[204:207], v[168:171], v[140:143]
	v_mfma_f32_16x16x32_bf16 v[144:147], v[196:199], v[176:179], v[144:147]
	v_mfma_f32_16x16x32_bf16 v[148:151], v[204:207], v[176:179], v[148:151]
	v_mfma_f32_16x16x32_bf16 v[120:123], v[200:203], v[156:159], v[120:123]
	v_mfma_f32_16x16x32_bf16 v[124:127], v[208:211], v[156:159], v[124:127]
	v_mfma_f32_16x16x32_bf16 v[128:131], v[200:203], v[164:167], v[128:131]
	v_mfma_f32_16x16x32_bf16 v[132:135], v[208:211], v[164:167], v[132:135]
	v_mfma_f32_16x16x32_bf16 v[136:139], v[200:203], v[172:175], v[136:139]
	v_mfma_f32_16x16x32_bf16 v[140:143], v[208:211], v[172:175], v[140:143]
	v_mfma_f32_16x16x32_bf16 v[144:147], v[200:203], v[180:183], v[144:147]
	v_mfma_f32_16x16x32_bf16 v[148:151], v[208:211], v[180:183], v[148:151]
	s_setprio 0
	s_barrier
; #define LAS __attribute__((address_space(3)))
; #define BAR() { __builtin_amdgcn_sched_barrier(0); __builtin_amdgcn_s_barrier(); asm volatile("" ::: "memory"); __builtin_amdgcn_sched_barrier(0); }
; DI void gemm_stream2(const bf16_t* __restrict__ A, int lda, const bf16_t* __restrict__ Bt, int ldb, int K, int m0, int n0, ...
;     ...
;     for (int kt = 0; kt < nk; ++kt) {
;         const bool pf = (kt + 2 < nk) || has_next, more = (kt + 1 < nk) || has_next;
;         const bf16_t* pa = (kt + 2 < nk) ? ga + (kt + 2) * 64 : gan + (kt + 2 - nk) * 64;
;         const bf16_t* pb = (kt + 2 < nk) ? gb + (kt + 2) * 64 : gbn + (kt + 2 - nk) * 64;
;         const int plda = (kt + 2 < nk) ? lda : ldan, pldb = (kt + 2 < nk) ? ldb : ldbn;
;         const int s2 = st >= 1 ? st - 1 : 2;
;         const LAS char* base = lds + st * 49152;
; #pragma unroll
;         for (int ks = 0; ks < 2; ++ks) {
;             const unsigned fo = ks ? fo1 : fo0;
;             bf16x8 af[4], bfr[4];
; #pragma unroll
;             for (int i = 0; i < 4; ++i) { af[i] = *(const LAS bf16x8*)(base + aoff + i * 2048 + fo); bfr[i] = *(const LAS bf16x8*)(base + boff + i * 2048 + fo); }
;             if (ks == 1 && more) { if (pf) asm volatile("s_waitcnt vmcnt(3)" ::: "memory"); else asm volatile("s_waitcnt vmcnt(0)" ::: "memory"); }
;             if (pf) { PIECE(s2, ks * 3 + 0); PIECE(s2, ks * 3 + 1); PIECE(s2, ks * 3 + 2); }
;             asm volatile("s_waitcnt lgkmcnt(0)" ::: "memory");
;             BAR();
;             __builtin_amdgcn_s_setprio(1);
; #pragma unroll
;             for (int mi = 0; mi < 4; ++mi)
; #pragma unroll
;                 for (int ni = 0; ni < 4; ++ni) acc[mi][ni] = __builtin_amdgcn_mfma_f32_16x16x32_bf16(bfr[ni], af[mi], acc[mi][ni], 0, 0, 0);
;             __builtin_amdgcn_s_setprio(0);
;             BAR();
;         }
;         st = st == 2 ? 0 : st + 1;
;     }
	ds_read_b128 v[0:3], v188 offset:32784
	ds_read_b128 v[4:7], v189 offset:32784
	ds_read_b128 v[8:11], v188 offset:34832
	ds_read_b128 v[12:15], v189 offset:34832
	ds_read_b128 v[152:155], v186 offset:32784
	ds_read_b128 v[156:159], v187 offset:32784
	ds_read_b128 v[160:163], v186 offset:34832
	ds_read_b128 v[164:167], v187 offset:34832
	ds_read_b128 v[168:171], v186 offset:36880
	ds_read_b128 v[172:175], v187 offset:36880
	ds_read_b128 v[176:179], v186 offset:38928
	ds_read_b128 v[180:183], v187 offset:38928
	s_add_i32 m0, s39, 0x4000
	s_nop 0
	global_load_lds_dwordx4 v184, s[68:69]
	s_add_i32 m0, s39, 0x4400
	s_nop 0
	global_load_lds_dwordx4 v185, s[68:69]
	s_add_u32 s68, s68, 0x80
	s_addc_u32 s69, s69, 0
	s_waitcnt lgkmcnt(8)
	s_barrier
	s_waitcnt lgkmcnt(0)
	s_setprio 1
	v_mfma_f32_16x16x32_bf16 v[24:27], v[0:3], v[152:155], v[24:27]
	v_mfma_f32_16x16x32_bf16 v[28:31], v[8:11], v[152:155], v[28:31]
	v_mfma_f32_16x16x32_bf16 v[32:35], v[0:3], v[160:163], v[32:35]
	v_mfma_f32_16x16x32_bf16 v[36:39], v[8:11], v[160:163], v[36:39]
	v_mfma_f32_16x16x32_bf16 v[40:43], v[0:3], v[168:171], v[40:43]
	v_mfma_f32_16x16x32_bf16 v[44:47], v[8:11], v[168:171], v[44:47]
	v_mfma_f32_16x16x32_bf16 v[48:51], v[0:3], v[176:179], v[48:51]
	v_mfma_f32_16x16x32_bf16 v[52:55], v[8:11], v[176:179], v[52:55]
	v_mfma_f32_16x16x32_bf16 v[24:27], v[4:7], v[156:159], v[24:27]
	v_mfma_f32_16x16x32_bf16 v[28:31], v[12:15], v[156:159], v[28:31]
	v_mfma_f32_16x16x32_bf16 v[32:35], v[4:7], v[164:167], v[32:35]
	v_mfma_f32_16x16x32_bf16 v[36:39], v[12:15], v[164:167], v[36:39]
	v_mfma_f32_16x16x32_bf16 v[40:43], v[4:7], v[172:175], v[40:43]
	v_mfma_f32_16x16x32_bf16 v[44:47], v[12:15], v[172:175], v[44:47]
	v_mfma_f32_16x16x32_bf16 v[48:51], v[4:7], v[180:183], v[48:51]
	v_mfma_f32_16x16x32_bf16 v[52:55], v[12:15], v[180:183], v[52:55]
	s_setprio 0
	s_barrier
	ds_read_b128 v[196:199], v188 offset:49168
	ds_read_b128 v[200:203], v189 offset:49168
	ds_read_b128 v[204:207], v188 offset:51216
	ds_read_b128 v[208:211], v189 offset:51216
	s_add_i32 m0, s39, 0x18000
	s_nop 0
	global_load_lds_dwordx4 v184, s[70:71]
	s_add_i32 m0, s39, 0x18400
	s_nop 0
	global_load_lds_dwordx4 v185, s[70:71]
	s_add_u32 s70, s70, 0x80
	s_addc_u32 s71, s71, 0
	s_barrier
	s_waitcnt lgkmcnt(0)
	s_setprio 1
	v_mfma_f32_16x16x32_bf16 v[56:59], v[196:199], v[152:155], v[56:59]
	v_mfma_f32_16x16x32_bf16 v[60:63], v[204:207], v[152:155], v[60:63]
	v_mfma_f32_16x16x32_bf16 v[64:67], v[196:199], v[160:163], v[64:67]
	v_mfma_f32_16x16x32_bf16 v[68:71], v[204:207], v[160:163], v[68:71]
	v_mfma_f32_16x16x32_bf16 v[72:75], v[196:199], v[168:171], v[72:75]
	v_mfma_f32_16x16x32_bf16 v[76:79], v[204:207], v[168:171], v[76:79]
	v_mfma_f32_16x16x32_bf16 v[80:83], v[196:199], v[176:179], v[80:83]
	v_mfma_f32_16x16x32_bf16 v[84:87], v[204:207], v[176:179], v[84:87]
	v_mfma_f32_16x16x32_bf16 v[56:59], v[200:203], v[156:159], v[56:59]
	v_mfma_f32_16x16x32_bf16 v[60:63], v[208:211], v[156:159], v[60:63]
	v_mfma_f32_16x16x32_bf16 v[64:67], v[200:203], v[164:167], v[64:67]
	v_mfma_f32_16x16x32_bf16 v[68:71], v[208:211], v[164:167], v[68:71]
	v_mfma_f32_16x16x32_bf16 v[72:75], v[200:203], v[172:175], v[72:75]
	v_mfma_f32_16x16x32_bf16 v[76:79], v[208:211], v[172:175], v[76:79]
	v_mfma_f32_16x16x32_bf16 v[80:83], v[200:203], v[180:183], v[80:83]
	v_mfma_f32_16x16x32_bf16 v[84:87], v[208:211], v[180:183], v[84:87]
	s_setprio 0
	s_barrier
	ds_read_b128 v[152:155], v186 offset:49168
	ds_read_b128 v[156:159], v187 offset:49168
	ds_read_b128 v[160:163], v186 offset:51216
	ds_read_b128 v[164:167], v187 offset:51216
	ds_read_b128 v[168:171], v186 offset:53264
	ds_read_b128 v[172:175], v187 offset:53264
	ds_read_b128 v[176:179], v186 offset:55312
	ds_read_b128 v[180:183], v187 offset:55312
	s_add_i32 m0, s39, 0x8000
	s_nop 0
	global_load_lds_dwordx4 v184, s[66:67]
	s_add_i32 m0, s39, 0x8400
	s_nop 0
	global_load_lds_dwordx4 v185, s[66:67]
	s_add_u32 s66, s66, 0x80
	s_addc_u32 s67, s67, 0
	s_barrier
	s_waitcnt lgkmcnt(0)
	s_setprio 1
	v_mfma_f32_16x16x32_bf16 v[88:91], v[0:3], v[152:155], v[88:91]
	v_mfma_f32_16x16x32_bf16 v[92:95], v[8:11], v[152:155], v[92:95]
	v_mfma_f32_16x16x32_bf16 v[96:99], v[0:3], v[160:163], v[96:99]
	v_mfma_f32_16x16x32_bf16 v[100:103], v[8:11], v[160:163], v[100:103]
	v_mfma_f32_16x16x32_bf16 v[104:107], v[0:3], v[168:171], v[104:107]
	v_mfma_f32_16x16x32_bf16 v[108:111], v[8:11], v[168:171], v[108:111]
	v_mfma_f32_16x16x32_bf16 v[112:115], v[0:3], v[176:179], v[112:115]
	v_mfma_f32_16x16x32_bf16 v[116:119], v[8:11], v[176:179], v[116:119]
	v_mfma_f32_16x16x32_bf16 v[88:91], v[4:7], v[156:159], v[88:91]
	v_mfma_f32_16x16x32_bf16 v[92:95], v[12:15], v[156:159], v[92:95]
	v_mfma_f32_16x16x32_bf16 v[96:99], v[4:7], v[164:167], v[96:99]
	v_mfma_f32_16x16x32_bf16 v[100:103], v[12:15], v[164:167], v[100:103]
	v_mfma_f32_16x16x32_bf16 v[104:107], v[4:7], v[172:175], v[104:107]
	v_mfma_f32_16x16x32_bf16 v[108:111], v[12:15], v[172:175], v[108:111]
	v_mfma_f32_16x16x32_bf16 v[112:115], v[4:7], v[180:183], v[112:115]
	v_mfma_f32_16x16x32_bf16 v[116:119], v[12:15], v[180:183], v[116:119]
	s_setprio 0
	s_barrier
	s_add_i32 m0, s39, 0x1c000
	s_nop 0
	global_load_lds_dwordx4 v184, s[72:73]
	s_add_i32 m0, s39, 0x1c400
	s_nop 0
	global_load_lds_dwordx4 v185, s[72:73]
	s_add_u32 s72, s72, 0x80
	s_addc_u32 s73, s73, 0
	s_waitcnt vmcnt(6)
	s_barrier
; #define LAS __attribute__((address_space(3)))
; #define BAR() { __builtin_amdgcn_sched_barrier(0); __builtin_amdgcn_s_barrier(); asm volatile("" ::: "memory"); __builtin_amdgcn_sched_barrier(0); }
; DI void gemm_stream2(const bf16_t* __restrict__ A, int lda, const bf16_t* __restrict__ Bt, int ldb, int K, int m0, int n0, ...
;     ...
;     for (int kt = 0; kt < nk; ++kt) {
;         const bool pf = (kt + 2 < nk) || has_next, more = (kt + 1 < nk) || has_next;
;         const bf16_t* pa = (kt + 2 < nk) ? ga + (kt + 2) * 64 : gan + (kt + 2 - nk) * 64;
;         const bf16_t* pb = (kt + 2 < nk) ? gb + (kt + 2) * 64 : gbn + (kt + 2 - nk) * 64;
;         const int plda = (kt + 2 < nk) ? lda : ldan, pldb = (kt + 2 < nk) ? ldb : ldbn;
;         const int s2 = st >= 1 ? st - 1 : 2;
;         const LAS char* base = lds + st * 49152;
; #pragma unroll
;         for (int ks = 0; ks < 2; ++ks) {
;             const unsigned fo = ks ? fo1 : fo0;
;             bf16x8 af[4], bfr[4];
; #pragma unroll
;             for (int i = 0; i < 4; ++i) { af[i] = *(const LAS bf16x8*)(base + aoff + i * 2048 + fo); bfr[i] = *(const LAS bf16x8*)(base + boff + i * 2048 + fo); }
;             if (ks == 1 && more) { if (pf) asm volatile("s_waitcnt vmcnt(3)" ::: "memory"); else asm volatile("s_waitcnt vmcnt(0)" ::: "memory"); }
;             if (pf) { PIECE(s2, ks * 3 + 0); PIECE(s2, ks * 3 + 1); PIECE(s2, ks * 3 + 2); }
;             asm volatile("s_waitcnt lgkmcnt(0)" ::: "memory");
;             BAR();
;             __builtin_amdgcn_s_setprio(1);
; #pragma unroll
;             for (int mi = 0; mi < 4; ++mi)
; #pragma unroll
;                 for (int ni = 0; ni < 4; ++ni) acc[mi][ni] = __builtin_amdgcn_mfma_f32_16x16x32_bf16(bfr[ni], af[mi], acc[mi][ni], 0, 0, 0);
;             __builtin_amdgcn_s_setprio(0);
;             BAR();
;         }
;         st = st == 2 ? 0 : st + 1;
;     }
	s_setprio 1
	v_mfma_f32_16x16x32_bf16 v[120:123], v[196:199], v[152:155], v[120:123]
	v_mfma_f32_16x16x32_bf16 v[124:127], v[204:207], v[152:155], v[124:127]
	v_mfma_f32_16x16x32_bf16 v[128:131], v[196:199], v[160:163], v[128:131]
	v_mfma_f32_16x16x32_bf16 v[132:135], v[204:207], v[160:163], v[132:135]
	v_mfma_f32_16x16x32_bf16 v[136:139], v[196:199], v[168:171], v[136:139]
	v_mfma_f32_16x16x32_bf16 v[140:143], v[204:207], v[168:171], v[140:143]
	v_mfma_f32_16x16x32_bf16 v[144:147], v[196:199], v[176:179], v[144:147]
	v_mfma_f32_16x16x32_bf16 v[148:151], v[204:207], v[176:179], v[148:151]
	v_mfma_f32_16x16x32_bf16 v[120:123], v[200:203], v[156:159], v[120:123]
	v_mfma_f32_16x16x32_bf16 v[124:127], v[208:211], v[156:159], v[124:127]
	v_mfma_f32_16x16x32_bf16 v[128:131], v[200:203], v[164:167], v[128:131]
	v_mfma_f32_16x16x32_bf16 v[132:135], v[208:211], v[164:167], v[132:135]
	v_mfma_f32_16x16x32_bf16 v[136:139], v[200:203], v[172:175], v[136:139]
	v_mfma_f32_16x16x32_bf16 v[140:143], v[208:211], v[172:175], v[140:143]
	v_mfma_f32_16x16x32_bf16 v[144:147], v[200:203], v[180:183], v[144:147]
	v_mfma_f32_16x16x32_bf16 v[148:151], v[208:211], v[180:183], v[148:151]
	s_setprio 0
	s_barrier
	ds_read_b128 v[0:3], v188 offset:16
	ds_read_b128 v[4:7], v189 offset:16
	ds_read_b128 v[8:11], v188 offset:2064
	ds_read_b128 v[12:15], v189 offset:2064
	ds_read_b128 v[152:155], v186 offset:16
	ds_read_b128 v[156:159], v187 offset:16
	ds_read_b128 v[160:163], v186 offset:2064
	ds_read_b128 v[164:167], v187 offset:2064
	ds_read_b128 v[168:171], v186 offset:4112
	ds_read_b128 v[172:175], v187 offset:4112
	ds_read_b128 v[176:179], v186 offset:6160
	ds_read_b128 v[180:183], v187 offset:6160
	s_add_i32 m0, s39, 0xc000
	s_nop 0
	global_load_lds_dwordx4 v184, s[68:69]
	s_add_i32 m0, s39, 0xc400
	s_nop 0
	global_load_lds_dwordx4 v185, s[68:69]
	s_add_u32 s68, s68, 0x80
	s_addc_u32 s69, s69, 0
	s_barrier
	s_waitcnt lgkmcnt(0)
	s_setprio 1
	v_mfma_f32_16x16x32_bf16 v[24:27], v[0:3], v[152:155], v[24:27]
	v_mfma_f32_16x16x32_bf16 v[28:31], v[8:11], v[152:155], v[28:31]
	v_mfma_f32_16x16x32_bf16 v[32:35], v[0:3], v[160:163], v[32:35]
	v_mfma_f32_16x16x32_bf16 v[36:39], v[8:11], v[160:163], v[36:39]
	v_mfma_f32_16x16x32_bf16 v[40:43], v[0:3], v[168:171], v[40:43]
	v_mfma_f32_16x16x32_bf16 v[44:47], v[8:11], v[168:171], v[44:47]
	v_mfma_f32_16x16x32_bf16 v[48:51], v[0:3], v[176:179], v[48:51]
	v_mfma_f32_16x16x32_bf16 v[52:55], v[8:11], v[176:179], v[52:55]
	v_mfma_f32_16x16x32_bf16 v[24:27], v[4:7], v[156:159], v[24:27]
	v_mfma_f32_16x16x32_bf16 v[28:31], v[12:15], v[156:159], v[28:31]
	v_mfma_f32_16x16x32_bf16 v[32:35], v[4:7], v[164:167], v[32:35]
	v_mfma_f32_16x16x32_bf16 v[36:39], v[12:15], v[164:167], v[36:39]
	v_mfma_f32_16x16x32_bf16 v[40:43], v[4:7], v[172:175], v[40:43]
	v_mfma_f32_16x16x32_bf16 v[44:47], v[12:15], v[172:175], v[44:47]
	v_mfma_f32_16x16x32_bf16 v[48:51], v[4:7], v[180:183], v[48:51]
	v_mfma_f32_16x16x32_bf16 v[52:55], v[12:15], v[180:183], v[52:55]
	s_setprio 0
	s_barrier
	ds_read_b128 v[196:199], v188 offset:16400
	ds_read_b128 v[200:203], v189 offset:16400
	ds_read_b128 v[204:207], v188 offset:18448
	ds_read_b128 v[208:211], v189 offset:18448
	s_barrier
	s_waitcnt lgkmcnt(0)
	s_setprio 1
	v_mfma_f32_16x16x32_bf16 v[56:59], v[196:199], v[152:155], v[56:59]
	v_mfma_f32_16x16x32_bf16 v[60:63], v[204:207], v[152:155], v[60:63]
	v_mfma_f32_16x16x32_bf16 v[64:67], v[196:199], v[160:163], v[64:67]
	v_mfma_f32_16x16x32_bf16 v[68:71], v[204:207], v[160:163], v[68:71]
	v_mfma_f32_16x16x32_bf16 v[72:75], v[196:199], v[168:171], v[72:75]
	v_mfma_f32_16x16x32_bf16 v[76:79], v[204:207], v[168:171], v[76:79]
	v_mfma_f32_16x16x32_bf16 v[80:83], v[196:199], v[176:179], v[80:83]
	v_mfma_f32_16x16x32_bf16 v[84:87], v[204:207], v[176:179], v[84:87]
	v_mfma_f32_16x16x32_bf16 v[56:59], v[200:203], v[156:159], v[56:59]
	v_mfma_f32_16x16x32_bf16 v[60:63], v[208:211], v[156:159], v[60:63]
	v_mfma_f32_16x16x32_bf16 v[64:67], v[200:203], v[164:167], v[64:67]
	v_mfma_f32_16x16x32_bf16 v[68:71], v[208:211], v[164:167], v[68:71]
	v_mfma_f32_16x16x32_bf16 v[72:75], v[200:203], v[172:175], v[72:75]
	v_mfma_f32_16x16x32_bf16 v[76:79], v[208:211], v[172:175], v[76:79]
	v_mfma_f32_16x16x32_bf16 v[80:83], v[200:203], v[180:183], v[80:83]
	v_mfma_f32_16x16x32_bf16 v[84:87], v[208:211], v[180:183], v[84:87]
	s_setprio 0
	s_barrier
	ds_read_b128 v[152:155], v186 offset:16400
	ds_read_b128 v[156:159], v187 offset:16400
	ds_read_b128 v[160:163], v186 offset:18448
	ds_read_b128 v[164:167], v187 offset:18448
	ds_read_b128 v[168:171], v186 offset:20496
	ds_read_b128 v[172:175], v187 offset:20496
	ds_read_b128 v[176:179], v186 offset:22544
	ds_read_b128 v[180:183], v187 offset:22544
	s_waitcnt vmcnt(4)
	s_barrier
; #define LAS __attribute__((address_space(3)))
; #define BAR() { __builtin_amdgcn_sched_barrier(0); __builtin_amdgcn_s_barrier(); asm volatile("" ::: "memory"); __builtin_amdgcn_sched_barrier(0); }
; DI void gemm_stream2(const bf16_t* __restrict__ A, int lda, const bf16_t* __restrict__ Bt, int ldb, int K, int m0, int n0, ...
;     ...
;     for (int kt = 0; kt < nk; ++kt) {
;         const bool pf = (kt + 2 < nk) || has_next, more = (kt + 1 < nk) || has_next;
;         const bf16_t* pa = (kt + 2 < nk) ? ga + (kt + 2) * 64 : gan + (kt + 2 - nk) * 64;
;         const bf16_t* pb = (kt + 2 < nk) ? gb + (kt + 2) * 64 : gbn + (kt + 2 - nk) * 64;
;         const int plda = (kt + 2 < nk) ? lda : ldan, pldb = (kt + 2 < nk) ? ldb : ldbn;
;         const int s2 = st >= 1 ? st - 1 : 2;
;         const LAS char* base = lds + st * 49152;
; #pragma unroll
;         for (int ks = 0; ks < 2; ++ks) {
;             const unsigned fo = ks ? fo1 : fo0;
;             bf16x8 af[4], bfr[4];
; #pragma unroll
;             for (int i = 0; i < 4; ++i) { af[i] = *(const LAS bf16x8*)(base + aoff + i * 2048 + fo); bfr[i] = *(const LAS bf16x8*)(base + boff + i * 2048 + fo); }
;             if (ks == 1 && more) { if (pf) asm volatile("s_waitcnt vmcnt(3)" ::: "memory"); else asm volatile("s_waitcnt vmcnt(0)" ::: "memory"); }
;             if (pf) { PIECE(s2, ks * 3 + 0); PIECE(s2, ks * 3 + 1); PIECE(s2, ks * 3 + 2); }
;             asm volatile("s_waitcnt lgkmcnt(0)" ::: "memory");
;             BAR();
;             __builtin_amdgcn_s_setprio(1);
; #pragma unroll
;             for (int mi = 0; mi < 4; ++mi)
; #pragma unroll
;                 for (int ni = 0; ni < 4; ++ni) acc[mi][ni] = __builtin_amdgcn_mfma_f32_16x16x32_bf16(bfr[ni], af[mi], acc[mi][ni], 0, 0, 0);
;             __builtin_amdgcn_s_setprio(0);
;             BAR();
;         }
;         st = st == 2 ? 0 : st + 1;
;     }
	s_waitcnt lgkmcnt(0)
	s_setprio 1
	v_mfma_f32_16x16x32_bf16 v[88:91], v[0:3], v[152:155], v[88:91]
	v_mfma_f32_16x16x32_bf16 v[92:95], v[8:11], v[152:155], v[92:95]
	v_mfma_f32_16x16x32_bf16 v[96:99], v[0:3], v[160:163], v[96:99]
	v_mfma_f32_16x16x32_bf16 v[100:103], v[8:11], v[160:163], v[100:103]
	v_mfma_f32_16x16x32_bf16 v[104:107], v[0:3], v[168:171], v[104:107]
	v_mfma_f32_16x16x32_bf16 v[108:111], v[8:11], v[168:171], v[108:111]
	v_mfma_f32_16x16x32_bf16 v[112:115], v[0:3], v[176:179], v[112:115]
	v_mfma_f32_16x16x32_bf16 v[116:119], v[8:11], v[176:179], v[116:119]
	v_mfma_f32_16x16x32_bf16 v[88:91], v[4:7], v[156:159], v[88:91]
	v_mfma_f32_16x16x32_bf16 v[92:95], v[12:15], v[156:159], v[92:95]
	v_mfma_f32_16x16x32_bf16 v[96:99], v[4:7], v[164:167], v[96:99]
	v_mfma_f32_16x16x32_bf16 v[100:103], v[12:15], v[164:167], v[100:103]
	v_mfma_f32_16x16x32_bf16 v[104:107], v[4:7], v[172:175], v[104:107]
	v_mfma_f32_16x16x32_bf16 v[108:111], v[12:15], v[172:175], v[108:111]
	v_mfma_f32_16x16x32_bf16 v[112:115], v[4:7], v[180:183], v[112:115]
	v_mfma_f32_16x16x32_bf16 v[116:119], v[12:15], v[180:183], v[116:119]
	s_setprio 0
	s_setprio 1
	v_mfma_f32_16x16x32_bf16 v[120:123], v[196:199], v[152:155], v[120:123]
	v_mfma_f32_16x16x32_bf16 v[124:127], v[204:207], v[152:155], v[124:127]
	v_mfma_f32_16x16x32_bf16 v[128:131], v[196:199], v[160:163], v[128:131]
	v_mfma_f32_16x16x32_bf16 v[132:135], v[204:207], v[160:163], v[132:135]
	v_mfma_f32_16x16x32_bf16 v[136:139], v[196:199], v[168:171], v[136:139]
	v_mfma_f32_16x16x32_bf16 v[140:143], v[204:207], v[168:171], v[140:143]
	v_mfma_f32_16x16x32_bf16 v[144:147], v[196:199], v[176:179], v[144:147]
	v_mfma_f32_16x16x32_bf16 v[148:151], v[204:207], v[176:179], v[148:151]
	v_mfma_f32_16x16x32_bf16 v[120:123], v[200:203], v[156:159], v[120:123]
	v_mfma_f32_16x16x32_bf16 v[124:127], v[208:211], v[156:159], v[124:127]
	v_mfma_f32_16x16x32_bf16 v[128:131], v[200:203], v[164:167], v[128:131]
	v_mfma_f32_16x16x32_bf16 v[132:135], v[208:211], v[164:167], v[132:135]
	v_mfma_f32_16x16x32_bf16 v[136:139], v[200:203], v[172:175], v[136:139]
	v_mfma_f32_16x16x32_bf16 v[140:143], v[208:211], v[172:175], v[140:143]
	v_mfma_f32_16x16x32_bf16 v[144:147], v[200:203], v[180:183], v[144:147]
	v_mfma_f32_16x16x32_bf16 v[148:151], v[208:211], v[180:183], v[148:151]
	s_setprio 0
	s_barrier
	ds_read_b128 v[0:3], v188 offset:32784
	ds_read_b128 v[4:7], v189 offset:32784
	ds_read_b128 v[8:11], v188 offset:34832
	ds_read_b128 v[12:15], v189 offset:34832
	ds_read_b128 v[152:155], v186 offset:32784
	ds_read_b128 v[156:159], v187 offset:32784
	ds_read_b128 v[160:163], v186 offset:34832
	ds_read_b128 v[164:167], v187 offset:34832
	ds_read_b128 v[168:171], v186 offset:36880
	ds_read_b128 v[172:175], v187 offset:36880
	ds_read_b128 v[176:179], v186 offset:38928
	ds_read_b128 v[180:183], v187 offset:38928
	s_waitcnt vmcnt(2)
	s_barrier
	s_waitcnt lgkmcnt(0)
	s_setprio 1
	v_mfma_f32_16x16x32_bf16 v[24:27], v[0:3], v[152:155], v[24:27]
	v_mfma_f32_16x16x32_bf16 v[28:31], v[8:11], v[152:155], v[28:31]
	v_mfma_f32_16x16x32_bf16 v[32:35], v[0:3], v[160:163], v[32:35]
	v_mfma_f32_16x16x32_bf16 v[36:39], v[8:11], v[160:163], v[36:39]
	v_mfma_f32_16x16x32_bf16 v[40:43], v[0:3], v[168:171], v[40:43]
	v_mfma_f32_16x16x32_bf16 v[44:47], v[8:11], v[168:171], v[44:47]
	v_mfma_f32_16x16x32_bf16 v[48:51], v[0:3], v[176:179], v[48:51]
	v_mfma_f32_16x16x32_bf16 v[52:55], v[8:11], v[176:179], v[52:55]
	v_mfma_f32_16x16x32_bf16 v[24:27], v[4:7], v[156:159], v[24:27]
	v_mfma_f32_16x16x32_bf16 v[28:31], v[12:15], v[156:159], v[28:31]
	v_mfma_f32_16x16x32_bf16 v[32:35], v[4:7], v[164:167], v[32:35]
	v_mfma_f32_16x16x32_bf16 v[36:39], v[12:15], v[164:167], v[36:39]
	v_mfma_f32_16x16x32_bf16 v[40:43], v[4:7], v[172:175], v[40:43]
	v_mfma_f32_16x16x32_bf16 v[44:47], v[12:15], v[172:175], v[44:47]
	v_mfma_f32_16x16x32_bf16 v[48:51], v[4:7], v[180:183], v[48:51]
	v_mfma_f32_16x16x32_bf16 v[52:55], v[12:15], v[180:183], v[52:55]
	s_setprio 0
	s_barrier
	ds_read_b128 v[196:199], v188 offset:49168
	ds_read_b128 v[200:203], v189 offset:49168
	ds_read_b128 v[204:207], v188 offset:51216
	ds_read_b128 v[208:211], v189 offset:51216
	s_waitcnt vmcnt(0)
	s_barrier
	s_waitcnt lgkmcnt(0)
	s_setprio 1
	v_mfma_f32_16x16x32_bf16 v[56:59], v[196:199], v[152:155], v[56:59]
	v_mfma_f32_16x16x32_bf16 v[60:63], v[204:207], v[152:155], v[60:63]
	v_mfma_f32_16x16x32_bf16 v[64:67], v[196:199], v[160:163], v[64:67]
	v_mfma_f32_16x16x32_bf16 v[68:71], v[204:207], v[160:163], v[68:71]
	v_mfma_f32_16x16x32_bf16 v[72:75], v[196:199], v[168:171], v[72:75]
	v_mfma_f32_16x16x32_bf16 v[76:79], v[204:207], v[168:171], v[76:79]
	v_mfma_f32_16x16x32_bf16 v[80:83], v[196:199], v[176:179], v[80:83]
	v_mfma_f32_16x16x32_bf16 v[84:87], v[204:207], v[176:179], v[84:87]
	v_mfma_f32_16x16x32_bf16 v[56:59], v[200:203], v[156:159], v[56:59]
	v_mfma_f32_16x16x32_bf16 v[60:63], v[208:211], v[156:159], v[60:63]
	v_mfma_f32_16x16x32_bf16 v[64:67], v[200:203], v[164:167], v[64:67]
	v_mfma_f32_16x16x32_bf16 v[68:71], v[208:211], v[164:167], v[68:71]
	v_mfma_f32_16x16x32_bf16 v[72:75], v[200:203], v[172:175], v[72:75]
	v_mfma_f32_16x16x32_bf16 v[76:79], v[208:211], v[172:175], v[76:79]
	v_mfma_f32_16x16x32_bf16 v[80:83], v[200:203], v[180:183], v[80:83]
	v_mfma_f32_16x16x32_bf16 v[84:87], v[208:211], v[180:183], v[84:87]
	s_setprio 0
	s_barrier
; DI unsigned pk2(float lo, float hi) { const f32x2 v = {lo, hi}; return __builtin_bit_cast(unsigned, __builtin_convertvector(v, bf2_t)); }
; #define BAR() { __builtin_amdgcn_sched_barrier(0); __builtin_amdgcn_s_barrier(); asm volatile("" ::: "memory"); __builtin_amdgcn_sched_barrier(0); }
; DI void gemm_stream2(const bf16_t* __restrict__ A, int lda, const bf16_t* __restrict__ Bt, int ldb, int K, int m0, int n0, ...
;     ...
;             for (int mi = 0; mi < 4; ++mi)
; #pragma unroll
;                 for (int ni = 0; ni < 4; ++ni) acc[mi][ni] = __builtin_amdgcn_mfma_f32_16x16x32_bf16(bfr[ni], af[mi], acc[mi][ni], 0, 0, 0);
;             __builtin_amdgcn_s_setprio(0);
;             BAR();
;         }
;         st = st == 2 ? 0 : st + 1;
;     }
;     if (grp == 0) BAR();
;     ...
; #pragma unroll
;     for (int mi = 0; mi < 4; ++mi) {
;         const int row = m0 + wm * 64 + mi * 16 + r;
; #pragma unroll
;         for (int ni = 0; ni < 4; ++ni) {
;             const int col = n0 + wn * 64 + ni * 16 + q * 4;
;             if (MODE == 0) {
;                 u32x2 w; w.x = pk2(acc[mi][ni][0], acc[mi][ni][1]); w.y = pk2(acc[mi][ni][2], acc[mi][ni][3]);
;                 *(u32x2*)(Y + (size_t)row * DM + col) = w;
;             } else if (MODE == 1) {
;                 *(f32x4*)(YS + (size_t)(row - NP) * DM + col) = acc[mi][ni];
;             } else {
;                 *(f32x4*)(YS + (size_t)part * NS * DM + (size_t)(row - NP) * DM + col) = acc[mi][ni];
;             }
;         }
	ds_read_b128 v[152:155], v186 offset:49168
	ds_read_b128 v[156:159], v187 offset:49168
	ds_read_b128 v[160:163], v186 offset:51216
	ds_read_b128 v[164:167], v187 offset:51216
	ds_read_b128 v[168:171], v186 offset:53264
	ds_read_b128 v[172:175], v187 offset:53264
	ds_read_b128 v[176:179], v186 offset:55312
	ds_read_b128 v[180:183], v187 offset:55312
	s_barrier
	s_waitcnt lgkmcnt(0)
	s_setprio 1
	v_mfma_f32_16x16x32_bf16 v[88:91], v[0:3], v[152:155], v[88:91]
	v_mfma_f32_16x16x32_bf16 v[92:95], v[8:11], v[152:155], v[92:95]
	v_mfma_f32_16x16x32_bf16 v[96:99], v[0:3], v[160:163], v[96:99]
	v_mfma_f32_16x16x32_bf16 v[100:103], v[8:11], v[160:163], v[100:103]
	v_mfma_f32_16x16x32_bf16 v[104:107], v[0:3], v[168:171], v[104:107]
	v_mfma_f32_16x16x32_bf16 v[108:111], v[8:11], v[168:171], v[108:111]
	v_mfma_f32_16x16x32_bf16 v[112:115], v[0:3], v[176:179], v[112:115]
	v_mfma_f32_16x16x32_bf16 v[116:119], v[8:11], v[176:179], v[116:119]
	v_mfma_f32_16x16x32_bf16 v[88:91], v[4:7], v[156:159], v[88:91]
	v_mfma_f32_16x16x32_bf16 v[92:95], v[12:15], v[156:159], v[92:95]
	v_mfma_f32_16x16x32_bf16 v[96:99], v[4:7], v[164:167], v[96:99]
	v_mfma_f32_16x16x32_bf16 v[100:103], v[12:15], v[164:167], v[100:103]
	v_mfma_f32_16x16x32_bf16 v[104:107], v[4:7], v[172:175], v[104:107]
	v_mfma_f32_16x16x32_bf16 v[108:111], v[12:15], v[172:175], v[108:111]
	v_mfma_f32_16x16x32_bf16 v[112:115], v[4:7], v[180:183], v[112:115]
	v_mfma_f32_16x16x32_bf16 v[116:119], v[12:15], v[180:183], v[116:119]
	s_setprio 0
	s_setprio 1
	v_mfma_f32_16x16x32_bf16 v[120:123], v[196:199], v[152:155], v[120:123]
	v_mfma_f32_16x16x32_bf16 v[124:127], v[204:207], v[152:155], v[124:127]
	v_mfma_f32_16x16x32_bf16 v[128:131], v[196:199], v[160:163], v[128:131]
	v_mfma_f32_16x16x32_bf16 v[132:135], v[204:207], v[160:163], v[132:135]
	v_mfma_f32_16x16x32_bf16 v[136:139], v[196:199], v[168:171], v[136:139]
	v_mfma_f32_16x16x32_bf16 v[140:143], v[204:207], v[168:171], v[140:143]
	v_mfma_f32_16x16x32_bf16 v[144:147], v[196:199], v[176:179], v[144:147]
	v_mfma_f32_16x16x32_bf16 v[148:151], v[204:207], v[176:179], v[148:151]
	v_mfma_f32_16x16x32_bf16 v[120:123], v[200:203], v[156:159], v[120:123]
	v_mfma_f32_16x16x32_bf16 v[124:127], v[208:211], v[156:159], v[124:127]
	v_mfma_f32_16x16x32_bf16 v[128:131], v[200:203], v[164:167], v[128:131]
	v_mfma_f32_16x16x32_bf16 v[132:135], v[208:211], v[164:167], v[132:135]
	v_mfma_f32_16x16x32_bf16 v[136:139], v[200:203], v[172:175], v[136:139]
	v_mfma_f32_16x16x32_bf16 v[140:143], v[208:211], v[172:175], v[140:143]
	v_mfma_f32_16x16x32_bf16 v[144:147], v[200:203], v[180:183], v[144:147]
	v_mfma_f32_16x16x32_bf16 v[148:151], v[208:211], v[180:183], v[148:151]
	s_setprio 0
	s_barrier
	s_cmp_lg_u32 s33, 0
	s_cbranch_scc1 .Lpls_epi
	s_barrier
.Lpls_epi:
	s_lshl_b32 s1, s57, 20
	s_lshl_b32 s62, s58, 10
	s_add_u32 s1, s1, s62
	s_add_u32 s1, s1, 0x12595000
	s_add_u32 s2, s88, s1
	s_addc_u32 s3, s89, 0
	v_lshlrev_b32_e32 v152, 1, v237
	s_nop 7
	s_nop 7
	global_store_dwordx4 v152, v[24:27], s[2:3] offset:0
	global_store_dwordx4 v152, v[28:31], s[2:3] offset:64
	global_store_dwordx4 v152, v[56:59], s[2:3] offset:512
	global_store_dwordx4 v152, v[60:63], s[2:3] offset:576
	s_add_u32 s2, s2, 0x10000
	s_addc_u32 s3, s3, 0
	global_store_dwordx4 v152, v[32:35], s[2:3] offset:0
	global_store_dwordx4 v152, v[36:39], s[2:3] offset:64
	global_store_dwordx4 v152, v[64:67], s[2:3] offset:512
	global_store_dwordx4 v152, v[68:71], s[2:3] offset:576
	s_add_u32 s2, s2, 0x10000
	s_addc_u32 s3, s3, 0
	global_store_dwordx4 v152, v[40:43], s[2:3] offset:0
	global_store_dwordx4 v152, v[44:47], s[2:3] offset:64
	global_store_dwordx4 v152, v[72:75], s[2:3] offset:512
	global_store_dwordx4 v152, v[76:79], s[2:3] offset:576
	s_add_u32 s2, s2, 0x10000
	s_addc_u32 s3, s3, 0
	global_store_dwordx4 v152, v[48:51], s[2:3] offset:0
	global_store_dwordx4 v152, v[52:55], s[2:3] offset:64
	global_store_dwordx4 v152, v[80:83], s[2:3] offset:512
	global_store_dwordx4 v152, v[84:87], s[2:3] offset:576
	s_add_u32 s2, s2, 0x50000
	s_addc_u32 s3, s3, 0
	global_store_dwordx4 v152, v[88:91], s[2:3] offset:0
	global_store_dwordx4 v152, v[92:95], s[2:3] offset:64
	global_store_dwordx4 v152, v[120:123], s[2:3] offset:512
	global_store_dwordx4 v152, v[124:127], s[2:3] offset:576
	s_add_u32 s2, s2, 0x10000
	s_addc_u32 s3, s3, 0
	global_store_dwordx4 v152, v[96:99], s[2:3] offset:0
	global_store_dwordx4 v152, v[100:103], s[2:3] offset:64
	global_store_dwordx4 v152, v[128:131], s[2:3] offset:512
	global_store_dwordx4 v152, v[132:135], s[2:3] offset:576
	s_add_u32 s2, s2, 0x10000
	s_addc_u32 s3, s3, 0
	global_store_dwordx4 v152, v[104:107], s[2:3] offset:0
	global_store_dwordx4 v152, v[108:111], s[2:3] offset:64
	global_store_dwordx4 v152, v[136:139], s[2:3] offset:512
	global_store_dwordx4 v152, v[140:143], s[2:3] offset:576
	s_add_u32 s2, s2, 0x10000
	s_addc_u32 s3, s3, 0
	global_store_dwordx4 v152, v[112:115], s[2:3] offset:0
	global_store_dwordx4 v152, v[116:119], s[2:3] offset:64
	global_store_dwordx4 v152, v[144:147], s[2:3] offset:512
	global_store_dwordx4 v152, v[148:151], s[2:3] offset:576
	s_nop 1
	s_branch .Lple_exit
.Lple_exit:
	s_mov_b64 s[70:71], s[46:47]
.LBB0_147:
	s_mov_b64 s[0:1], 0
	s_mov_b64 s[46:47], s[70:71]
